# v64 + code placement: every 16/32-MFMA burst padded (s_nop in the load part before the vmcnt wait) to start on an 8-byte boundary
# baseline (speedup 1.0000x reference)
; #define PG8_STAGE(bufoff, gbase, voff) do { _Pragma("unroll") for (int _i = 0; _i < 2; ++_i) \
;         __builtin_amdgcn_global_load_lds((const unsigned*)((const char*)(gbase) + (voff)[_i]), (PG8_LAS unsigned*)(lds + (bufoff) + ldsw + _i * 8192), 16, 0, 0); } while (0)
; #define PG8_STAGE_NT(bufoff, gbase, voff) do { _Pragma("unroll") for (int _i = 0; _i < 2; ++_i) \
;         __builtin_amdgcn_global_load_lds((const unsigned*)((const char*)(gbase) + (voff)[_i]), (PG8_LAS unsigned*)(lds + (bufoff) + ldsw + _i * 8192), 16, 0, PG8_B_AUX); } while (0)
; #define PG8_LDA(dst, b, h) do { _Pragma("unroll") for (int m = 0; m < 4; ++m) _Pragma("unroll") for (int k = 0; k < 2; ++k) dst[m][k] = *(const PG8_LAS bf16x8*)(lds + PG8_SA(b, h) + aoff + m * 2048 + k * 1024); } while (0)
; #define PG8_LDB(dst, b, h) do { _Pragma("unroll") for (int n = 0; n < 2; ++n) _Pragma("unroll") for (int k = 0; k < 2; ++k) dst[n][k] = *(const PG8_LAS bf16x8*)(lds + PG8_SB(b, h) + boff + n * 2048 + k * 1024); } while (0)
; #define PG8_WAIT_V(n) asm volatile("s_waitcnt vmcnt(" #n ")" ::: "memory")
; #define PG8_WAIT_L(n) asm volatile("s_waitcnt lgkmcnt(" #n ")" ::: "memory")
; #define PG8_BAR __builtin_amdgcn_s_barrier()
; #define PG8_SCHED __builtin_amdgcn_sched_barrier(0)
; template <class Epi, class Sched, bool ALIGN_EPI = false, bool SP2 = false>
; __device__ __forceinline__ void gemm_phase(PG8_LAS unsigned char* lds, const Gemm g, const Sched& S, const Epi& E, int wid) {
;     ...
;             const bool last = (t == nt - 2);
;             const char* a1 = cA + (size_t)(t + 1) * kstep;
;             const char* a2 = last ? nA : cA + (size_t)(t + 2) * kstep; const char* b2 = last ? nB : cB + (size_t)(t + 2) * kstep;
;             const char* a3 = a2 + kstep; const char* b3 = b2 + kstep;
;             if (last && has_next) S.a_ready(nxt);
;             if constexpr (SP2) {
;             PG8_LDB(B0, 0, 0); PG8_LDB(B1, 0, 1); PG8_SCHED; PG8_LDA(At, 0, 0); PG8_STAGE(PG8_SA(1, 1), a1 + hstepA, voffA);
;             PG8_WAIT_V(8); PG8_WAIT_L(0); PG8_BAR; PG8_MMA(0, 0, At, B0); PG8_MMA(0, 1, At, B1); PG8_BAR; PG8_SCHED;
;             PG8_LDA(At, 0, 1); PG8_STAGE_NT(PG8_SB(0, 0), b2, voffB); PG8_STAGE_NT(PG8_SB(0, 1), b2 + hstepB, voffB); PG8_STAGE(PG8_SA(0, 0), a2, voffA);
;             PG8_WAIT_V(8); PG8_WAIT_L(0); PG8_BAR; PG8_MMA(1, 0, At, B0); PG8_MMA(1, 1, At, B1); PG8_BAR; PG8_SCHED;
.LBB0_233:
	ds_read_b128 v[144:147], v155
	ds_read_b128 v[148:151], v155 offset:1024
	ds_read_b128 v[160:163], v155 offset:2048
	ds_read_b128 v[164:167], v155 offset:3072
	ds_read_b128 v[168:171], v156
	ds_read_b128 v[172:175], v156 offset:1024
	ds_read_b128 v[176:179], v156 offset:2048
	ds_read_b128 v[180:183], v156 offset:3072
	s_add_u32 s4, s48, 0x100
	s_addc_u32 s5, s49, 0
	s_add_u32 s98, s48, 0x80
	s_addc_u32 s99, s49, 0
	s_add_u32 s100, s48, 0x104080
	s_addc_u32 s101, s49, 0
	s_cmp_eq_u32 s66, 60
	s_cselect_b32 s53, s45, s5
	s_cselect_b32 s52, s44, s4
	s_cselect_b32 s51, s47, s65
	s_cselect_b32 s50, s46, s64
	s_add_i32 m0, s23, 0xc000
	ds_read_b128 v[184:187], v157
	ds_read_b128 v[188:191], v157 offset:1024
	ds_read_b128 v[192:195], v157 offset:2048
	ds_read_b128 v[196:199], v157 offset:3072
	ds_read_b128 v[200:203], v157 offset:4096
	ds_read_b128 v[204:207], v157 offset:5120
	ds_read_b128 v[208:211], v157 offset:6144
	ds_read_b128 v[212:215], v157 offset:7168
	global_load_lds_dwordx4 v134, s[100:101]
	s_add_i32 m0, s23, 0xe000
	s_nop 0
	global_load_lds_dwordx4 v130, s[100:101]
	s_mov_b32 m0, s55
	s_nop 0
	global_load_lds_dwordx4 v134, s[98:99]
	s_mov_b32 m0, s56
	s_nop 0
	global_load_lds_dwordx4 v130, s[98:99]
	s_nop 0
	s_waitcnt vmcnt(8)
	s_waitcnt lgkmcnt(0)
	s_barrier
	s_waitcnt lgkmcnt(0)
	v_mfma_f32_16x16x32_bf16 v[112:115], v[144:147], v[184:187], v[112:115]
	v_mfma_f32_16x16x32_bf16 v[108:111], v[160:163], v[184:187], v[108:111]
	v_mfma_f32_16x16x32_bf16 v[104:107], v[144:147], v[192:195], v[104:107]
	v_mfma_f32_16x16x32_bf16 v[100:103], v[160:163], v[192:195], v[100:103]
	v_mfma_f32_16x16x32_bf16 v[92:95], v[144:147], v[200:203], v[92:95]
	v_mfma_f32_16x16x32_bf16 v[84:87], v[160:163], v[200:203], v[84:87]
	v_mfma_f32_16x16x32_bf16 v[76:79], v[144:147], v[208:211], v[76:79]
	v_mfma_f32_16x16x32_bf16 v[68:71], v[160:163], v[208:211], v[68:71]
	v_mfma_f32_16x16x32_bf16 v[112:115], v[148:151], v[188:191], v[112:115]
	v_mfma_f32_16x16x32_bf16 v[108:111], v[164:167], v[188:191], v[108:111]
	v_mfma_f32_16x16x32_bf16 v[104:107], v[148:151], v[196:199], v[104:107]
	v_mfma_f32_16x16x32_bf16 v[100:103], v[164:167], v[196:199], v[100:103]
	v_mfma_f32_16x16x32_bf16 v[92:95], v[148:151], v[204:207], v[92:95]
	v_mfma_f32_16x16x32_bf16 v[84:87], v[164:167], v[204:207], v[84:87]
	v_mfma_f32_16x16x32_bf16 v[76:79], v[148:151], v[212:215], v[76:79]
	v_mfma_f32_16x16x32_bf16 v[68:71], v[164:167], v[212:215], v[68:71]
	v_mfma_f32_16x16x32_bf16 v[124:127], v[168:171], v[184:187], v[124:127]
	v_mfma_f32_16x16x32_bf16 v[120:123], v[176:179], v[184:187], v[120:123]
	v_mfma_f32_16x16x32_bf16 v[116:119], v[168:171], v[192:195], v[116:119]
	v_mfma_f32_16x16x32_bf16 v[96:99], v[176:179], v[192:195], v[96:99]
	v_mfma_f32_16x16x32_bf16 v[88:91], v[168:171], v[200:203], v[88:91]
	v_mfma_f32_16x16x32_bf16 v[80:83], v[176:179], v[200:203], v[80:83]
	v_mfma_f32_16x16x32_bf16 v[72:75], v[168:171], v[208:211], v[72:75]
	v_mfma_f32_16x16x32_bf16 v[64:67], v[176:179], v[208:211], v[64:67]
	v_mfma_f32_16x16x32_bf16 v[124:127], v[172:175], v[188:191], v[124:127]
	v_mfma_f32_16x16x32_bf16 v[120:123], v[180:183], v[188:191], v[120:123]
	v_mfma_f32_16x16x32_bf16 v[116:119], v[172:175], v[196:199], v[116:119]
	v_mfma_f32_16x16x32_bf16 v[96:99], v[180:183], v[196:199], v[96:99]
	v_mfma_f32_16x16x32_bf16 v[88:91], v[172:175], v[204:207], v[88:91]
	v_mfma_f32_16x16x32_bf16 v[80:83], v[180:183], v[204:207], v[80:83]
	v_mfma_f32_16x16x32_bf16 v[72:75], v[172:175], v[212:215], v[72:75]
	v_mfma_f32_16x16x32_bf16 v[64:67], v[180:183], v[212:215], v[64:67]
	s_barrier
	s_add_i32 s48, s58, s17
	s_mov_b32 m0, s48
	ds_read_b128 v[184:187], v157 offset:16384
	ds_read_b128 v[188:191], v157 offset:17408
	ds_read_b128 v[192:195], v157 offset:18432
	ds_read_b128 v[196:199], v157 offset:19456
	ds_read_b128 v[200:203], v157 offset:20480
	ds_read_b128 v[204:207], v157 offset:21504
	ds_read_b128 v[208:211], v157 offset:22528
	ds_read_b128 v[212:215], v157 offset:23552
	global_load_lds_dwordx4 v132, s[50:51]
	s_add_i32 m0, s48, 0x2000
	s_add_u32 s48, s50, 0x104000
	s_addc_u32 s49, s51, 0
	s_add_i32 s67, s59, s17
	global_load_lds_dwordx4 v128, s[50:51]
	s_mov_b32 m0, s67
	s_nop 0
	global_load_lds_dwordx4 v132, s[48:49]
	s_add_i32 m0, s67, 0x2000
	s_nop 0
	global_load_lds_dwordx4 v128, s[48:49]
	s_waitcnt vmcnt(4)
	s_waitcnt lgkmcnt(0)
	s_barrier
	s_waitcnt lgkmcnt(0)
	v_mfma_f32_16x16x32_bf16 v[60:63], v[144:147], v[184:187], v[60:63]
	v_mfma_f32_16x16x32_bf16 v[52:55], v[160:163], v[184:187], v[52:55]
	v_mfma_f32_16x16x32_bf16 v[44:47], v[144:147], v[192:195], v[44:47]
	v_mfma_f32_16x16x32_bf16 v[36:39], v[160:163], v[192:195], v[36:39]
	v_mfma_f32_16x16x32_bf16 v[28:31], v[144:147], v[200:203], v[28:31]
	v_mfma_f32_16x16x32_bf16 v[20:23], v[160:163], v[200:203], v[20:23]
	v_mfma_f32_16x16x32_bf16 v[12:15], v[144:147], v[208:211], v[12:15]
	v_mfma_f32_16x16x32_bf16 v[4:7], v[160:163], v[208:211], v[4:7]
	v_mfma_f32_16x16x32_bf16 v[60:63], v[148:151], v[188:191], v[60:63]
	v_mfma_f32_16x16x32_bf16 v[52:55], v[164:167], v[188:191], v[52:55]
	v_mfma_f32_16x16x32_bf16 v[44:47], v[148:151], v[196:199], v[44:47]
	v_mfma_f32_16x16x32_bf16 v[36:39], v[164:167], v[196:199], v[36:39]
	v_mfma_f32_16x16x32_bf16 v[28:31], v[148:151], v[204:207], v[28:31]
	v_mfma_f32_16x16x32_bf16 v[20:23], v[164:167], v[204:207], v[20:23]
	v_mfma_f32_16x16x32_bf16 v[12:15], v[148:151], v[212:215], v[12:15]
	v_mfma_f32_16x16x32_bf16 v[4:7], v[164:167], v[212:215], v[4:7]
	v_mfma_f32_16x16x32_bf16 v[56:59], v[168:171], v[184:187], v[56:59]
	v_mfma_f32_16x16x32_bf16 v[48:51], v[176:179], v[184:187], v[48:51]
	v_mfma_f32_16x16x32_bf16 v[40:43], v[168:171], v[192:195], v[40:43]
	v_mfma_f32_16x16x32_bf16 v[32:35], v[176:179], v[192:195], v[32:35]
	v_mfma_f32_16x16x32_bf16 v[24:27], v[168:171], v[200:203], v[24:27]
	v_mfma_f32_16x16x32_bf16 v[16:19], v[176:179], v[200:203], v[16:19]
	v_mfma_f32_16x16x32_bf16 v[8:11], v[168:171], v[208:211], v[8:11]
	v_mfma_f32_16x16x32_bf16 v[0:3], v[176:179], v[208:211], v[0:3]
	v_mfma_f32_16x16x32_bf16 v[56:59], v[172:175], v[188:191], v[56:59]
	v_mfma_f32_16x16x32_bf16 v[48:51], v[180:183], v[188:191], v[48:51]
	v_mfma_f32_16x16x32_bf16 v[40:43], v[172:175], v[196:199], v[40:43]
	v_mfma_f32_16x16x32_bf16 v[32:35], v[180:183], v[196:199], v[32:35]
	v_mfma_f32_16x16x32_bf16 v[24:27], v[172:175], v[204:207], v[24:27]
	v_mfma_f32_16x16x32_bf16 v[16:19], v[180:183], v[204:207], v[16:19]
	v_mfma_f32_16x16x32_bf16 v[8:11], v[172:175], v[212:215], v[8:11]
	v_mfma_f32_16x16x32_bf16 v[0:3], v[180:183], v[212:215], v[0:3]
	s_barrier
; #define PG8_STAGE(bufoff, gbase, voff) do { _Pragma("unroll") for (int _i = 0; _i < 2; ++_i) \
;         __builtin_amdgcn_global_load_lds((const unsigned*)((const char*)(gbase) + (voff)[_i]), (PG8_LAS unsigned*)(lds + (bufoff) + ldsw + _i * 8192), 16, 0, 0); } while (0)
; #define PG8_STAGE_NT(bufoff, gbase, voff) do { _Pragma("unroll") for (int _i = 0; _i < 2; ++_i) \
;         __builtin_amdgcn_global_load_lds((const unsigned*)((const char*)(gbase) + (voff)[_i]), (PG8_LAS unsigned*)(lds + (bufoff) + ldsw + _i * 8192), 16, 0, PG8_B_AUX); } while (0)
; #define PG8_LDA(dst, b, h) do { _Pragma("unroll") for (int m = 0; m < 4; ++m) _Pragma("unroll") for (int k = 0; k < 2; ++k) dst[m][k] = *(const PG8_LAS bf16x8*)(lds + PG8_SA(b, h) + aoff + m * 2048 + k * 1024); } while (0)
; #define PG8_LDB(dst, b, h) do { _Pragma("unroll") for (int n = 0; n < 2; ++n) _Pragma("unroll") for (int k = 0; k < 2; ++k) dst[n][k] = *(const PG8_LAS bf16x8*)(lds + PG8_SB(b, h) + boff + n * 2048 + k * 1024); } while (0)
; #define PG8_MMA(ai, bj, At, Bt) do { __builtin_amdgcn_s_setprio(1); _Pragma("unroll") for (int m = 0; m < 4; ++m) _Pragma("unroll") for (int n = 0; n < 2; ++n) _Pragma("unroll") for (int k = 0; k < 2; ++k) \
;         acc[ai][bj][m][n] = __builtin_amdgcn_mfma_f32_16x16x32_bf16(Bt[n][k], At[m][k], acc[ai][bj][m][n], 0, 0, 0); __builtin_amdgcn_s_setprio(0); } while (0)
; #define PG8_WAIT_V(n) asm volatile("s_waitcnt vmcnt(" #n ")" ::: "memory")
; #define PG8_WAIT_L(n) asm volatile("s_waitcnt lgkmcnt(" #n ")" ::: "memory")
; #define PG8_BAR __builtin_amdgcn_s_barrier()
; template <class Epi, class Sched, bool ALIGN_EPI = false, bool SP2 = false>
; __device__ __forceinline__ void gemm_phase(PG8_LAS unsigned char* lds, const Gemm g, const Sched& S, const Epi& E, int wid) {
;     ...
;             PG8_LDB(B0, 1, 0); PG8_LDB(B1, 1, 1); PG8_SCHED; PG8_LDA(At, 1, 0); PG8_STAGE(PG8_SA(0, 1), a2 + hstepA, voffA);
;             PG8_WAIT_V(8); PG8_WAIT_L(0); PG8_BAR; PG8_MMA(0, 0, At, B0); PG8_MMA(0, 1, At, B1); PG8_BAR; PG8_SCHED;
;             PG8_LDA(At, 1, 1); PG8_STAGE_NT(PG8_SB(1, 0), b3, voffB); PG8_STAGE_NT(PG8_SB(1, 1), b3 + hstepB, voffB); PG8_STAGE(PG8_SA(1, 0), a3, voffA);
;             PG8_WAIT_V(8); PG8_WAIT_L(0); PG8_BAR; PG8_MMA(1, 0, At, B0); PG8_MMA(1, 1, At, B1); PG8_BAR; PG8_SCHED;
;     ...
;         if constexpr (ALIGN_EPI) { if (wr == 0) PG8_BAR; }
	s_add_i32 s67, 0, 0x18000
	v_add_u32_e32 v159, s67, v153
	s_add_i32 s68, 0, 0x1c000
	ds_read_b128 v[144:147], v159
	ds_read_b128 v[148:151], v159 offset:1024
	ds_read_b128 v[160:163], v159 offset:2048
	ds_read_b128 v[164:167], v159 offset:3072
	v_add_u32_e32 v159, s68, v153
	ds_read_b128 v[168:171], v159
	ds_read_b128 v[172:175], v159 offset:1024
	ds_read_b128 v[176:179], v159 offset:2048
	ds_read_b128 v[180:183], v159 offset:3072
	s_add_u32 s48, s52, 0x104000
	s_addc_u32 s49, s53, 0
	s_mov_b32 m0, s25
	ds_read_b128 v[184:187], v157 offset:32768
	ds_read_b128 v[188:191], v157 offset:33792
	ds_read_b128 v[192:195], v157 offset:34816
	ds_read_b128 v[196:199], v157 offset:35840
	ds_read_b128 v[200:203], v157 offset:36864
	ds_read_b128 v[204:207], v157 offset:37888
	ds_read_b128 v[208:211], v157 offset:38912
	ds_read_b128 v[212:215], v157 offset:39936
	global_load_lds_dwordx4 v134, s[48:49]
	s_mov_b32 m0, s29
	s_nop 0
	global_load_lds_dwordx4 v130, s[48:49]
	s_mov_b32 m0, s23
	s_nop 0
	global_load_lds_dwordx4 v134, s[52:53]
	s_mov_b32 m0, s24
	s_nop 0
	global_load_lds_dwordx4 v130, s[52:53]
	s_nop 0
	s_waitcnt vmcnt(8)
	s_waitcnt lgkmcnt(0)
	s_barrier
	s_waitcnt lgkmcnt(0)
	v_mfma_f32_16x16x32_bf16 v[112:115], v[144:147], v[184:187], v[112:115]
	v_mfma_f32_16x16x32_bf16 v[108:111], v[160:163], v[184:187], v[108:111]
	v_mfma_f32_16x16x32_bf16 v[104:107], v[144:147], v[192:195], v[104:107]
	v_mfma_f32_16x16x32_bf16 v[100:103], v[160:163], v[192:195], v[100:103]
	v_mfma_f32_16x16x32_bf16 v[92:95], v[144:147], v[200:203], v[92:95]
	v_mfma_f32_16x16x32_bf16 v[84:87], v[160:163], v[200:203], v[84:87]
	v_mfma_f32_16x16x32_bf16 v[76:79], v[144:147], v[208:211], v[76:79]
	v_mfma_f32_16x16x32_bf16 v[68:71], v[160:163], v[208:211], v[68:71]
	v_mfma_f32_16x16x32_bf16 v[112:115], v[148:151], v[188:191], v[112:115]
	v_mfma_f32_16x16x32_bf16 v[108:111], v[164:167], v[188:191], v[108:111]
	v_mfma_f32_16x16x32_bf16 v[104:107], v[148:151], v[196:199], v[104:107]
	v_mfma_f32_16x16x32_bf16 v[100:103], v[164:167], v[196:199], v[100:103]
	v_mfma_f32_16x16x32_bf16 v[92:95], v[148:151], v[204:207], v[92:95]
	v_mfma_f32_16x16x32_bf16 v[84:87], v[164:167], v[204:207], v[84:87]
	v_mfma_f32_16x16x32_bf16 v[76:79], v[148:151], v[212:215], v[76:79]
	v_mfma_f32_16x16x32_bf16 v[68:71], v[164:167], v[212:215], v[68:71]
	v_mfma_f32_16x16x32_bf16 v[124:127], v[168:171], v[184:187], v[124:127]
	v_mfma_f32_16x16x32_bf16 v[120:123], v[176:179], v[184:187], v[120:123]
	v_mfma_f32_16x16x32_bf16 v[116:119], v[168:171], v[192:195], v[116:119]
	v_mfma_f32_16x16x32_bf16 v[96:99], v[176:179], v[192:195], v[96:99]
	v_mfma_f32_16x16x32_bf16 v[88:91], v[168:171], v[200:203], v[88:91]
	v_mfma_f32_16x16x32_bf16 v[80:83], v[176:179], v[200:203], v[80:83]
	v_mfma_f32_16x16x32_bf16 v[72:75], v[168:171], v[208:211], v[72:75]
	v_mfma_f32_16x16x32_bf16 v[64:67], v[176:179], v[208:211], v[64:67]
	v_mfma_f32_16x16x32_bf16 v[124:127], v[172:175], v[188:191], v[124:127]
	v_mfma_f32_16x16x32_bf16 v[120:123], v[180:183], v[188:191], v[120:123]
	v_mfma_f32_16x16x32_bf16 v[116:119], v[172:175], v[196:199], v[116:119]
	v_mfma_f32_16x16x32_bf16 v[96:99], v[180:183], v[196:199], v[96:99]
	v_mfma_f32_16x16x32_bf16 v[88:91], v[172:175], v[204:207], v[88:91]
	v_mfma_f32_16x16x32_bf16 v[80:83], v[180:183], v[204:207], v[80:83]
	v_mfma_f32_16x16x32_bf16 v[72:75], v[172:175], v[212:215], v[72:75]
	v_mfma_f32_16x16x32_bf16 v[64:67], v[180:183], v[212:215], v[64:67]
	s_barrier
	s_add_i32 s48, s67, s17
	s_mov_b32 m0, s48
	s_add_u32 s98, s50, 0x80
	s_addc_u32 s99, s51, 0
	ds_read_b128 v[184:187], v157 offset:49152
	ds_read_b128 v[188:191], v157 offset:50176
	ds_read_b128 v[192:195], v157 offset:51200
	ds_read_b128 v[196:199], v157 offset:52224
	ds_read_b128 v[200:203], v157 offset:53248
	ds_read_b128 v[204:207], v157 offset:54272
	ds_read_b128 v[208:211], v157 offset:55296
	ds_read_b128 v[212:215], v157 offset:56320
	global_load_lds_dwordx4 v132, s[98:99]
	s_add_i32 m0, s48, 0x2000
	s_add_u32 s48, s50, 0x104080
	s_addc_u32 s49, s51, 0
	s_add_i32 s50, s68, s17
	global_load_lds_dwordx4 v128, s[98:99]
	s_mov_b32 m0, s50
	s_nop 0
	global_load_lds_dwordx4 v132, s[48:49]
	s_add_i32 m0, s50, 0x2000
	s_nop 0
	global_load_lds_dwordx4 v128, s[48:49]
	s_nop 0
	s_waitcnt vmcnt(4)
	s_waitcnt lgkmcnt(0)
	s_barrier
	s_waitcnt lgkmcnt(0)
	v_mfma_f32_16x16x32_bf16 v[60:63], v[144:147], v[184:187], v[60:63]
	v_mfma_f32_16x16x32_bf16 v[52:55], v[160:163], v[184:187], v[52:55]
	v_mfma_f32_16x16x32_bf16 v[44:47], v[144:147], v[192:195], v[44:47]
	v_mfma_f32_16x16x32_bf16 v[36:39], v[160:163], v[192:195], v[36:39]
	v_mfma_f32_16x16x32_bf16 v[28:31], v[144:147], v[200:203], v[28:31]
	v_mfma_f32_16x16x32_bf16 v[20:23], v[160:163], v[200:203], v[20:23]
	v_mfma_f32_16x16x32_bf16 v[12:15], v[144:147], v[208:211], v[12:15]
	v_mfma_f32_16x16x32_bf16 v[4:7], v[160:163], v[208:211], v[4:7]
	v_mfma_f32_16x16x32_bf16 v[60:63], v[148:151], v[188:191], v[60:63]
	v_mfma_f32_16x16x32_bf16 v[52:55], v[164:167], v[188:191], v[52:55]
	v_mfma_f32_16x16x32_bf16 v[44:47], v[148:151], v[196:199], v[44:47]
	v_mfma_f32_16x16x32_bf16 v[36:39], v[164:167], v[196:199], v[36:39]
	v_mfma_f32_16x16x32_bf16 v[28:31], v[148:151], v[204:207], v[28:31]
	v_mfma_f32_16x16x32_bf16 v[20:23], v[164:167], v[204:207], v[20:23]
	v_mfma_f32_16x16x32_bf16 v[12:15], v[148:151], v[212:215], v[12:15]
	v_mfma_f32_16x16x32_bf16 v[4:7], v[164:167], v[212:215], v[4:7]
	v_mfma_f32_16x16x32_bf16 v[56:59], v[168:171], v[184:187], v[56:59]
	v_mfma_f32_16x16x32_bf16 v[48:51], v[176:179], v[184:187], v[48:51]
	v_mfma_f32_16x16x32_bf16 v[40:43], v[168:171], v[192:195], v[40:43]
	v_mfma_f32_16x16x32_bf16 v[32:35], v[176:179], v[192:195], v[32:35]
	v_mfma_f32_16x16x32_bf16 v[24:27], v[168:171], v[200:203], v[24:27]
	v_mfma_f32_16x16x32_bf16 v[16:19], v[176:179], v[200:203], v[16:19]
	v_mfma_f32_16x16x32_bf16 v[8:11], v[168:171], v[208:211], v[8:11]
	v_mfma_f32_16x16x32_bf16 v[0:3], v[176:179], v[208:211], v[0:3]
	v_mfma_f32_16x16x32_bf16 v[56:59], v[172:175], v[188:191], v[56:59]
	v_mfma_f32_16x16x32_bf16 v[48:51], v[180:183], v[188:191], v[48:51]
	v_mfma_f32_16x16x32_bf16 v[40:43], v[172:175], v[196:199], v[40:43]
	v_mfma_f32_16x16x32_bf16 v[32:35], v[180:183], v[196:199], v[32:35]
	v_mfma_f32_16x16x32_bf16 v[24:27], v[172:175], v[204:207], v[24:27]
	v_mfma_f32_16x16x32_bf16 v[16:19], v[180:183], v[204:207], v[16:19]
	v_mfma_f32_16x16x32_bf16 v[8:11], v[172:175], v[212:215], v[8:11]
	v_mfma_f32_16x16x32_bf16 v[0:3], v[180:183], v[212:215], v[0:3]
	s_barrier
	s_add_i32 s66, s66, 2
	s_add_u32 s64, s64, 0x100
	s_addc_u32 s65, s65, 0
	s_cmp_gt_u32 s66, 61
	s_mov_b64 s[48:49], s[4:5]
	s_cbranch_scc0 .LBB0_233
	s_and_b64 vcc, exec, s[42:43]
	s_cbranch_vccz .LBB0_236
	s_barrier

; #define PG8_STAGE(bufoff, gbase, voff) do { _Pragma("unroll") for (int _i = 0; _i < 2; ++_i) \
;         __builtin_amdgcn_global_load_lds((const unsigned*)((const char*)(gbase) + (voff)[_i]), (PG8_LAS unsigned*)(lds + (bufoff) + ldsw + _i * 8192), 16, 0, 0); } while (0)
; #define PG8_STAGE_NT(bufoff, gbase, voff) do { _Pragma("unroll") for (int _i = 0; _i < 2; ++_i) \
;         __builtin_amdgcn_global_load_lds((const unsigned*)((const char*)(gbase) + (voff)[_i]), (PG8_LAS unsigned*)(lds + (bufoff) + ldsw + _i * 8192), 16, 0, PG8_B_AUX); } while (0)
; #define PG8_LDA(dst, b, h) do { _Pragma("unroll") for (int m = 0; m < 4; ++m) _Pragma("unroll") for (int k = 0; k < 2; ++k) dst[m][k] = *(const PG8_LAS bf16x8*)(lds + PG8_SA(b, h) + aoff + m * 2048 + k * 1024); } while (0)
; #define PG8_LDB(dst, b, h) do { _Pragma("unroll") for (int n = 0; n < 2; ++n) _Pragma("unroll") for (int k = 0; k < 2; ++k) dst[n][k] = *(const PG8_LAS bf16x8*)(lds + PG8_SB(b, h) + boff + n * 2048 + k * 1024); } while (0)
; #define PG8_WAIT_V(n) asm volatile("s_waitcnt vmcnt(" #n ")" ::: "memory")
; #define PG8_WAIT_L(n) asm volatile("s_waitcnt lgkmcnt(" #n ")" ::: "memory")
; #define PG8_BAR __builtin_amdgcn_s_barrier()
; #define PG8_SCHED __builtin_amdgcn_sched_barrier(0)
; template <class Epi, class Sched, bool ALIGN_EPI = false, bool SP2 = false>
; __device__ __forceinline__ void gemm_phase(PG8_LAS unsigned char* lds, const Gemm g, const Sched& S, const Epi& E, int wid) {
;     ...
;             const bool last = (t == nt - 2);
;             const char* a1 = cA + (size_t)(t + 1) * kstep;
;             const char* a2 = last ? nA : cA + (size_t)(t + 2) * kstep; const char* b2 = last ? nB : cB + (size_t)(t + 2) * kstep;
;             const char* a3 = a2 + kstep; const char* b3 = b2 + kstep;
;             if (last && has_next) S.a_ready(nxt);
;             if constexpr (SP2) {
;             PG8_LDB(B0, 0, 0); PG8_LDB(B1, 0, 1); PG8_SCHED; PG8_LDA(At, 0, 0); PG8_STAGE(PG8_SA(1, 1), a1 + hstepA, voffA);
;             PG8_WAIT_V(8); PG8_WAIT_L(0); PG8_BAR; PG8_MMA(0, 0, At, B0); PG8_MMA(0, 1, At, B1); PG8_BAR; PG8_SCHED;
;             PG8_LDA(At, 0, 1); PG8_STAGE_NT(PG8_SB(0, 0), b2, voffB); PG8_STAGE_NT(PG8_SB(0, 1), b2 + hstepB, voffB); PG8_STAGE(PG8_SA(0, 0), a2, voffA);
;             PG8_WAIT_V(8); PG8_WAIT_L(0); PG8_BAR; PG8_MMA(1, 0, At, B0); PG8_MMA(1, 1, At, B1); PG8_BAR; PG8_SCHED;
.LBB0_317:
	ds_read_b128 v[128:131], v205
	ds_read_b128 v[132:135], v205 offset:1024
	ds_read_b128 v[136:139], v205 offset:2048
	ds_read_b128 v[140:143], v205 offset:3072
	ds_read_b128 v[144:147], v206
	ds_read_b128 v[148:151], v206 offset:1024
	ds_read_b128 v[152:155], v206 offset:2048
	ds_read_b128 v[156:159], v206 offset:3072
	s_add_u32 s48, s46, 0x100
	s_addc_u32 s49, s47, 0
	s_add_u32 s98, s46, 0x80
	s_addc_u32 s99, s47, 0
	s_add_u32 s100, s46, 0x2b4080
	s_addc_u32 s101, s47, 0
	s_cmpk_eq_i32 s64, 0xa8
	s_cselect_b32 s53, s7, s49
	s_cselect_b32 s52, s6, s48
	s_cselect_b32 s51, s45, s63
	s_cselect_b32 s50, s44, s62
	s_add_i32 m0, s19, 0xc000
	ds_read_b128 v[160:163], v207
	ds_read_b128 v[164:167], v207 offset:1024
	ds_read_b128 v[184:187], v207 offset:2048
	ds_read_b128 v[188:191], v207 offset:3072
	ds_read_b128 v[192:195], v207 offset:4096
	ds_read_b128 v[196:199], v207 offset:5120
	ds_read_b128 v[210:213], v207 offset:6144
	ds_read_b128 v[214:217], v207 offset:7168
	global_load_lds_dwordx4 v168, s[100:101]
	s_add_i32 m0, s19, 0xe000
	s_nop 0
	global_load_lds_dwordx4 v172, s[100:101]
	s_mov_b32 m0, s29
	s_nop 0
	global_load_lds_dwordx4 v168, s[98:99]
	s_mov_b32 m0, s54
	s_nop 0
	global_load_lds_dwordx4 v172, s[98:99]
	s_waitcnt vmcnt(8)
	s_waitcnt lgkmcnt(0)
	s_barrier
	s_waitcnt lgkmcnt(0)
	v_mfma_f32_16x16x32_bf16 v[124:127], v[128:131], v[160:163], v[124:127]
	v_mfma_f32_16x16x32_bf16 v[120:123], v[136:139], v[160:163], v[120:123]
	v_mfma_f32_16x16x32_bf16 v[116:119], v[128:131], v[184:187], v[116:119]
	v_mfma_f32_16x16x32_bf16 v[112:115], v[136:139], v[184:187], v[112:115]
	v_mfma_f32_16x16x32_bf16 v[92:95], v[128:131], v[192:195], v[92:95]
	v_mfma_f32_16x16x32_bf16 v[88:91], v[136:139], v[192:195], v[88:91]
	v_mfma_f32_16x16x32_bf16 v[76:79], v[128:131], v[210:213], v[76:79]
	v_mfma_f32_16x16x32_bf16 v[72:75], v[136:139], v[210:213], v[72:75]
	v_mfma_f32_16x16x32_bf16 v[124:127], v[132:135], v[164:167], v[124:127]
	v_mfma_f32_16x16x32_bf16 v[120:123], v[140:143], v[164:167], v[120:123]
	v_mfma_f32_16x16x32_bf16 v[116:119], v[132:135], v[188:191], v[116:119]
	v_mfma_f32_16x16x32_bf16 v[112:115], v[140:143], v[188:191], v[112:115]
	v_mfma_f32_16x16x32_bf16 v[92:95], v[132:135], v[196:199], v[92:95]
	v_mfma_f32_16x16x32_bf16 v[88:91], v[140:143], v[196:199], v[88:91]
	v_mfma_f32_16x16x32_bf16 v[76:79], v[132:135], v[214:217], v[76:79]
	v_mfma_f32_16x16x32_bf16 v[72:75], v[140:143], v[214:217], v[72:75]
	v_mfma_f32_16x16x32_bf16 v[108:111], v[144:147], v[160:163], v[108:111]
	v_mfma_f32_16x16x32_bf16 v[104:107], v[152:155], v[160:163], v[104:107]
	v_mfma_f32_16x16x32_bf16 v[100:103], v[144:147], v[184:187], v[100:103]
	v_mfma_f32_16x16x32_bf16 v[96:99], v[152:155], v[184:187], v[96:99]
	v_mfma_f32_16x16x32_bf16 v[84:87], v[144:147], v[192:195], v[84:87]
	v_mfma_f32_16x16x32_bf16 v[80:83], v[152:155], v[192:195], v[80:83]
	v_mfma_f32_16x16x32_bf16 v[68:71], v[144:147], v[210:213], v[68:71]
	v_mfma_f32_16x16x32_bf16 v[64:67], v[152:155], v[210:213], v[64:67]
	v_mfma_f32_16x16x32_bf16 v[108:111], v[148:151], v[164:167], v[108:111]
	v_mfma_f32_16x16x32_bf16 v[104:107], v[156:159], v[164:167], v[104:107]
	v_mfma_f32_16x16x32_bf16 v[100:103], v[148:151], v[188:191], v[100:103]
	v_mfma_f32_16x16x32_bf16 v[96:99], v[156:159], v[188:191], v[96:99]
	v_mfma_f32_16x16x32_bf16 v[84:87], v[148:151], v[196:199], v[84:87]
	v_mfma_f32_16x16x32_bf16 v[80:83], v[156:159], v[196:199], v[80:83]
	v_mfma_f32_16x16x32_bf16 v[68:71], v[148:151], v[214:217], v[68:71]
	v_mfma_f32_16x16x32_bf16 v[64:67], v[156:159], v[214:217], v[64:67]
	s_barrier
	s_add_i32 s46, s57, s17
	s_mov_b32 m0, s46
	ds_read_b128 v[160:163], v207 offset:16384
	ds_read_b128 v[164:167], v207 offset:17408
	ds_read_b128 v[184:187], v207 offset:18432
	ds_read_b128 v[188:191], v207 offset:19456
	ds_read_b128 v[192:195], v207 offset:20480
	ds_read_b128 v[196:199], v207 offset:21504
	ds_read_b128 v[210:213], v207 offset:22528
	ds_read_b128 v[214:217], v207 offset:23552
	global_load_lds_dwordx4 v170, s[50:51]
	s_add_i32 m0, s46, 0x2000
	s_add_u32 s46, s50, 0x2b4000
	s_addc_u32 s47, s51, 0
	s_add_i32 s65, s58, s17
	global_load_lds_dwordx4 v174, s[50:51]
	s_mov_b32 m0, s65
	s_nop 0
	global_load_lds_dwordx4 v170, s[46:47]
	s_add_i32 m0, s65, 0x2000
	s_nop 0
	global_load_lds_dwordx4 v174, s[46:47]
	s_waitcnt vmcnt(4)
	s_waitcnt lgkmcnt(0)
	s_barrier
	s_waitcnt lgkmcnt(0)
	v_mfma_f32_16x16x32_bf16 v[60:63], v[128:131], v[160:163], v[60:63]
	v_mfma_f32_16x16x32_bf16 v[56:59], v[136:139], v[160:163], v[56:59]
	v_mfma_f32_16x16x32_bf16 v[44:47], v[128:131], v[184:187], v[44:47]
	v_mfma_f32_16x16x32_bf16 v[40:43], v[136:139], v[184:187], v[40:43]
	v_mfma_f32_16x16x32_bf16 v[28:31], v[128:131], v[192:195], v[28:31]
	v_mfma_f32_16x16x32_bf16 v[24:27], v[136:139], v[192:195], v[24:27]
	v_mfma_f32_16x16x32_bf16 v[12:15], v[128:131], v[210:213], v[12:15]
	v_mfma_f32_16x16x32_bf16 v[8:11], v[136:139], v[210:213], v[8:11]
	v_mfma_f32_16x16x32_bf16 v[60:63], v[132:135], v[164:167], v[60:63]
	v_mfma_f32_16x16x32_bf16 v[56:59], v[140:143], v[164:167], v[56:59]
	v_mfma_f32_16x16x32_bf16 v[44:47], v[132:135], v[188:191], v[44:47]
	v_mfma_f32_16x16x32_bf16 v[40:43], v[140:143], v[188:191], v[40:43]
	v_mfma_f32_16x16x32_bf16 v[28:31], v[132:135], v[196:199], v[28:31]
	v_mfma_f32_16x16x32_bf16 v[24:27], v[140:143], v[196:199], v[24:27]
	v_mfma_f32_16x16x32_bf16 v[12:15], v[132:135], v[214:217], v[12:15]
	v_mfma_f32_16x16x32_bf16 v[8:11], v[140:143], v[214:217], v[8:11]
	v_mfma_f32_16x16x32_bf16 v[52:55], v[144:147], v[160:163], v[52:55]
	v_mfma_f32_16x16x32_bf16 v[48:51], v[152:155], v[160:163], v[48:51]
	v_mfma_f32_16x16x32_bf16 v[36:39], v[144:147], v[184:187], v[36:39]
	v_mfma_f32_16x16x32_bf16 v[32:35], v[152:155], v[184:187], v[32:35]
	v_mfma_f32_16x16x32_bf16 v[20:23], v[144:147], v[192:195], v[20:23]
	v_mfma_f32_16x16x32_bf16 v[16:19], v[152:155], v[192:195], v[16:19]
	v_mfma_f32_16x16x32_bf16 v[4:7], v[144:147], v[210:213], v[4:7]
	v_mfma_f32_16x16x32_bf16 v[0:3], v[152:155], v[210:213], v[0:3]
	v_mfma_f32_16x16x32_bf16 v[52:55], v[148:151], v[164:167], v[52:55]
	v_mfma_f32_16x16x32_bf16 v[48:51], v[156:159], v[164:167], v[48:51]
	v_mfma_f32_16x16x32_bf16 v[36:39], v[148:151], v[188:191], v[36:39]
	v_mfma_f32_16x16x32_bf16 v[32:35], v[156:159], v[188:191], v[32:35]
	v_mfma_f32_16x16x32_bf16 v[20:23], v[148:151], v[196:199], v[20:23]
	v_mfma_f32_16x16x32_bf16 v[16:19], v[156:159], v[196:199], v[16:19]
	v_mfma_f32_16x16x32_bf16 v[4:7], v[148:151], v[214:217], v[4:7]
	v_mfma_f32_16x16x32_bf16 v[0:3], v[156:159], v[214:217], v[0:3]
	s_barrier
; #define PG8_STAGE(bufoff, gbase, voff) do { _Pragma("unroll") for (int _i = 0; _i < 2; ++_i) \
;         __builtin_amdgcn_global_load_lds((const unsigned*)((const char*)(gbase) + (voff)[_i]), (PG8_LAS unsigned*)(lds + (bufoff) + ldsw + _i * 8192), 16, 0, 0); } while (0)
; #define PG8_STAGE_NT(bufoff, gbase, voff) do { _Pragma("unroll") for (int _i = 0; _i < 2; ++_i) \
;         __builtin_amdgcn_global_load_lds((const unsigned*)((const char*)(gbase) + (voff)[_i]), (PG8_LAS unsigned*)(lds + (bufoff) + ldsw + _i * 8192), 16, 0, PG8_B_AUX); } while (0)
; #define PG8_LDA(dst, b, h) do { _Pragma("unroll") for (int m = 0; m < 4; ++m) _Pragma("unroll") for (int k = 0; k < 2; ++k) dst[m][k] = *(const PG8_LAS bf16x8*)(lds + PG8_SA(b, h) + aoff + m * 2048 + k * 1024); } while (0)
; #define PG8_LDB(dst, b, h) do { _Pragma("unroll") for (int n = 0; n < 2; ++n) _Pragma("unroll") for (int k = 0; k < 2; ++k) dst[n][k] = *(const PG8_LAS bf16x8*)(lds + PG8_SB(b, h) + boff + n * 2048 + k * 1024); } while (0)
; #define PG8_MMA(ai, bj, At, Bt) do { __builtin_amdgcn_s_setprio(1); _Pragma("unroll") for (int m = 0; m < 4; ++m) _Pragma("unroll") for (int n = 0; n < 2; ++n) _Pragma("unroll") for (int k = 0; k < 2; ++k) \
;         acc[ai][bj][m][n] = __builtin_amdgcn_mfma_f32_16x16x32_bf16(Bt[n][k], At[m][k], acc[ai][bj][m][n], 0, 0, 0); __builtin_amdgcn_s_setprio(0); } while (0)
; #define PG8_WAIT_V(n) asm volatile("s_waitcnt vmcnt(" #n ")" ::: "memory")
; #define PG8_WAIT_L(n) asm volatile("s_waitcnt lgkmcnt(" #n ")" ::: "memory")
; #define PG8_BAR __builtin_amdgcn_s_barrier()
; template <class Epi, class Sched, bool ALIGN_EPI = false, bool SP2 = false>
; __device__ __forceinline__ void gemm_phase(PG8_LAS unsigned char* lds, const Gemm g, const Sched& S, const Epi& E, int wid) {
;     ...
;             PG8_LDB(B0, 1, 0); PG8_LDB(B1, 1, 1); PG8_SCHED; PG8_LDA(At, 1, 0); PG8_STAGE(PG8_SA(0, 1), a2 + hstepA, voffA);
;             PG8_WAIT_V(8); PG8_WAIT_L(0); PG8_BAR; PG8_MMA(0, 0, At, B0); PG8_MMA(0, 1, At, B1); PG8_BAR; PG8_SCHED;
;             PG8_LDA(At, 1, 1); PG8_STAGE_NT(PG8_SB(1, 0), b3, voffB); PG8_STAGE_NT(PG8_SB(1, 1), b3 + hstepB, voffB); PG8_STAGE(PG8_SA(1, 0), a3, voffA);
;             PG8_WAIT_V(8); PG8_WAIT_L(0); PG8_BAR; PG8_MMA(1, 0, At, B0); PG8_MMA(1, 1, At, B1); PG8_BAR; PG8_SCHED;
;     ...
;         if constexpr (ALIGN_EPI) { if (wr == 0) PG8_BAR; }
	s_add_i32 s65, 0, 0x18000
	v_add_u32_e32 v140, s65, v203
	s_add_i32 s66, 0, 0x1c000
	ds_read_b128 v[128:131], v140
	ds_read_b128 v[132:135], v140 offset:1024
	ds_read_b128 v[136:139], v140 offset:2048
	ds_read_b128 v[140:143], v140 offset:3072
	v_add_u32_e32 v156, s66, v203
	ds_read_b128 v[144:147], v156
	ds_read_b128 v[148:151], v156 offset:1024
	ds_read_b128 v[152:155], v156 offset:2048
	ds_read_b128 v[156:159], v156 offset:3072
	s_add_u32 s46, s52, 0x2b4000
	s_addc_u32 s47, s53, 0
	s_mov_b32 m0, s23
	ds_read_b128 v[160:163], v207 offset:32768
	ds_read_b128 v[164:167], v207 offset:33792
	ds_read_b128 v[184:187], v207 offset:34816
	ds_read_b128 v[188:191], v207 offset:35840
	ds_read_b128 v[192:195], v207 offset:36864
	ds_read_b128 v[196:199], v207 offset:37888
	ds_read_b128 v[210:213], v207 offset:38912
	ds_read_b128 v[214:217], v207 offset:39936
	global_load_lds_dwordx4 v168, s[46:47]
	s_mov_b32 m0, s24
	s_nop 0
	global_load_lds_dwordx4 v172, s[46:47]
	s_mov_b32 m0, s19
	s_nop 0
	global_load_lds_dwordx4 v168, s[52:53]
	s_mov_b32 m0, s22
	s_nop 0
	global_load_lds_dwordx4 v172, s[52:53]
	s_nop 0
	s_waitcnt vmcnt(8)
	s_waitcnt lgkmcnt(0)
	s_barrier
	s_waitcnt lgkmcnt(0)
	v_mfma_f32_16x16x32_bf16 v[124:127], v[128:131], v[160:163], v[124:127]
	v_mfma_f32_16x16x32_bf16 v[120:123], v[136:139], v[160:163], v[120:123]
	v_mfma_f32_16x16x32_bf16 v[116:119], v[128:131], v[184:187], v[116:119]
	v_mfma_f32_16x16x32_bf16 v[112:115], v[136:139], v[184:187], v[112:115]
	v_mfma_f32_16x16x32_bf16 v[92:95], v[128:131], v[192:195], v[92:95]
	v_mfma_f32_16x16x32_bf16 v[88:91], v[136:139], v[192:195], v[88:91]
	v_mfma_f32_16x16x32_bf16 v[76:79], v[128:131], v[210:213], v[76:79]
	v_mfma_f32_16x16x32_bf16 v[72:75], v[136:139], v[210:213], v[72:75]
	v_mfma_f32_16x16x32_bf16 v[124:127], v[132:135], v[164:167], v[124:127]
	v_mfma_f32_16x16x32_bf16 v[120:123], v[140:143], v[164:167], v[120:123]
	v_mfma_f32_16x16x32_bf16 v[116:119], v[132:135], v[188:191], v[116:119]
	v_mfma_f32_16x16x32_bf16 v[112:115], v[140:143], v[188:191], v[112:115]
	v_mfma_f32_16x16x32_bf16 v[92:95], v[132:135], v[196:199], v[92:95]
	v_mfma_f32_16x16x32_bf16 v[88:91], v[140:143], v[196:199], v[88:91]
	v_mfma_f32_16x16x32_bf16 v[76:79], v[132:135], v[214:217], v[76:79]
	v_mfma_f32_16x16x32_bf16 v[72:75], v[140:143], v[214:217], v[72:75]
	v_mfma_f32_16x16x32_bf16 v[108:111], v[144:147], v[160:163], v[108:111]
	v_mfma_f32_16x16x32_bf16 v[104:107], v[152:155], v[160:163], v[104:107]
	v_mfma_f32_16x16x32_bf16 v[100:103], v[144:147], v[184:187], v[100:103]
	v_mfma_f32_16x16x32_bf16 v[96:99], v[152:155], v[184:187], v[96:99]
	v_mfma_f32_16x16x32_bf16 v[84:87], v[144:147], v[192:195], v[84:87]
	v_mfma_f32_16x16x32_bf16 v[80:83], v[152:155], v[192:195], v[80:83]
	v_mfma_f32_16x16x32_bf16 v[68:71], v[144:147], v[210:213], v[68:71]
	v_mfma_f32_16x16x32_bf16 v[64:67], v[152:155], v[210:213], v[64:67]
	v_mfma_f32_16x16x32_bf16 v[108:111], v[148:151], v[164:167], v[108:111]
	v_mfma_f32_16x16x32_bf16 v[104:107], v[156:159], v[164:167], v[104:107]
	v_mfma_f32_16x16x32_bf16 v[100:103], v[148:151], v[188:191], v[100:103]
	v_mfma_f32_16x16x32_bf16 v[96:99], v[156:159], v[188:191], v[96:99]
	v_mfma_f32_16x16x32_bf16 v[84:87], v[148:151], v[196:199], v[84:87]
	v_mfma_f32_16x16x32_bf16 v[80:83], v[156:159], v[196:199], v[80:83]
	v_mfma_f32_16x16x32_bf16 v[68:71], v[148:151], v[214:217], v[68:71]
	v_mfma_f32_16x16x32_bf16 v[64:67], v[156:159], v[214:217], v[64:67]
	s_barrier
	s_add_i32 s46, s65, s17
	s_mov_b32 m0, s46
	s_add_u32 s98, s50, 0x80
	s_addc_u32 s99, s51, 0
	ds_read_b128 v[160:163], v207 offset:49152
	ds_read_b128 v[164:167], v207 offset:50176
	ds_read_b128 v[184:187], v207 offset:51200
	ds_read_b128 v[188:191], v207 offset:52224
	ds_read_b128 v[192:195], v207 offset:53248
	ds_read_b128 v[196:199], v207 offset:54272
	ds_read_b128 v[210:213], v207 offset:55296
	ds_read_b128 v[214:217], v207 offset:56320
	global_load_lds_dwordx4 v170, s[98:99]
	s_add_i32 m0, s46, 0x2000
	s_add_u32 s46, s50, 0x2b4080
	s_addc_u32 s47, s51, 0
	s_add_i32 s50, s66, s17
	global_load_lds_dwordx4 v174, s[98:99]
	s_mov_b32 m0, s50
	s_nop 0
	global_load_lds_dwordx4 v170, s[46:47]
	s_add_i32 m0, s50, 0x2000
	s_nop 0
	global_load_lds_dwordx4 v174, s[46:47]
	s_nop 0
	s_waitcnt vmcnt(4)
	s_waitcnt lgkmcnt(0)
	s_barrier
	s_waitcnt lgkmcnt(0)
	v_mfma_f32_16x16x32_bf16 v[60:63], v[128:131], v[160:163], v[60:63]
	v_mfma_f32_16x16x32_bf16 v[56:59], v[136:139], v[160:163], v[56:59]
	v_mfma_f32_16x16x32_bf16 v[44:47], v[128:131], v[184:187], v[44:47]
	v_mfma_f32_16x16x32_bf16 v[40:43], v[136:139], v[184:187], v[40:43]
	v_mfma_f32_16x16x32_bf16 v[28:31], v[128:131], v[192:195], v[28:31]
	v_mfma_f32_16x16x32_bf16 v[24:27], v[136:139], v[192:195], v[24:27]
	v_mfma_f32_16x16x32_bf16 v[12:15], v[128:131], v[210:213], v[12:15]
	v_mfma_f32_16x16x32_bf16 v[8:11], v[136:139], v[210:213], v[8:11]
	v_mfma_f32_16x16x32_bf16 v[60:63], v[132:135], v[164:167], v[60:63]
	v_mfma_f32_16x16x32_bf16 v[56:59], v[140:143], v[164:167], v[56:59]
	v_mfma_f32_16x16x32_bf16 v[44:47], v[132:135], v[188:191], v[44:47]
	v_mfma_f32_16x16x32_bf16 v[40:43], v[140:143], v[188:191], v[40:43]
	v_mfma_f32_16x16x32_bf16 v[28:31], v[132:135], v[196:199], v[28:31]
	v_mfma_f32_16x16x32_bf16 v[24:27], v[140:143], v[196:199], v[24:27]
	v_mfma_f32_16x16x32_bf16 v[12:15], v[132:135], v[214:217], v[12:15]
	v_mfma_f32_16x16x32_bf16 v[8:11], v[140:143], v[214:217], v[8:11]
	v_mfma_f32_16x16x32_bf16 v[52:55], v[144:147], v[160:163], v[52:55]
	v_mfma_f32_16x16x32_bf16 v[48:51], v[152:155], v[160:163], v[48:51]
	v_mfma_f32_16x16x32_bf16 v[36:39], v[144:147], v[184:187], v[36:39]
	v_mfma_f32_16x16x32_bf16 v[32:35], v[152:155], v[184:187], v[32:35]
	v_mfma_f32_16x16x32_bf16 v[20:23], v[144:147], v[192:195], v[20:23]
	v_mfma_f32_16x16x32_bf16 v[16:19], v[152:155], v[192:195], v[16:19]
	v_mfma_f32_16x16x32_bf16 v[4:7], v[144:147], v[210:213], v[4:7]
	v_mfma_f32_16x16x32_bf16 v[0:3], v[152:155], v[210:213], v[0:3]
	v_mfma_f32_16x16x32_bf16 v[52:55], v[148:151], v[164:167], v[52:55]
	v_mfma_f32_16x16x32_bf16 v[48:51], v[156:159], v[164:167], v[48:51]
	v_mfma_f32_16x16x32_bf16 v[36:39], v[148:151], v[188:191], v[36:39]
	v_mfma_f32_16x16x32_bf16 v[32:35], v[156:159], v[188:191], v[32:35]
	v_mfma_f32_16x16x32_bf16 v[20:23], v[148:151], v[196:199], v[20:23]
	v_mfma_f32_16x16x32_bf16 v[16:19], v[156:159], v[196:199], v[16:19]
	v_mfma_f32_16x16x32_bf16 v[4:7], v[148:151], v[214:217], v[4:7]
	v_mfma_f32_16x16x32_bf16 v[0:3], v[156:159], v[214:217], v[0:3]
	s_barrier
	s_add_i32 s64, s64, 2
	s_add_u32 s62, s62, 0x100
	s_addc_u32 s63, s63, 0
	s_cmpk_gt_u32 s64, 0xa9
	s_mov_b64 s[46:47], s[48:49]
	s_cbranch_scc0 .LBB0_317
	s_and_b64 vcc, exec, s[42:43]
	s_cbranch_vccz .LBB0_320
	s_barrier

; #define PG8_STAGE(bufoff, gbase, voff) do { _Pragma("unroll") for (int _i = 0; _i < 2; ++_i) \
;         __builtin_amdgcn_global_load_lds((const unsigned*)((const char*)(gbase) + (voff)[_i]), (PG8_LAS unsigned*)(lds + (bufoff) + ldsw + _i * 8192), 16, 0, 0); } while (0)
; #define PG8_STAGE_NT(bufoff, gbase, voff) do { _Pragma("unroll") for (int _i = 0; _i < 2; ++_i) \
;         __builtin_amdgcn_global_load_lds((const unsigned*)((const char*)(gbase) + (voff)[_i]), (PG8_LAS unsigned*)(lds + (bufoff) + ldsw + _i * 8192), 16, 0, PG8_B_AUX); } while (0)
; #define PG8_LDA(dst, b, h) do { _Pragma("unroll") for (int m = 0; m < 4; ++m) _Pragma("unroll") for (int k = 0; k < 2; ++k) dst[m][k] = *(const PG8_LAS bf16x8*)(lds + PG8_SA(b, h) + aoff + m * 2048 + k * 1024); } while (0)
; #define PG8_LDB(dst, b, h) do { _Pragma("unroll") for (int n = 0; n < 2; ++n) _Pragma("unroll") for (int k = 0; k < 2; ++k) dst[n][k] = *(const PG8_LAS bf16x8*)(lds + PG8_SB(b, h) + boff + n * 2048 + k * 1024); } while (0)
; #define PG8_WAIT_V(n) asm volatile("s_waitcnt vmcnt(" #n ")" ::: "memory")
; #define PG8_WAIT_L(n) asm volatile("s_waitcnt lgkmcnt(" #n ")" ::: "memory")
; #define PG8_BAR __builtin_amdgcn_s_barrier()
; #define PG8_SCHED __builtin_amdgcn_sched_barrier(0)
; template <class Epi, class Sched, bool ALIGN_EPI = false, bool SP2 = false>
; __device__ __forceinline__ void gemm_phase(PG8_LAS unsigned char* lds, const Gemm g, const Sched& S, const Epi& E, int wid) {
;     ...
;             const bool last = (t == nt - 2);
;             const char* a1 = cA + (size_t)(t + 1) * kstep;
;             const char* a2 = last ? nA : cA + (size_t)(t + 2) * kstep; const char* b2 = last ? nB : cB + (size_t)(t + 2) * kstep;
;             const char* a3 = a2 + kstep; const char* b3 = b2 + kstep;
;             if (last && has_next) S.a_ready(nxt);
;             if constexpr (SP2) {
;             PG8_LDB(B0, 0, 0); PG8_LDB(B1, 0, 1); PG8_SCHED; PG8_LDA(At, 0, 0); PG8_STAGE(PG8_SA(1, 1), a1 + hstepA, voffA);
;             PG8_WAIT_V(8); PG8_WAIT_L(0); PG8_BAR; PG8_MMA(0, 0, At, B0); PG8_MMA(0, 1, At, B1); PG8_BAR; PG8_SCHED;
;             PG8_LDA(At, 0, 1); PG8_STAGE_NT(PG8_SB(0, 0), b2, voffB); PG8_STAGE_NT(PG8_SB(0, 1), b2 + hstepB, voffB); PG8_STAGE(PG8_SA(0, 0), a2, voffA);
;             PG8_WAIT_V(8); PG8_WAIT_L(0); PG8_BAR; PG8_MMA(1, 0, At, B0); PG8_MMA(1, 1, At, B1); PG8_BAR; PG8_SCHED;
.LBB0_426:
	ds_read_b128 v[144:147], v161
	ds_read_b128 v[148:151], v161 offset:1024
	ds_read_b128 v[152:155], v161 offset:2048
	ds_read_b128 v[166:169], v161 offset:3072
	ds_read_b128 v[170:173], v162
	ds_read_b128 v[174:177], v162 offset:1024
	ds_read_b128 v[178:181], v162 offset:2048
	ds_read_b128 v[182:185], v162 offset:3072
	s_add_u32 s4, s46, 0x100
	s_addc_u32 s5, s47, 0
	s_add_u32 s98, s46, 0x80
	s_addc_u32 s99, s47, 0
	s_add_u32 s100, s46, 0x104080
	s_addc_u32 s101, s47, 0
	s_cmp_eq_u32 s64, 60
	s_cselect_b32 s51, s43, s5
	s_cselect_b32 s50, s42, s4
	s_cselect_b32 s49, s45, s63
	s_cselect_b32 s48, s44, s62
	s_add_i32 m0, s23, 0xc000
	ds_read_b128 v[186:189], v163
	ds_read_b128 v[190:193], v163 offset:1024
	ds_read_b128 v[194:197], v163 offset:2048
	ds_read_b128 v[198:201], v163 offset:3072
	ds_read_b128 v[202:205], v163 offset:4096
	ds_read_b128 v[206:209], v163 offset:5120
	ds_read_b128 v[210:213], v163 offset:6144
	ds_read_b128 v[214:217], v163 offset:7168
	global_load_lds_dwordx4 v134, s[100:101]
	s_add_i32 m0, s23, 0xe000
	s_nop 0
	global_load_lds_dwordx4 v130, s[100:101]
	s_mov_b32 m0, s53
	s_nop 0
	global_load_lds_dwordx4 v134, s[98:99]
	s_mov_b32 m0, s54
	s_nop 0
	global_load_lds_dwordx4 v130, s[98:99]
	s_waitcnt vmcnt(8)
	s_waitcnt lgkmcnt(0)
	s_barrier
	s_waitcnt lgkmcnt(0)
	v_mfma_f32_16x16x32_bf16 v[124:127], v[144:147], v[186:189], v[124:127]
	v_mfma_f32_16x16x32_bf16 v[120:123], v[152:155], v[186:189], v[120:123]
	v_mfma_f32_16x16x32_bf16 v[116:119], v[144:147], v[194:197], v[116:119]
	v_mfma_f32_16x16x32_bf16 v[112:115], v[152:155], v[194:197], v[112:115]
	v_mfma_f32_16x16x32_bf16 v[92:95], v[144:147], v[202:205], v[92:95]
	v_mfma_f32_16x16x32_bf16 v[88:91], v[152:155], v[202:205], v[88:91]
	v_mfma_f32_16x16x32_bf16 v[76:79], v[144:147], v[210:213], v[76:79]
	v_mfma_f32_16x16x32_bf16 v[72:75], v[152:155], v[210:213], v[72:75]
	v_mfma_f32_16x16x32_bf16 v[124:127], v[148:151], v[190:193], v[124:127]
	v_mfma_f32_16x16x32_bf16 v[120:123], v[166:169], v[190:193], v[120:123]
	v_mfma_f32_16x16x32_bf16 v[116:119], v[148:151], v[198:201], v[116:119]
	v_mfma_f32_16x16x32_bf16 v[112:115], v[166:169], v[198:201], v[112:115]
	v_mfma_f32_16x16x32_bf16 v[92:95], v[148:151], v[206:209], v[92:95]
	v_mfma_f32_16x16x32_bf16 v[88:91], v[166:169], v[206:209], v[88:91]
	v_mfma_f32_16x16x32_bf16 v[76:79], v[148:151], v[214:217], v[76:79]
	v_mfma_f32_16x16x32_bf16 v[72:75], v[166:169], v[214:217], v[72:75]
	v_mfma_f32_16x16x32_bf16 v[108:111], v[170:173], v[186:189], v[108:111]
	v_mfma_f32_16x16x32_bf16 v[104:107], v[178:181], v[186:189], v[104:107]
	v_mfma_f32_16x16x32_bf16 v[100:103], v[170:173], v[194:197], v[100:103]
	v_mfma_f32_16x16x32_bf16 v[96:99], v[178:181], v[194:197], v[96:99]
	v_mfma_f32_16x16x32_bf16 v[84:87], v[170:173], v[202:205], v[84:87]
	v_mfma_f32_16x16x32_bf16 v[80:83], v[178:181], v[202:205], v[80:83]
	v_mfma_f32_16x16x32_bf16 v[68:71], v[170:173], v[210:213], v[68:71]
	v_mfma_f32_16x16x32_bf16 v[64:67], v[178:181], v[210:213], v[64:67]
	v_mfma_f32_16x16x32_bf16 v[108:111], v[174:177], v[190:193], v[108:111]
	v_mfma_f32_16x16x32_bf16 v[104:107], v[182:185], v[190:193], v[104:107]
	v_mfma_f32_16x16x32_bf16 v[100:103], v[174:177], v[198:201], v[100:103]
	v_mfma_f32_16x16x32_bf16 v[96:99], v[182:185], v[198:201], v[96:99]
	v_mfma_f32_16x16x32_bf16 v[84:87], v[174:177], v[206:209], v[84:87]
	v_mfma_f32_16x16x32_bf16 v[80:83], v[182:185], v[206:209], v[80:83]
	v_mfma_f32_16x16x32_bf16 v[68:71], v[174:177], v[214:217], v[68:71]
	v_mfma_f32_16x16x32_bf16 v[64:67], v[182:185], v[214:217], v[64:67]
	s_barrier
	s_add_i32 s46, s56, s17
	s_mov_b32 m0, s46
	ds_read_b128 v[186:189], v163 offset:16384
	ds_read_b128 v[190:193], v163 offset:17408
	ds_read_b128 v[194:197], v163 offset:18432
	ds_read_b128 v[198:201], v163 offset:19456
	ds_read_b128 v[202:205], v163 offset:20480
	ds_read_b128 v[206:209], v163 offset:21504
	ds_read_b128 v[210:213], v163 offset:22528
	ds_read_b128 v[214:217], v163 offset:23552
	global_load_lds_dwordx4 v132, s[48:49]
	s_add_i32 m0, s46, 0x2000
	s_add_u32 s46, s48, 0x104000
	s_addc_u32 s47, s49, 0
	s_add_i32 s65, s57, s17
	global_load_lds_dwordx4 v128, s[48:49]
	s_mov_b32 m0, s65
	s_nop 0
	global_load_lds_dwordx4 v132, s[46:47]
	s_add_i32 m0, s65, 0x2000
	s_nop 0
	global_load_lds_dwordx4 v128, s[46:47]
	s_waitcnt vmcnt(4)
	s_waitcnt lgkmcnt(0)
	s_barrier
	s_waitcnt lgkmcnt(0)
	v_mfma_f32_16x16x32_bf16 v[60:63], v[144:147], v[186:189], v[60:63]
	v_mfma_f32_16x16x32_bf16 v[56:59], v[152:155], v[186:189], v[56:59]
	v_mfma_f32_16x16x32_bf16 v[44:47], v[144:147], v[194:197], v[44:47]
	v_mfma_f32_16x16x32_bf16 v[40:43], v[152:155], v[194:197], v[40:43]
	v_mfma_f32_16x16x32_bf16 v[28:31], v[144:147], v[202:205], v[28:31]
	v_mfma_f32_16x16x32_bf16 v[24:27], v[152:155], v[202:205], v[24:27]
	v_mfma_f32_16x16x32_bf16 v[12:15], v[144:147], v[210:213], v[12:15]
	v_mfma_f32_16x16x32_bf16 v[8:11], v[152:155], v[210:213], v[8:11]
	v_mfma_f32_16x16x32_bf16 v[60:63], v[148:151], v[190:193], v[60:63]
	v_mfma_f32_16x16x32_bf16 v[56:59], v[166:169], v[190:193], v[56:59]
	v_mfma_f32_16x16x32_bf16 v[44:47], v[148:151], v[198:201], v[44:47]
	v_mfma_f32_16x16x32_bf16 v[40:43], v[166:169], v[198:201], v[40:43]
	v_mfma_f32_16x16x32_bf16 v[28:31], v[148:151], v[206:209], v[28:31]
	v_mfma_f32_16x16x32_bf16 v[24:27], v[166:169], v[206:209], v[24:27]
	v_mfma_f32_16x16x32_bf16 v[12:15], v[148:151], v[214:217], v[12:15]
	v_mfma_f32_16x16x32_bf16 v[8:11], v[166:169], v[214:217], v[8:11]
	v_mfma_f32_16x16x32_bf16 v[52:55], v[170:173], v[186:189], v[52:55]
	v_mfma_f32_16x16x32_bf16 v[48:51], v[178:181], v[186:189], v[48:51]
	v_mfma_f32_16x16x32_bf16 v[36:39], v[170:173], v[194:197], v[36:39]
	v_mfma_f32_16x16x32_bf16 v[32:35], v[178:181], v[194:197], v[32:35]
	v_mfma_f32_16x16x32_bf16 v[20:23], v[170:173], v[202:205], v[20:23]
	v_mfma_f32_16x16x32_bf16 v[16:19], v[178:181], v[202:205], v[16:19]
	v_mfma_f32_16x16x32_bf16 v[4:7], v[170:173], v[210:213], v[4:7]
	v_mfma_f32_16x16x32_bf16 v[0:3], v[178:181], v[210:213], v[0:3]
	v_mfma_f32_16x16x32_bf16 v[52:55], v[174:177], v[190:193], v[52:55]
	v_mfma_f32_16x16x32_bf16 v[48:51], v[182:185], v[190:193], v[48:51]
	v_mfma_f32_16x16x32_bf16 v[36:39], v[174:177], v[198:201], v[36:39]
	v_mfma_f32_16x16x32_bf16 v[32:35], v[182:185], v[198:201], v[32:35]
	v_mfma_f32_16x16x32_bf16 v[20:23], v[174:177], v[206:209], v[20:23]
	v_mfma_f32_16x16x32_bf16 v[16:19], v[182:185], v[206:209], v[16:19]
	v_mfma_f32_16x16x32_bf16 v[4:7], v[174:177], v[214:217], v[4:7]
	v_mfma_f32_16x16x32_bf16 v[0:3], v[182:185], v[214:217], v[0:3]
	s_barrier
; #define PG8_STAGE(bufoff, gbase, voff) do { _Pragma("unroll") for (int _i = 0; _i < 2; ++_i) \
;         __builtin_amdgcn_global_load_lds((const unsigned*)((const char*)(gbase) + (voff)[_i]), (PG8_LAS unsigned*)(lds + (bufoff) + ldsw + _i * 8192), 16, 0, 0); } while (0)
; #define PG8_STAGE_NT(bufoff, gbase, voff) do { _Pragma("unroll") for (int _i = 0; _i < 2; ++_i) \
;         __builtin_amdgcn_global_load_lds((const unsigned*)((const char*)(gbase) + (voff)[_i]), (PG8_LAS unsigned*)(lds + (bufoff) + ldsw + _i * 8192), 16, 0, PG8_B_AUX); } while (0)
; #define PG8_LDA(dst, b, h) do { _Pragma("unroll") for (int m = 0; m < 4; ++m) _Pragma("unroll") for (int k = 0; k < 2; ++k) dst[m][k] = *(const PG8_LAS bf16x8*)(lds + PG8_SA(b, h) + aoff + m * 2048 + k * 1024); } while (0)
; #define PG8_LDB(dst, b, h) do { _Pragma("unroll") for (int n = 0; n < 2; ++n) _Pragma("unroll") for (int k = 0; k < 2; ++k) dst[n][k] = *(const PG8_LAS bf16x8*)(lds + PG8_SB(b, h) + boff + n * 2048 + k * 1024); } while (0)
; #define PG8_MMA(ai, bj, At, Bt) do { __builtin_amdgcn_s_setprio(1); _Pragma("unroll") for (int m = 0; m < 4; ++m) _Pragma("unroll") for (int n = 0; n < 2; ++n) _Pragma("unroll") for (int k = 0; k < 2; ++k) \
;         acc[ai][bj][m][n] = __builtin_amdgcn_mfma_f32_16x16x32_bf16(Bt[n][k], At[m][k], acc[ai][bj][m][n], 0, 0, 0); __builtin_amdgcn_s_setprio(0); } while (0)
; #define PG8_WAIT_V(n) asm volatile("s_waitcnt vmcnt(" #n ")" ::: "memory")
; #define PG8_WAIT_L(n) asm volatile("s_waitcnt lgkmcnt(" #n ")" ::: "memory")
; #define PG8_BAR __builtin_amdgcn_s_barrier()
; template <class Epi, class Sched, bool ALIGN_EPI = false, bool SP2 = false>
; __device__ __forceinline__ void gemm_phase(PG8_LAS unsigned char* lds, const Gemm g, const Sched& S, const Epi& E, int wid) {
;     ...
;             PG8_LDB(B0, 1, 0); PG8_LDB(B1, 1, 1); PG8_SCHED; PG8_LDA(At, 1, 0); PG8_STAGE(PG8_SA(0, 1), a2 + hstepA, voffA);
;             PG8_WAIT_V(8); PG8_WAIT_L(0); PG8_BAR; PG8_MMA(0, 0, At, B0); PG8_MMA(0, 1, At, B1); PG8_BAR; PG8_SCHED;
;             PG8_LDA(At, 1, 1); PG8_STAGE_NT(PG8_SB(1, 0), b3, voffB); PG8_STAGE_NT(PG8_SB(1, 1), b3 + hstepB, voffB); PG8_STAGE(PG8_SA(1, 0), a3, voffA);
;             PG8_WAIT_V(8); PG8_WAIT_L(0); PG8_BAR; PG8_MMA(1, 0, At, B0); PG8_MMA(1, 1, At, B1); PG8_BAR; PG8_SCHED;
;     ...
;         if constexpr (ALIGN_EPI) { if (wr == 0) PG8_BAR; }
	s_add_i32 s65, 0, 0x18000
	v_add_u32_e32 v165, s65, v159
	s_add_i32 s66, 0, 0x1c000
	ds_read_b128 v[144:147], v165
	ds_read_b128 v[148:151], v165 offset:1024
	ds_read_b128 v[152:155], v165 offset:2048
	ds_read_b128 v[166:169], v165 offset:3072
	v_add_u32_e32 v165, s66, v159
	ds_read_b128 v[170:173], v165
	ds_read_b128 v[174:177], v165 offset:1024
	ds_read_b128 v[178:181], v165 offset:2048
	ds_read_b128 v[182:185], v165 offset:3072
	s_add_u32 s46, s50, 0x104000
	s_addc_u32 s47, s51, 0
	s_mov_b32 m0, s25
	ds_read_b128 v[186:189], v163 offset:32768
	ds_read_b128 v[190:193], v163 offset:33792
	ds_read_b128 v[194:197], v163 offset:34816
	ds_read_b128 v[198:201], v163 offset:35840
	ds_read_b128 v[202:205], v163 offset:36864
	ds_read_b128 v[206:209], v163 offset:37888
	ds_read_b128 v[210:213], v163 offset:38912
	ds_read_b128 v[214:217], v163 offset:39936
	global_load_lds_dwordx4 v134, s[46:47]
	s_mov_b32 m0, s29
	s_nop 0
	global_load_lds_dwordx4 v130, s[46:47]
	s_mov_b32 m0, s23
	s_nop 0
	global_load_lds_dwordx4 v134, s[50:51]
	s_mov_b32 m0, s24
	s_nop 0
	global_load_lds_dwordx4 v130, s[50:51]
	s_nop 0
	s_waitcnt vmcnt(8)
	s_waitcnt lgkmcnt(0)
	s_barrier
	s_waitcnt lgkmcnt(0)
	v_mfma_f32_16x16x32_bf16 v[124:127], v[144:147], v[186:189], v[124:127]
	v_mfma_f32_16x16x32_bf16 v[120:123], v[152:155], v[186:189], v[120:123]
	v_mfma_f32_16x16x32_bf16 v[116:119], v[144:147], v[194:197], v[116:119]
	v_mfma_f32_16x16x32_bf16 v[112:115], v[152:155], v[194:197], v[112:115]
	v_mfma_f32_16x16x32_bf16 v[92:95], v[144:147], v[202:205], v[92:95]
	v_mfma_f32_16x16x32_bf16 v[88:91], v[152:155], v[202:205], v[88:91]
	v_mfma_f32_16x16x32_bf16 v[76:79], v[144:147], v[210:213], v[76:79]
	v_mfma_f32_16x16x32_bf16 v[72:75], v[152:155], v[210:213], v[72:75]
	v_mfma_f32_16x16x32_bf16 v[124:127], v[148:151], v[190:193], v[124:127]
	v_mfma_f32_16x16x32_bf16 v[120:123], v[166:169], v[190:193], v[120:123]
	v_mfma_f32_16x16x32_bf16 v[116:119], v[148:151], v[198:201], v[116:119]
	v_mfma_f32_16x16x32_bf16 v[112:115], v[166:169], v[198:201], v[112:115]
	v_mfma_f32_16x16x32_bf16 v[92:95], v[148:151], v[206:209], v[92:95]
	v_mfma_f32_16x16x32_bf16 v[88:91], v[166:169], v[206:209], v[88:91]
	v_mfma_f32_16x16x32_bf16 v[76:79], v[148:151], v[214:217], v[76:79]
	v_mfma_f32_16x16x32_bf16 v[72:75], v[166:169], v[214:217], v[72:75]
	v_mfma_f32_16x16x32_bf16 v[108:111], v[170:173], v[186:189], v[108:111]
	v_mfma_f32_16x16x32_bf16 v[104:107], v[178:181], v[186:189], v[104:107]
	v_mfma_f32_16x16x32_bf16 v[100:103], v[170:173], v[194:197], v[100:103]
	v_mfma_f32_16x16x32_bf16 v[96:99], v[178:181], v[194:197], v[96:99]
	v_mfma_f32_16x16x32_bf16 v[84:87], v[170:173], v[202:205], v[84:87]
	v_mfma_f32_16x16x32_bf16 v[80:83], v[178:181], v[202:205], v[80:83]
	v_mfma_f32_16x16x32_bf16 v[68:71], v[170:173], v[210:213], v[68:71]
	v_mfma_f32_16x16x32_bf16 v[64:67], v[178:181], v[210:213], v[64:67]
	v_mfma_f32_16x16x32_bf16 v[108:111], v[174:177], v[190:193], v[108:111]
	v_mfma_f32_16x16x32_bf16 v[104:107], v[182:185], v[190:193], v[104:107]
	v_mfma_f32_16x16x32_bf16 v[100:103], v[174:177], v[198:201], v[100:103]
	v_mfma_f32_16x16x32_bf16 v[96:99], v[182:185], v[198:201], v[96:99]
	v_mfma_f32_16x16x32_bf16 v[84:87], v[174:177], v[206:209], v[84:87]
	v_mfma_f32_16x16x32_bf16 v[80:83], v[182:185], v[206:209], v[80:83]
	v_mfma_f32_16x16x32_bf16 v[68:71], v[174:177], v[214:217], v[68:71]
	v_mfma_f32_16x16x32_bf16 v[64:67], v[182:185], v[214:217], v[64:67]
	s_barrier
	s_add_i32 s46, s65, s17
	s_mov_b32 m0, s46
	s_add_u32 s98, s48, 0x80
	s_addc_u32 s99, s49, 0
	ds_read_b128 v[186:189], v163 offset:49152
	ds_read_b128 v[190:193], v163 offset:50176
	ds_read_b128 v[194:197], v163 offset:51200
	ds_read_b128 v[198:201], v163 offset:52224
	ds_read_b128 v[202:205], v163 offset:53248
	ds_read_b128 v[206:209], v163 offset:54272
	ds_read_b128 v[210:213], v163 offset:55296
	ds_read_b128 v[214:217], v163 offset:56320
	global_load_lds_dwordx4 v132, s[98:99]
	s_add_i32 m0, s46, 0x2000
	s_add_u32 s46, s48, 0x104080
	s_addc_u32 s47, s49, 0
	s_add_i32 s48, s66, s17
	global_load_lds_dwordx4 v128, s[98:99]
	s_mov_b32 m0, s48
	s_nop 0
	global_load_lds_dwordx4 v132, s[46:47]
	s_add_i32 m0, s48, 0x2000
	s_nop 0
	global_load_lds_dwordx4 v128, s[46:47]
	s_nop 0
	s_waitcnt vmcnt(4)
	s_waitcnt lgkmcnt(0)
	s_barrier
	s_waitcnt lgkmcnt(0)
	v_mfma_f32_16x16x32_bf16 v[60:63], v[144:147], v[186:189], v[60:63]
	v_mfma_f32_16x16x32_bf16 v[56:59], v[152:155], v[186:189], v[56:59]
	v_mfma_f32_16x16x32_bf16 v[44:47], v[144:147], v[194:197], v[44:47]
	v_mfma_f32_16x16x32_bf16 v[40:43], v[152:155], v[194:197], v[40:43]
	v_mfma_f32_16x16x32_bf16 v[28:31], v[144:147], v[202:205], v[28:31]
	v_mfma_f32_16x16x32_bf16 v[24:27], v[152:155], v[202:205], v[24:27]
	v_mfma_f32_16x16x32_bf16 v[12:15], v[144:147], v[210:213], v[12:15]
	v_mfma_f32_16x16x32_bf16 v[8:11], v[152:155], v[210:213], v[8:11]
	v_mfma_f32_16x16x32_bf16 v[60:63], v[148:151], v[190:193], v[60:63]
	v_mfma_f32_16x16x32_bf16 v[56:59], v[166:169], v[190:193], v[56:59]
	v_mfma_f32_16x16x32_bf16 v[44:47], v[148:151], v[198:201], v[44:47]
	v_mfma_f32_16x16x32_bf16 v[40:43], v[166:169], v[198:201], v[40:43]
	v_mfma_f32_16x16x32_bf16 v[28:31], v[148:151], v[206:209], v[28:31]
	v_mfma_f32_16x16x32_bf16 v[24:27], v[166:169], v[206:209], v[24:27]
	v_mfma_f32_16x16x32_bf16 v[12:15], v[148:151], v[214:217], v[12:15]
	v_mfma_f32_16x16x32_bf16 v[8:11], v[166:169], v[214:217], v[8:11]
	v_mfma_f32_16x16x32_bf16 v[52:55], v[170:173], v[186:189], v[52:55]
	v_mfma_f32_16x16x32_bf16 v[48:51], v[178:181], v[186:189], v[48:51]
	v_mfma_f32_16x16x32_bf16 v[36:39], v[170:173], v[194:197], v[36:39]
	v_mfma_f32_16x16x32_bf16 v[32:35], v[178:181], v[194:197], v[32:35]
	v_mfma_f32_16x16x32_bf16 v[20:23], v[170:173], v[202:205], v[20:23]
	v_mfma_f32_16x16x32_bf16 v[16:19], v[178:181], v[202:205], v[16:19]
	v_mfma_f32_16x16x32_bf16 v[4:7], v[170:173], v[210:213], v[4:7]
	v_mfma_f32_16x16x32_bf16 v[0:3], v[178:181], v[210:213], v[0:3]
	v_mfma_f32_16x16x32_bf16 v[52:55], v[174:177], v[190:193], v[52:55]
	v_mfma_f32_16x16x32_bf16 v[48:51], v[182:185], v[190:193], v[48:51]
	v_mfma_f32_16x16x32_bf16 v[36:39], v[174:177], v[198:201], v[36:39]
	v_mfma_f32_16x16x32_bf16 v[32:35], v[182:185], v[198:201], v[32:35]
	v_mfma_f32_16x16x32_bf16 v[20:23], v[174:177], v[206:209], v[20:23]
	v_mfma_f32_16x16x32_bf16 v[16:19], v[182:185], v[206:209], v[16:19]
	v_mfma_f32_16x16x32_bf16 v[4:7], v[174:177], v[214:217], v[4:7]
	v_mfma_f32_16x16x32_bf16 v[0:3], v[182:185], v[214:217], v[0:3]
	s_barrier
	s_add_i32 s64, s64, 2
	s_add_u32 s62, s62, 0x100
	s_addc_u32 s63, s63, 0
	s_cmp_gt_u32 s64, 61
	s_mov_b64 s[46:47], s[4:5]
	s_cbranch_scc0 .LBB0_426
	s_and_b64 vcc, exec, s[40:41]
	s_cbranch_vccz .LBB0_429
	s_barrier

; #define PG8_STAGE(bufoff, gbase, voff) do { _Pragma("unroll") for (int _i = 0; _i < 2; ++_i) \
;         __builtin_amdgcn_global_load_lds((const unsigned*)((const char*)(gbase) + (voff)[_i]), (PG8_LAS unsigned*)(lds + (bufoff) + ldsw + _i * 8192), 16, 0, 0); } while (0)
; #define PG8_STAGE_NT(bufoff, gbase, voff) do { _Pragma("unroll") for (int _i = 0; _i < 2; ++_i) \
;         __builtin_amdgcn_global_load_lds((const unsigned*)((const char*)(gbase) + (voff)[_i]), (PG8_LAS unsigned*)(lds + (bufoff) + ldsw + _i * 8192), 16, 0, PG8_B_AUX); } while (0)
; #define PG8_LDA(dst, b, h) do { _Pragma("unroll") for (int m = 0; m < 4; ++m) _Pragma("unroll") for (int k = 0; k < 2; ++k) dst[m][k] = *(const PG8_LAS bf16x8*)(lds + PG8_SA(b, h) + aoff + m * 2048 + k * 1024); } while (0)
; #define PG8_LDB(dst, b, h) do { _Pragma("unroll") for (int n = 0; n < 2; ++n) _Pragma("unroll") for (int k = 0; k < 2; ++k) dst[n][k] = *(const PG8_LAS bf16x8*)(lds + PG8_SB(b, h) + boff + n * 2048 + k * 1024); } while (0)
; #define PG8_WAIT_V(n) asm volatile("s_waitcnt vmcnt(" #n ")" ::: "memory")
; #define PG8_WAIT_L(n) asm volatile("s_waitcnt lgkmcnt(" #n ")" ::: "memory")
; #define PG8_BAR __builtin_amdgcn_s_barrier()
; #define PG8_SCHED __builtin_amdgcn_sched_barrier(0)
; template <class Epi, class Sched, bool ALIGN_EPI = false, bool SP2 = false>
; __device__ __forceinline__ void gemm_phase(PG8_LAS unsigned char* lds, const Gemm g, const Sched& S, const Epi& E, int wid) {
;     ...
;             const bool last = (t == nt - 2);
;             const char* a1 = cA + (size_t)(t + 1) * kstep;
;             const char* a2 = last ? nA : cA + (size_t)(t + 2) * kstep; const char* b2 = last ? nB : cB + (size_t)(t + 2) * kstep;
;             const char* a3 = a2 + kstep; const char* b3 = b2 + kstep;
;             if (last && has_next) S.a_ready(nxt);
;             if constexpr (SP2) {
;             PG8_LDB(B0, 0, 0); PG8_LDB(B1, 0, 1); PG8_SCHED; PG8_LDA(At, 0, 0); PG8_STAGE(PG8_SA(1, 1), a1 + hstepA, voffA);
;             PG8_WAIT_V(8); PG8_WAIT_L(0); PG8_BAR; PG8_MMA(0, 0, At, B0); PG8_MMA(0, 1, At, B1); PG8_BAR; PG8_SCHED;
;             PG8_LDA(At, 0, 1); PG8_STAGE_NT(PG8_SB(0, 0), b2, voffB); PG8_STAGE_NT(PG8_SB(0, 1), b2 + hstepB, voffB); PG8_STAGE(PG8_SA(0, 0), a2, voffA);
;             PG8_WAIT_V(8); PG8_WAIT_L(0); PG8_BAR; PG8_MMA(1, 0, At, B0); PG8_MMA(1, 1, At, B1); PG8_BAR; PG8_SCHED;
.LBB0_1037:
	ds_read_b128 v[104:107], v221
	ds_read_b128 v[116:119], v221 offset:1024
	ds_read_b128 v[128:131], v221 offset:2048
	ds_read_b128 v[140:143], v221 offset:3072
	ds_read_b128 v[144:147], v222
	ds_read_b128 v[148:151], v222 offset:1024
	ds_read_b128 v[152:155], v222 offset:2048
	ds_read_b128 v[156:159], v222 offset:3072
	s_add_u32 s52, s50, 0x100
	s_addc_u32 s53, s51, 0
	s_add_u32 s98, s50, 0x80
	s_addc_u32 s99, s51, 0
	s_add_u32 s100, s50, 0x104080
	s_addc_u32 s101, s51, 0
	s_cmp_eq_u32 s67, 60
	s_cselect_b32 s57, s7, s53
	s_cselect_b32 s56, s6, s52
	s_cselect_b32 s55, s49, s66
	s_cselect_b32 s54, s48, s65
	s_add_i32 m0, s17, 0xc000
	ds_read_b128 v[160:163], v223
	ds_read_b128 v[164:167], v223 offset:1024
	ds_read_b128 v[168:171], v223 offset:2048
	ds_read_b128 v[172:175], v223 offset:3072
	ds_read_b128 v[176:179], v223 offset:4096
	ds_read_b128 v[180:183], v223 offset:5120
	ds_read_b128 v[200:203], v223 offset:6144
	ds_read_b128 v[204:207], v223 offset:7168
	global_load_lds_dwordx4 v184, s[100:101]
	s_add_i32 m0, s17, 0xe000
	s_nop 0
	global_load_lds_dwordx4 v188, s[100:101]
	s_mov_b32 m0, s25
	s_nop 0
	global_load_lds_dwordx4 v184, s[98:99]
	s_mov_b32 m0, s29
	s_nop 0
	global_load_lds_dwordx4 v188, s[98:99]
	s_waitcnt vmcnt(8)
	s_waitcnt lgkmcnt(0)
	s_barrier
	s_waitcnt lgkmcnt(0)
	v_mfma_f32_16x16x32_bf16 v[136:139], v[104:107], v[160:163], v[136:139]
	v_mfma_f32_16x16x32_bf16 v[132:135], v[128:131], v[160:163], v[132:135]
	v_mfma_f32_16x16x32_bf16 v[112:115], v[104:107], v[168:171], v[112:115]
	v_mfma_f32_16x16x32_bf16 v[108:111], v[128:131], v[168:171], v[108:111]
	v_mfma_f32_16x16x32_bf16 v[92:95], v[104:107], v[176:179], v[92:95]
	v_mfma_f32_16x16x32_bf16 v[88:91], v[128:131], v[176:179], v[88:91]
	v_mfma_f32_16x16x32_bf16 v[76:79], v[104:107], v[200:203], v[76:79]
	v_mfma_f32_16x16x32_bf16 v[72:75], v[128:131], v[200:203], v[72:75]
	v_mfma_f32_16x16x32_bf16 v[136:139], v[116:119], v[164:167], v[136:139]
	v_mfma_f32_16x16x32_bf16 v[132:135], v[140:143], v[164:167], v[132:135]
	v_mfma_f32_16x16x32_bf16 v[112:115], v[116:119], v[172:175], v[112:115]
	v_mfma_f32_16x16x32_bf16 v[108:111], v[140:143], v[172:175], v[108:111]
	v_mfma_f32_16x16x32_bf16 v[92:95], v[116:119], v[180:183], v[92:95]
	v_mfma_f32_16x16x32_bf16 v[88:91], v[140:143], v[180:183], v[88:91]
	v_mfma_f32_16x16x32_bf16 v[76:79], v[116:119], v[204:207], v[76:79]
	v_mfma_f32_16x16x32_bf16 v[72:75], v[140:143], v[204:207], v[72:75]
	v_mfma_f32_16x16x32_bf16 v[124:127], v[144:147], v[160:163], v[124:127]
	v_mfma_f32_16x16x32_bf16 v[120:123], v[152:155], v[160:163], v[120:123]
	v_mfma_f32_16x16x32_bf16 v[100:103], v[144:147], v[168:171], v[100:103]
	v_mfma_f32_16x16x32_bf16 v[96:99], v[152:155], v[168:171], v[96:99]
	v_mfma_f32_16x16x32_bf16 v[84:87], v[144:147], v[176:179], v[84:87]
	v_mfma_f32_16x16x32_bf16 v[80:83], v[152:155], v[176:179], v[80:83]
	v_mfma_f32_16x16x32_bf16 v[68:71], v[144:147], v[200:203], v[68:71]
	v_mfma_f32_16x16x32_bf16 v[64:67], v[152:155], v[200:203], v[64:67]
	v_mfma_f32_16x16x32_bf16 v[124:127], v[148:151], v[164:167], v[124:127]
	v_mfma_f32_16x16x32_bf16 v[120:123], v[156:159], v[164:167], v[120:123]
	v_mfma_f32_16x16x32_bf16 v[100:103], v[148:151], v[172:175], v[100:103]
	v_mfma_f32_16x16x32_bf16 v[96:99], v[156:159], v[172:175], v[96:99]
	v_mfma_f32_16x16x32_bf16 v[84:87], v[148:151], v[180:183], v[84:87]
	v_mfma_f32_16x16x32_bf16 v[80:83], v[156:159], v[180:183], v[80:83]
	v_mfma_f32_16x16x32_bf16 v[68:71], v[148:151], v[204:207], v[68:71]
	v_mfma_f32_16x16x32_bf16 v[64:67], v[156:159], v[204:207], v[64:67]
	s_barrier
	s_add_i32 s50, s60, s9
	s_mov_b32 m0, s50
	ds_read_b128 v[160:163], v223 offset:16384
	ds_read_b128 v[164:167], v223 offset:17408
	ds_read_b128 v[168:171], v223 offset:18432
	ds_read_b128 v[172:175], v223 offset:19456
	ds_read_b128 v[176:179], v223 offset:20480
	ds_read_b128 v[180:183], v223 offset:21504
	ds_read_b128 v[200:203], v223 offset:22528
	ds_read_b128 v[204:207], v223 offset:23552
	global_load_lds_dwordx4 v186, s[54:55]
	s_add_i32 m0, s50, 0x2000
	s_add_u32 s50, s54, 0x104000
	s_addc_u32 s51, s55, 0
	s_add_i32 s68, s61, s9
	global_load_lds_dwordx4 v190, s[54:55]
	s_mov_b32 m0, s68
	s_nop 0
	global_load_lds_dwordx4 v186, s[50:51]
	s_add_i32 m0, s68, 0x2000
	s_nop 0
	global_load_lds_dwordx4 v190, s[50:51]
	s_waitcnt vmcnt(4)
	s_waitcnt lgkmcnt(0)
	s_barrier
	s_waitcnt lgkmcnt(0)
	v_mfma_f32_16x16x32_bf16 v[60:63], v[104:107], v[160:163], v[60:63]
	v_mfma_f32_16x16x32_bf16 v[56:59], v[128:131], v[160:163], v[56:59]
	v_mfma_f32_16x16x32_bf16 v[44:47], v[104:107], v[168:171], v[44:47]
	v_mfma_f32_16x16x32_bf16 v[40:43], v[128:131], v[168:171], v[40:43]
	v_mfma_f32_16x16x32_bf16 v[28:31], v[104:107], v[176:179], v[28:31]
	v_mfma_f32_16x16x32_bf16 v[24:27], v[128:131], v[176:179], v[24:27]
	v_mfma_f32_16x16x32_bf16 v[12:15], v[104:107], v[200:203], v[12:15]
	v_mfma_f32_16x16x32_bf16 v[8:11], v[128:131], v[200:203], v[8:11]
	v_mfma_f32_16x16x32_bf16 v[60:63], v[116:119], v[164:167], v[60:63]
	v_mfma_f32_16x16x32_bf16 v[56:59], v[140:143], v[164:167], v[56:59]
	v_mfma_f32_16x16x32_bf16 v[44:47], v[116:119], v[172:175], v[44:47]
	v_mfma_f32_16x16x32_bf16 v[40:43], v[140:143], v[172:175], v[40:43]
	v_mfma_f32_16x16x32_bf16 v[28:31], v[116:119], v[180:183], v[28:31]
	v_mfma_f32_16x16x32_bf16 v[24:27], v[140:143], v[180:183], v[24:27]
	v_mfma_f32_16x16x32_bf16 v[12:15], v[116:119], v[204:207], v[12:15]
	v_mfma_f32_16x16x32_bf16 v[8:11], v[140:143], v[204:207], v[8:11]
	v_mfma_f32_16x16x32_bf16 v[52:55], v[144:147], v[160:163], v[52:55]
	v_mfma_f32_16x16x32_bf16 v[48:51], v[152:155], v[160:163], v[48:51]
	v_mfma_f32_16x16x32_bf16 v[36:39], v[144:147], v[168:171], v[36:39]
	v_mfma_f32_16x16x32_bf16 v[32:35], v[152:155], v[168:171], v[32:35]
	v_mfma_f32_16x16x32_bf16 v[20:23], v[144:147], v[176:179], v[20:23]
	v_mfma_f32_16x16x32_bf16 v[16:19], v[152:155], v[176:179], v[16:19]
	v_mfma_f32_16x16x32_bf16 v[4:7], v[144:147], v[200:203], v[4:7]
	v_mfma_f32_16x16x32_bf16 v[0:3], v[152:155], v[200:203], v[0:3]
	v_mfma_f32_16x16x32_bf16 v[52:55], v[148:151], v[164:167], v[52:55]
	v_mfma_f32_16x16x32_bf16 v[48:51], v[156:159], v[164:167], v[48:51]
	v_mfma_f32_16x16x32_bf16 v[36:39], v[148:151], v[172:175], v[36:39]
	v_mfma_f32_16x16x32_bf16 v[32:35], v[156:159], v[172:175], v[32:35]
	v_mfma_f32_16x16x32_bf16 v[20:23], v[148:151], v[180:183], v[20:23]
	v_mfma_f32_16x16x32_bf16 v[16:19], v[156:159], v[180:183], v[16:19]
	v_mfma_f32_16x16x32_bf16 v[4:7], v[148:151], v[204:207], v[4:7]
	v_mfma_f32_16x16x32_bf16 v[0:3], v[156:159], v[204:207], v[0:3]
	s_barrier
; #define PG8_STAGE(bufoff, gbase, voff) do { _Pragma("unroll") for (int _i = 0; _i < 2; ++_i) \
;         __builtin_amdgcn_global_load_lds((const unsigned*)((const char*)(gbase) + (voff)[_i]), (PG8_LAS unsigned*)(lds + (bufoff) + ldsw + _i * 8192), 16, 0, 0); } while (0)
; #define PG8_STAGE_NT(bufoff, gbase, voff) do { _Pragma("unroll") for (int _i = 0; _i < 2; ++_i) \
;         __builtin_amdgcn_global_load_lds((const unsigned*)((const char*)(gbase) + (voff)[_i]), (PG8_LAS unsigned*)(lds + (bufoff) + ldsw + _i * 8192), 16, 0, PG8_B_AUX); } while (0)
; #define PG8_LDA(dst, b, h) do { _Pragma("unroll") for (int m = 0; m < 4; ++m) _Pragma("unroll") for (int k = 0; k < 2; ++k) dst[m][k] = *(const PG8_LAS bf16x8*)(lds + PG8_SA(b, h) + aoff + m * 2048 + k * 1024); } while (0)
; #define PG8_LDB(dst, b, h) do { _Pragma("unroll") for (int n = 0; n < 2; ++n) _Pragma("unroll") for (int k = 0; k < 2; ++k) dst[n][k] = *(const PG8_LAS bf16x8*)(lds + PG8_SB(b, h) + boff + n * 2048 + k * 1024); } while (0)
; #define PG8_MMA(ai, bj, At, Bt) do { __builtin_amdgcn_s_setprio(1); _Pragma("unroll") for (int m = 0; m < 4; ++m) _Pragma("unroll") for (int n = 0; n < 2; ++n) _Pragma("unroll") for (int k = 0; k < 2; ++k) \
;         acc[ai][bj][m][n] = __builtin_amdgcn_mfma_f32_16x16x32_bf16(Bt[n][k], At[m][k], acc[ai][bj][m][n], 0, 0, 0); __builtin_amdgcn_s_setprio(0); } while (0)
; #define PG8_WAIT_V(n) asm volatile("s_waitcnt vmcnt(" #n ")" ::: "memory")
; #define PG8_WAIT_L(n) asm volatile("s_waitcnt lgkmcnt(" #n ")" ::: "memory")
; #define PG8_BAR __builtin_amdgcn_s_barrier()
; template <class Epi, class Sched, bool ALIGN_EPI = false, bool SP2 = false>
; __device__ __forceinline__ void gemm_phase(PG8_LAS unsigned char* lds, const Gemm g, const Sched& S, const Epi& E, int wid) {
;     ...
;             PG8_LDB(B0, 1, 0); PG8_LDB(B1, 1, 1); PG8_SCHED; PG8_LDA(At, 1, 0); PG8_STAGE(PG8_SA(0, 1), a2 + hstepA, voffA);
;             PG8_WAIT_V(8); PG8_WAIT_L(0); PG8_BAR; PG8_MMA(0, 0, At, B0); PG8_MMA(0, 1, At, B1); PG8_BAR; PG8_SCHED;
;             PG8_LDA(At, 1, 1); PG8_STAGE_NT(PG8_SB(1, 0), b3, voffB); PG8_STAGE_NT(PG8_SB(1, 1), b3 + hstepB, voffB); PG8_STAGE(PG8_SA(1, 0), a3, voffA);
;             PG8_WAIT_V(8); PG8_WAIT_L(0); PG8_BAR; PG8_MMA(1, 0, At, B0); PG8_MMA(1, 1, At, B1); PG8_BAR; PG8_SCHED;
;     ...
;         if constexpr (ALIGN_EPI) { if (wr == 0) PG8_BAR; }
	s_add_i32 s68, 0, 0x18000
	v_add_u32_e32 v140, s68, v219
	s_add_i32 s69, 0, 0x1c000
	ds_read_b128 v[104:107], v140
	ds_read_b128 v[116:119], v140 offset:1024
	ds_read_b128 v[128:131], v140 offset:2048
	ds_read_b128 v[140:143], v140 offset:3072
	v_add_u32_e32 v156, s69, v219
	ds_read_b128 v[144:147], v156
	ds_read_b128 v[148:151], v156 offset:1024
	ds_read_b128 v[152:155], v156 offset:2048
	ds_read_b128 v[156:159], v156 offset:3072
	s_add_u32 s50, s56, 0x104000
	s_addc_u32 s51, s57, 0
	s_mov_b32 m0, s22
	ds_read_b128 v[160:163], v223 offset:32768
	ds_read_b128 v[164:167], v223 offset:33792
	ds_read_b128 v[168:171], v223 offset:34816
	ds_read_b128 v[172:175], v223 offset:35840
	ds_read_b128 v[176:179], v223 offset:36864
	ds_read_b128 v[180:183], v223 offset:37888
	ds_read_b128 v[200:203], v223 offset:38912
	ds_read_b128 v[204:207], v223 offset:39936
	global_load_lds_dwordx4 v184, s[50:51]
	s_mov_b32 m0, s23
	s_nop 0
	global_load_lds_dwordx4 v188, s[50:51]
	s_mov_b32 m0, s17
	s_nop 0
	global_load_lds_dwordx4 v184, s[56:57]
	s_mov_b32 m0, s19
	s_nop 0
	global_load_lds_dwordx4 v188, s[56:57]
	s_nop 0
	s_waitcnt vmcnt(8)
	s_waitcnt lgkmcnt(0)
	s_barrier
	s_waitcnt lgkmcnt(0)
	v_mfma_f32_16x16x32_bf16 v[136:139], v[104:107], v[160:163], v[136:139]
	v_mfma_f32_16x16x32_bf16 v[132:135], v[128:131], v[160:163], v[132:135]
	v_mfma_f32_16x16x32_bf16 v[112:115], v[104:107], v[168:171], v[112:115]
	v_mfma_f32_16x16x32_bf16 v[108:111], v[128:131], v[168:171], v[108:111]
	v_mfma_f32_16x16x32_bf16 v[92:95], v[104:107], v[176:179], v[92:95]
	v_mfma_f32_16x16x32_bf16 v[88:91], v[128:131], v[176:179], v[88:91]
	v_mfma_f32_16x16x32_bf16 v[76:79], v[104:107], v[200:203], v[76:79]
	v_mfma_f32_16x16x32_bf16 v[72:75], v[128:131], v[200:203], v[72:75]
	v_mfma_f32_16x16x32_bf16 v[136:139], v[116:119], v[164:167], v[136:139]
	v_mfma_f32_16x16x32_bf16 v[132:135], v[140:143], v[164:167], v[132:135]
	v_mfma_f32_16x16x32_bf16 v[112:115], v[116:119], v[172:175], v[112:115]
	v_mfma_f32_16x16x32_bf16 v[108:111], v[140:143], v[172:175], v[108:111]
	v_mfma_f32_16x16x32_bf16 v[92:95], v[116:119], v[180:183], v[92:95]
	v_mfma_f32_16x16x32_bf16 v[88:91], v[140:143], v[180:183], v[88:91]
	v_mfma_f32_16x16x32_bf16 v[76:79], v[116:119], v[204:207], v[76:79]
	v_mfma_f32_16x16x32_bf16 v[72:75], v[140:143], v[204:207], v[72:75]
	v_mfma_f32_16x16x32_bf16 v[124:127], v[144:147], v[160:163], v[124:127]
	v_mfma_f32_16x16x32_bf16 v[120:123], v[152:155], v[160:163], v[120:123]
	v_mfma_f32_16x16x32_bf16 v[100:103], v[144:147], v[168:171], v[100:103]
	v_mfma_f32_16x16x32_bf16 v[96:99], v[152:155], v[168:171], v[96:99]
	v_mfma_f32_16x16x32_bf16 v[84:87], v[144:147], v[176:179], v[84:87]
	v_mfma_f32_16x16x32_bf16 v[80:83], v[152:155], v[176:179], v[80:83]
	v_mfma_f32_16x16x32_bf16 v[68:71], v[144:147], v[200:203], v[68:71]
	v_mfma_f32_16x16x32_bf16 v[64:67], v[152:155], v[200:203], v[64:67]
	v_mfma_f32_16x16x32_bf16 v[124:127], v[148:151], v[164:167], v[124:127]
	v_mfma_f32_16x16x32_bf16 v[120:123], v[156:159], v[164:167], v[120:123]
	v_mfma_f32_16x16x32_bf16 v[100:103], v[148:151], v[172:175], v[100:103]
	v_mfma_f32_16x16x32_bf16 v[96:99], v[156:159], v[172:175], v[96:99]
	v_mfma_f32_16x16x32_bf16 v[84:87], v[148:151], v[180:183], v[84:87]
	v_mfma_f32_16x16x32_bf16 v[80:83], v[156:159], v[180:183], v[80:83]
	v_mfma_f32_16x16x32_bf16 v[68:71], v[148:151], v[204:207], v[68:71]
	v_mfma_f32_16x16x32_bf16 v[64:67], v[156:159], v[204:207], v[64:67]
	s_barrier
	s_add_i32 s50, s68, s9
	s_mov_b32 m0, s50
	s_add_u32 s98, s54, 0x80
	s_addc_u32 s99, s55, 0
	ds_read_b128 v[160:163], v223 offset:49152
	ds_read_b128 v[164:167], v223 offset:50176
	ds_read_b128 v[168:171], v223 offset:51200
	ds_read_b128 v[172:175], v223 offset:52224
	ds_read_b128 v[176:179], v223 offset:53248
	ds_read_b128 v[180:183], v223 offset:54272
	ds_read_b128 v[200:203], v223 offset:55296
	ds_read_b128 v[204:207], v223 offset:56320
	global_load_lds_dwordx4 v186, s[98:99]
	s_add_i32 m0, s50, 0x2000
	s_add_u32 s50, s54, 0x104080
	s_addc_u32 s51, s55, 0
	s_add_i32 s54, s69, s9
	global_load_lds_dwordx4 v190, s[98:99]
	s_mov_b32 m0, s54
	s_nop 0
	global_load_lds_dwordx4 v186, s[50:51]
	s_add_i32 m0, s54, 0x2000
	s_nop 0
	global_load_lds_dwordx4 v190, s[50:51]
	s_nop 0
	s_waitcnt vmcnt(4)
	s_waitcnt lgkmcnt(0)
	s_barrier
	s_waitcnt lgkmcnt(0)
	v_mfma_f32_16x16x32_bf16 v[60:63], v[104:107], v[160:163], v[60:63]
	v_mfma_f32_16x16x32_bf16 v[56:59], v[128:131], v[160:163], v[56:59]
	v_mfma_f32_16x16x32_bf16 v[44:47], v[104:107], v[168:171], v[44:47]
	v_mfma_f32_16x16x32_bf16 v[40:43], v[128:131], v[168:171], v[40:43]
	v_mfma_f32_16x16x32_bf16 v[28:31], v[104:107], v[176:179], v[28:31]
	v_mfma_f32_16x16x32_bf16 v[24:27], v[128:131], v[176:179], v[24:27]
	v_mfma_f32_16x16x32_bf16 v[12:15], v[104:107], v[200:203], v[12:15]
	v_mfma_f32_16x16x32_bf16 v[8:11], v[128:131], v[200:203], v[8:11]
	v_mfma_f32_16x16x32_bf16 v[60:63], v[116:119], v[164:167], v[60:63]
	v_mfma_f32_16x16x32_bf16 v[56:59], v[140:143], v[164:167], v[56:59]
	v_mfma_f32_16x16x32_bf16 v[44:47], v[116:119], v[172:175], v[44:47]
	v_mfma_f32_16x16x32_bf16 v[40:43], v[140:143], v[172:175], v[40:43]
	v_mfma_f32_16x16x32_bf16 v[28:31], v[116:119], v[180:183], v[28:31]
	v_mfma_f32_16x16x32_bf16 v[24:27], v[140:143], v[180:183], v[24:27]
	v_mfma_f32_16x16x32_bf16 v[12:15], v[116:119], v[204:207], v[12:15]
	v_mfma_f32_16x16x32_bf16 v[8:11], v[140:143], v[204:207], v[8:11]
	v_mfma_f32_16x16x32_bf16 v[52:55], v[144:147], v[160:163], v[52:55]
	v_mfma_f32_16x16x32_bf16 v[48:51], v[152:155], v[160:163], v[48:51]
	v_mfma_f32_16x16x32_bf16 v[36:39], v[144:147], v[168:171], v[36:39]
	v_mfma_f32_16x16x32_bf16 v[32:35], v[152:155], v[168:171], v[32:35]
	v_mfma_f32_16x16x32_bf16 v[20:23], v[144:147], v[176:179], v[20:23]
	v_mfma_f32_16x16x32_bf16 v[16:19], v[152:155], v[176:179], v[16:19]
	v_mfma_f32_16x16x32_bf16 v[4:7], v[144:147], v[200:203], v[4:7]
	v_mfma_f32_16x16x32_bf16 v[0:3], v[152:155], v[200:203], v[0:3]
	v_mfma_f32_16x16x32_bf16 v[52:55], v[148:151], v[164:167], v[52:55]
	v_mfma_f32_16x16x32_bf16 v[48:51], v[156:159], v[164:167], v[48:51]
	v_mfma_f32_16x16x32_bf16 v[36:39], v[148:151], v[172:175], v[36:39]
	v_mfma_f32_16x16x32_bf16 v[32:35], v[156:159], v[172:175], v[32:35]
	v_mfma_f32_16x16x32_bf16 v[20:23], v[148:151], v[180:183], v[20:23]
	v_mfma_f32_16x16x32_bf16 v[16:19], v[156:159], v[180:183], v[16:19]
	v_mfma_f32_16x16x32_bf16 v[4:7], v[148:151], v[204:207], v[4:7]
	v_mfma_f32_16x16x32_bf16 v[0:3], v[156:159], v[204:207], v[0:3]
	s_barrier
	s_add_i32 s67, s67, 2
	s_add_u32 s65, s65, 0x100
	s_addc_u32 s66, s66, 0
	s_cmp_gt_u32 s67, 61
	s_mov_b64 s[50:51], s[52:53]
	s_cbranch_scc0 .LBB0_1037
	s_and_b64 vcc, exec, s[46:47]
	s_cbranch_vccz .LBB0_1040
	s_barrier

; #define PG8_STAGE(bufoff, gbase, voff) do { _Pragma("unroll") for (int _i = 0; _i < 2; ++_i) \
;         __builtin_amdgcn_global_load_lds((const unsigned*)((const char*)(gbase) + (voff)[_i]), (PG8_LAS unsigned*)(lds + (bufoff) + ldsw + _i * 8192), 16, 0, 0); } while (0)
; #define PG8_STAGE_NT(bufoff, gbase, voff) do { _Pragma("unroll") for (int _i = 0; _i < 2; ++_i) \
;         __builtin_amdgcn_global_load_lds((const unsigned*)((const char*)(gbase) + (voff)[_i]), (PG8_LAS unsigned*)(lds + (bufoff) + ldsw + _i * 8192), 16, 0, PG8_B_AUX); } while (0)
; #define PG8_LDA(dst, b, h) do { _Pragma("unroll") for (int m = 0; m < 4; ++m) _Pragma("unroll") for (int k = 0; k < 2; ++k) dst[m][k] = *(const PG8_LAS bf16x8*)(lds + PG8_SA(b, h) + aoff + m * 2048 + k * 1024); } while (0)
; #define PG8_LDB(dst, b, h) do { _Pragma("unroll") for (int n = 0; n < 2; ++n) _Pragma("unroll") for (int k = 0; k < 2; ++k) dst[n][k] = *(const PG8_LAS bf16x8*)(lds + PG8_SB(b, h) + boff + n * 2048 + k * 1024); } while (0)
; #define PG8_WAIT_V(n) asm volatile("s_waitcnt vmcnt(" #n ")" ::: "memory")
; #define PG8_WAIT_L(n) asm volatile("s_waitcnt lgkmcnt(" #n ")" ::: "memory")
; #define PG8_BAR __builtin_amdgcn_s_barrier()
; #define PG8_SCHED __builtin_amdgcn_sched_barrier(0)
; template <class Epi, class Sched, bool ALIGN_EPI = false, bool SP2 = false>
; __device__ __forceinline__ void gemm_phase(PG8_LAS unsigned char* lds, const Gemm g, const Sched& S, const Epi& E, int wid) {
;     ...
;             const bool last = (t == nt - 2);
;             const char* a1 = cA + (size_t)(t + 1) * kstep;
;             const char* a2 = last ? nA : cA + (size_t)(t + 2) * kstep; const char* b2 = last ? nB : cB + (size_t)(t + 2) * kstep;
;             const char* a3 = a2 + kstep; const char* b3 = b2 + kstep;
;             if (last && has_next) S.a_ready(nxt);
;             if constexpr (SP2) {
;             PG8_LDB(B0, 0, 0); PG8_LDB(B1, 0, 1); PG8_SCHED; PG8_LDA(At, 0, 0); PG8_STAGE(PG8_SA(1, 1), a1 + hstepA, voffA);
;             PG8_WAIT_V(8); PG8_WAIT_L(0); PG8_BAR; PG8_MMA(0, 0, At, B0); PG8_MMA(0, 1, At, B1); PG8_BAR; PG8_SCHED;
;             PG8_LDA(At, 0, 1); PG8_STAGE_NT(PG8_SB(0, 0), b2, voffB); PG8_STAGE_NT(PG8_SB(0, 1), b2 + hstepB, voffB); PG8_STAGE(PG8_SA(0, 0), a2, voffA);
;             PG8_WAIT_V(8); PG8_WAIT_L(0); PG8_BAR; PG8_MMA(1, 0, At, B0); PG8_MMA(1, 1, At, B1); PG8_BAR; PG8_SCHED;
.LBB0_1133:
	ds_read_b128 v[144:147], v155
	ds_read_b128 v[148:151], v155 offset:1024
	ds_read_b128 v[160:163], v155 offset:2048
	ds_read_b128 v[164:167], v155 offset:3072
	ds_read_b128 v[168:171], v156
	ds_read_b128 v[172:175], v156 offset:1024
	ds_read_b128 v[176:179], v156 offset:2048
	ds_read_b128 v[180:183], v156 offset:3072
	s_add_u32 s4, s46, 0x100
	s_addc_u32 s5, s47, 0
	s_add_u32 s98, s46, 0x80
	s_addc_u32 s99, s47, 0
	s_add_u32 s100, s46, 0x104080
	s_addc_u32 s101, s47, 0
	s_cmp_eq_u32 s63, 60
	s_cselect_b32 s51, s43, s5
	s_cselect_b32 s50, s42, s4
	s_cselect_b32 s49, s45, s62
	s_cselect_b32 s48, s44, s61
	s_add_i32 m0, s22, 0xc000
	ds_read_b128 v[184:187], v157
	ds_read_b128 v[188:191], v157 offset:1024
	ds_read_b128 v[192:195], v157 offset:2048
	ds_read_b128 v[196:199], v157 offset:3072
	ds_read_b128 v[200:203], v157 offset:4096
	ds_read_b128 v[204:207], v157 offset:5120
	ds_read_b128 v[208:211], v157 offset:6144
	ds_read_b128 v[212:215], v157 offset:7168
	global_load_lds_dwordx4 v134, s[100:101]
	s_add_i32 m0, s22, 0xe000
	s_nop 0
	global_load_lds_dwordx4 v130, s[100:101]
	s_mov_b32 m0, s52
	s_nop 0
	global_load_lds_dwordx4 v134, s[98:99]
	s_mov_b32 m0, s53
	s_nop 0
	global_load_lds_dwordx4 v130, s[98:99]
	s_waitcnt vmcnt(8)
	s_waitcnt lgkmcnt(0)
	s_barrier
	s_waitcnt lgkmcnt(0)
	v_mfma_f32_16x16x32_bf16 v[112:115], v[144:147], v[184:187], v[112:115]
	v_mfma_f32_16x16x32_bf16 v[108:111], v[160:163], v[184:187], v[108:111]
	v_mfma_f32_16x16x32_bf16 v[104:107], v[144:147], v[192:195], v[104:107]
	v_mfma_f32_16x16x32_bf16 v[100:103], v[160:163], v[192:195], v[100:103]
	v_mfma_f32_16x16x32_bf16 v[92:95], v[144:147], v[200:203], v[92:95]
	v_mfma_f32_16x16x32_bf16 v[84:87], v[160:163], v[200:203], v[84:87]
	v_mfma_f32_16x16x32_bf16 v[76:79], v[144:147], v[208:211], v[76:79]
	v_mfma_f32_16x16x32_bf16 v[68:71], v[160:163], v[208:211], v[68:71]
	v_mfma_f32_16x16x32_bf16 v[112:115], v[148:151], v[188:191], v[112:115]
	v_mfma_f32_16x16x32_bf16 v[108:111], v[164:167], v[188:191], v[108:111]
	v_mfma_f32_16x16x32_bf16 v[104:107], v[148:151], v[196:199], v[104:107]
	v_mfma_f32_16x16x32_bf16 v[100:103], v[164:167], v[196:199], v[100:103]
	v_mfma_f32_16x16x32_bf16 v[92:95], v[148:151], v[204:207], v[92:95]
	v_mfma_f32_16x16x32_bf16 v[84:87], v[164:167], v[204:207], v[84:87]
	v_mfma_f32_16x16x32_bf16 v[76:79], v[148:151], v[212:215], v[76:79]
	v_mfma_f32_16x16x32_bf16 v[68:71], v[164:167], v[212:215], v[68:71]
	v_mfma_f32_16x16x32_bf16 v[124:127], v[168:171], v[184:187], v[124:127]
	v_mfma_f32_16x16x32_bf16 v[120:123], v[176:179], v[184:187], v[120:123]
	v_mfma_f32_16x16x32_bf16 v[116:119], v[168:171], v[192:195], v[116:119]
	v_mfma_f32_16x16x32_bf16 v[96:99], v[176:179], v[192:195], v[96:99]
	v_mfma_f32_16x16x32_bf16 v[88:91], v[168:171], v[200:203], v[88:91]
	v_mfma_f32_16x16x32_bf16 v[80:83], v[176:179], v[200:203], v[80:83]
	v_mfma_f32_16x16x32_bf16 v[72:75], v[168:171], v[208:211], v[72:75]
	v_mfma_f32_16x16x32_bf16 v[64:67], v[176:179], v[208:211], v[64:67]
	v_mfma_f32_16x16x32_bf16 v[124:127], v[172:175], v[188:191], v[124:127]
	v_mfma_f32_16x16x32_bf16 v[120:123], v[180:183], v[188:191], v[120:123]
	v_mfma_f32_16x16x32_bf16 v[116:119], v[172:175], v[196:199], v[116:119]
	v_mfma_f32_16x16x32_bf16 v[96:99], v[180:183], v[196:199], v[96:99]
	v_mfma_f32_16x16x32_bf16 v[88:91], v[172:175], v[204:207], v[88:91]
	v_mfma_f32_16x16x32_bf16 v[80:83], v[180:183], v[204:207], v[80:83]
	v_mfma_f32_16x16x32_bf16 v[72:75], v[172:175], v[212:215], v[72:75]
	v_mfma_f32_16x16x32_bf16 v[64:67], v[180:183], v[212:215], v[64:67]
	s_barrier
	s_add_i32 s46, s55, s9
	s_mov_b32 m0, s46
	ds_read_b128 v[184:187], v157 offset:16384
	ds_read_b128 v[188:191], v157 offset:17408
	ds_read_b128 v[192:195], v157 offset:18432
	ds_read_b128 v[196:199], v157 offset:19456
	ds_read_b128 v[200:203], v157 offset:20480
	ds_read_b128 v[204:207], v157 offset:21504
	ds_read_b128 v[208:211], v157 offset:22528
	ds_read_b128 v[212:215], v157 offset:23552
	global_load_lds_dwordx4 v132, s[48:49]
	s_add_i32 m0, s46, 0x2000
	s_add_u32 s46, s48, 0x104000
	s_addc_u32 s47, s49, 0
	s_add_i32 s64, s56, s9
	global_load_lds_dwordx4 v128, s[48:49]
	s_mov_b32 m0, s64
	s_nop 0
	global_load_lds_dwordx4 v132, s[46:47]
	s_add_i32 m0, s64, 0x2000
	s_nop 0
	global_load_lds_dwordx4 v128, s[46:47]
	s_waitcnt vmcnt(4)
	s_waitcnt lgkmcnt(0)
	s_barrier
	s_waitcnt lgkmcnt(0)
	v_mfma_f32_16x16x32_bf16 v[60:63], v[144:147], v[184:187], v[60:63]
	v_mfma_f32_16x16x32_bf16 v[52:55], v[160:163], v[184:187], v[52:55]
	v_mfma_f32_16x16x32_bf16 v[44:47], v[144:147], v[192:195], v[44:47]
	v_mfma_f32_16x16x32_bf16 v[36:39], v[160:163], v[192:195], v[36:39]
	v_mfma_f32_16x16x32_bf16 v[28:31], v[144:147], v[200:203], v[28:31]
	v_mfma_f32_16x16x32_bf16 v[20:23], v[160:163], v[200:203], v[20:23]
	v_mfma_f32_16x16x32_bf16 v[12:15], v[144:147], v[208:211], v[12:15]
	v_mfma_f32_16x16x32_bf16 v[4:7], v[160:163], v[208:211], v[4:7]
	v_mfma_f32_16x16x32_bf16 v[60:63], v[148:151], v[188:191], v[60:63]
	v_mfma_f32_16x16x32_bf16 v[52:55], v[164:167], v[188:191], v[52:55]
	v_mfma_f32_16x16x32_bf16 v[44:47], v[148:151], v[196:199], v[44:47]
	v_mfma_f32_16x16x32_bf16 v[36:39], v[164:167], v[196:199], v[36:39]
	v_mfma_f32_16x16x32_bf16 v[28:31], v[148:151], v[204:207], v[28:31]
	v_mfma_f32_16x16x32_bf16 v[20:23], v[164:167], v[204:207], v[20:23]
	v_mfma_f32_16x16x32_bf16 v[12:15], v[148:151], v[212:215], v[12:15]
	v_mfma_f32_16x16x32_bf16 v[4:7], v[164:167], v[212:215], v[4:7]
	v_mfma_f32_16x16x32_bf16 v[56:59], v[168:171], v[184:187], v[56:59]
	v_mfma_f32_16x16x32_bf16 v[48:51], v[176:179], v[184:187], v[48:51]
	v_mfma_f32_16x16x32_bf16 v[40:43], v[168:171], v[192:195], v[40:43]
	v_mfma_f32_16x16x32_bf16 v[32:35], v[176:179], v[192:195], v[32:35]
	v_mfma_f32_16x16x32_bf16 v[24:27], v[168:171], v[200:203], v[24:27]
	v_mfma_f32_16x16x32_bf16 v[16:19], v[176:179], v[200:203], v[16:19]
	v_mfma_f32_16x16x32_bf16 v[8:11], v[168:171], v[208:211], v[8:11]
	v_mfma_f32_16x16x32_bf16 v[0:3], v[176:179], v[208:211], v[0:3]
	v_mfma_f32_16x16x32_bf16 v[56:59], v[172:175], v[188:191], v[56:59]
	v_mfma_f32_16x16x32_bf16 v[48:51], v[180:183], v[188:191], v[48:51]
	v_mfma_f32_16x16x32_bf16 v[40:43], v[172:175], v[196:199], v[40:43]
	v_mfma_f32_16x16x32_bf16 v[32:35], v[180:183], v[196:199], v[32:35]
	v_mfma_f32_16x16x32_bf16 v[24:27], v[172:175], v[204:207], v[24:27]
	v_mfma_f32_16x16x32_bf16 v[16:19], v[180:183], v[204:207], v[16:19]
	v_mfma_f32_16x16x32_bf16 v[8:11], v[172:175], v[212:215], v[8:11]
	v_mfma_f32_16x16x32_bf16 v[0:3], v[180:183], v[212:215], v[0:3]
	s_barrier
; #define PG8_STAGE(bufoff, gbase, voff) do { _Pragma("unroll") for (int _i = 0; _i < 2; ++_i) \
;         __builtin_amdgcn_global_load_lds((const unsigned*)((const char*)(gbase) + (voff)[_i]), (PG8_LAS unsigned*)(lds + (bufoff) + ldsw + _i * 8192), 16, 0, 0); } while (0)
; #define PG8_STAGE_NT(bufoff, gbase, voff) do { _Pragma("unroll") for (int _i = 0; _i < 2; ++_i) \
;         __builtin_amdgcn_global_load_lds((const unsigned*)((const char*)(gbase) + (voff)[_i]), (PG8_LAS unsigned*)(lds + (bufoff) + ldsw + _i * 8192), 16, 0, PG8_B_AUX); } while (0)
; #define PG8_LDA(dst, b, h) do { _Pragma("unroll") for (int m = 0; m < 4; ++m) _Pragma("unroll") for (int k = 0; k < 2; ++k) dst[m][k] = *(const PG8_LAS bf16x8*)(lds + PG8_SA(b, h) + aoff + m * 2048 + k * 1024); } while (0)
; #define PG8_LDB(dst, b, h) do { _Pragma("unroll") for (int n = 0; n < 2; ++n) _Pragma("unroll") for (int k = 0; k < 2; ++k) dst[n][k] = *(const PG8_LAS bf16x8*)(lds + PG8_SB(b, h) + boff + n * 2048 + k * 1024); } while (0)
; #define PG8_MMA(ai, bj, At, Bt) do { __builtin_amdgcn_s_setprio(1); _Pragma("unroll") for (int m = 0; m < 4; ++m) _Pragma("unroll") for (int n = 0; n < 2; ++n) _Pragma("unroll") for (int k = 0; k < 2; ++k) \
;         acc[ai][bj][m][n] = __builtin_amdgcn_mfma_f32_16x16x32_bf16(Bt[n][k], At[m][k], acc[ai][bj][m][n], 0, 0, 0); __builtin_amdgcn_s_setprio(0); } while (0)
; #define PG8_WAIT_V(n) asm volatile("s_waitcnt vmcnt(" #n ")" ::: "memory")
; #define PG8_WAIT_L(n) asm volatile("s_waitcnt lgkmcnt(" #n ")" ::: "memory")
; #define PG8_BAR __builtin_amdgcn_s_barrier()
; template <class Epi, class Sched, bool ALIGN_EPI = false, bool SP2 = false>
; __device__ __forceinline__ void gemm_phase(PG8_LAS unsigned char* lds, const Gemm g, const Sched& S, const Epi& E, int wid) {
;     ...
;             PG8_LDB(B0, 1, 0); PG8_LDB(B1, 1, 1); PG8_SCHED; PG8_LDA(At, 1, 0); PG8_STAGE(PG8_SA(0, 1), a2 + hstepA, voffA);
;             PG8_WAIT_V(8); PG8_WAIT_L(0); PG8_BAR; PG8_MMA(0, 0, At, B0); PG8_MMA(0, 1, At, B1); PG8_BAR; PG8_SCHED;
;             PG8_LDA(At, 1, 1); PG8_STAGE_NT(PG8_SB(1, 0), b3, voffB); PG8_STAGE_NT(PG8_SB(1, 1), b3 + hstepB, voffB); PG8_STAGE(PG8_SA(1, 0), a3, voffA);
;             PG8_WAIT_V(8); PG8_WAIT_L(0); PG8_BAR; PG8_MMA(1, 0, At, B0); PG8_MMA(1, 1, At, B1); PG8_BAR; PG8_SCHED;
;     ...
;         if constexpr (ALIGN_EPI) { if (wr == 0) PG8_BAR; }
	s_add_i32 s64, 0, 0x18000
	v_add_u32_e32 v159, s64, v153
	s_add_i32 s65, 0, 0x1c000
	ds_read_b128 v[144:147], v159
	ds_read_b128 v[148:151], v159 offset:1024
	ds_read_b128 v[160:163], v159 offset:2048
	ds_read_b128 v[164:167], v159 offset:3072
	v_add_u32_e32 v159, s65, v153
	ds_read_b128 v[168:171], v159
	ds_read_b128 v[172:175], v159 offset:1024
	ds_read_b128 v[176:179], v159 offset:2048
	ds_read_b128 v[180:183], v159 offset:3072
	s_add_u32 s46, s50, 0x104000
	s_addc_u32 s47, s51, 0
	s_mov_b32 m0, s24
	ds_read_b128 v[184:187], v157 offset:32768
	ds_read_b128 v[188:191], v157 offset:33792
	ds_read_b128 v[192:195], v157 offset:34816
	ds_read_b128 v[196:199], v157 offset:35840
	ds_read_b128 v[200:203], v157 offset:36864
	ds_read_b128 v[204:207], v157 offset:37888
	ds_read_b128 v[208:211], v157 offset:38912
	ds_read_b128 v[212:215], v157 offset:39936
	global_load_lds_dwordx4 v134, s[46:47]
	s_mov_b32 m0, s25
	s_nop 0
	global_load_lds_dwordx4 v130, s[46:47]
	s_mov_b32 m0, s22
	s_nop 0
	global_load_lds_dwordx4 v134, s[50:51]
	s_mov_b32 m0, s23
	s_nop 0
	global_load_lds_dwordx4 v130, s[50:51]
	s_nop 0
	s_waitcnt vmcnt(8)
	s_waitcnt lgkmcnt(0)
	s_barrier
	s_waitcnt lgkmcnt(0)
	v_mfma_f32_16x16x32_bf16 v[112:115], v[144:147], v[184:187], v[112:115]
	v_mfma_f32_16x16x32_bf16 v[108:111], v[160:163], v[184:187], v[108:111]
	v_mfma_f32_16x16x32_bf16 v[104:107], v[144:147], v[192:195], v[104:107]
	v_mfma_f32_16x16x32_bf16 v[100:103], v[160:163], v[192:195], v[100:103]
	v_mfma_f32_16x16x32_bf16 v[92:95], v[144:147], v[200:203], v[92:95]
	v_mfma_f32_16x16x32_bf16 v[84:87], v[160:163], v[200:203], v[84:87]
	v_mfma_f32_16x16x32_bf16 v[76:79], v[144:147], v[208:211], v[76:79]
	v_mfma_f32_16x16x32_bf16 v[68:71], v[160:163], v[208:211], v[68:71]
	v_mfma_f32_16x16x32_bf16 v[112:115], v[148:151], v[188:191], v[112:115]
	v_mfma_f32_16x16x32_bf16 v[108:111], v[164:167], v[188:191], v[108:111]
	v_mfma_f32_16x16x32_bf16 v[104:107], v[148:151], v[196:199], v[104:107]
	v_mfma_f32_16x16x32_bf16 v[100:103], v[164:167], v[196:199], v[100:103]
	v_mfma_f32_16x16x32_bf16 v[92:95], v[148:151], v[204:207], v[92:95]
	v_mfma_f32_16x16x32_bf16 v[84:87], v[164:167], v[204:207], v[84:87]
	v_mfma_f32_16x16x32_bf16 v[76:79], v[148:151], v[212:215], v[76:79]
	v_mfma_f32_16x16x32_bf16 v[68:71], v[164:167], v[212:215], v[68:71]
	v_mfma_f32_16x16x32_bf16 v[124:127], v[168:171], v[184:187], v[124:127]
	v_mfma_f32_16x16x32_bf16 v[120:123], v[176:179], v[184:187], v[120:123]
	v_mfma_f32_16x16x32_bf16 v[116:119], v[168:171], v[192:195], v[116:119]
	v_mfma_f32_16x16x32_bf16 v[96:99], v[176:179], v[192:195], v[96:99]
	v_mfma_f32_16x16x32_bf16 v[88:91], v[168:171], v[200:203], v[88:91]
	v_mfma_f32_16x16x32_bf16 v[80:83], v[176:179], v[200:203], v[80:83]
	v_mfma_f32_16x16x32_bf16 v[72:75], v[168:171], v[208:211], v[72:75]
	v_mfma_f32_16x16x32_bf16 v[64:67], v[176:179], v[208:211], v[64:67]
	v_mfma_f32_16x16x32_bf16 v[124:127], v[172:175], v[188:191], v[124:127]
	v_mfma_f32_16x16x32_bf16 v[120:123], v[180:183], v[188:191], v[120:123]
	v_mfma_f32_16x16x32_bf16 v[116:119], v[172:175], v[196:199], v[116:119]
	v_mfma_f32_16x16x32_bf16 v[96:99], v[180:183], v[196:199], v[96:99]
	v_mfma_f32_16x16x32_bf16 v[88:91], v[172:175], v[204:207], v[88:91]
	v_mfma_f32_16x16x32_bf16 v[80:83], v[180:183], v[204:207], v[80:83]
	v_mfma_f32_16x16x32_bf16 v[72:75], v[172:175], v[212:215], v[72:75]
	v_mfma_f32_16x16x32_bf16 v[64:67], v[180:183], v[212:215], v[64:67]
	s_barrier
	s_add_i32 s46, s64, s9
	s_mov_b32 m0, s46
	s_add_u32 s98, s48, 0x80
	s_addc_u32 s99, s49, 0
	ds_read_b128 v[184:187], v157 offset:49152
	ds_read_b128 v[188:191], v157 offset:50176
	ds_read_b128 v[192:195], v157 offset:51200
	ds_read_b128 v[196:199], v157 offset:52224
	ds_read_b128 v[200:203], v157 offset:53248
	ds_read_b128 v[204:207], v157 offset:54272
	ds_read_b128 v[208:211], v157 offset:55296
	ds_read_b128 v[212:215], v157 offset:56320
	global_load_lds_dwordx4 v132, s[98:99]
	s_add_i32 m0, s46, 0x2000
	s_add_u32 s46, s48, 0x104080
	s_addc_u32 s47, s49, 0
	s_add_i32 s48, s65, s9
	global_load_lds_dwordx4 v128, s[98:99]
	s_mov_b32 m0, s48
	s_nop 0
	global_load_lds_dwordx4 v132, s[46:47]
	s_add_i32 m0, s48, 0x2000
	s_nop 0
	global_load_lds_dwordx4 v128, s[46:47]
	s_nop 0
	s_waitcnt vmcnt(4)
	s_waitcnt lgkmcnt(0)
	s_barrier
	s_waitcnt lgkmcnt(0)
	v_mfma_f32_16x16x32_bf16 v[60:63], v[144:147], v[184:187], v[60:63]
	v_mfma_f32_16x16x32_bf16 v[52:55], v[160:163], v[184:187], v[52:55]
	v_mfma_f32_16x16x32_bf16 v[44:47], v[144:147], v[192:195], v[44:47]
	v_mfma_f32_16x16x32_bf16 v[36:39], v[160:163], v[192:195], v[36:39]
	v_mfma_f32_16x16x32_bf16 v[28:31], v[144:147], v[200:203], v[28:31]
	v_mfma_f32_16x16x32_bf16 v[20:23], v[160:163], v[200:203], v[20:23]
	v_mfma_f32_16x16x32_bf16 v[12:15], v[144:147], v[208:211], v[12:15]
	v_mfma_f32_16x16x32_bf16 v[4:7], v[160:163], v[208:211], v[4:7]
	v_mfma_f32_16x16x32_bf16 v[60:63], v[148:151], v[188:191], v[60:63]
	v_mfma_f32_16x16x32_bf16 v[52:55], v[164:167], v[188:191], v[52:55]
	v_mfma_f32_16x16x32_bf16 v[44:47], v[148:151], v[196:199], v[44:47]
	v_mfma_f32_16x16x32_bf16 v[36:39], v[164:167], v[196:199], v[36:39]
	v_mfma_f32_16x16x32_bf16 v[28:31], v[148:151], v[204:207], v[28:31]
	v_mfma_f32_16x16x32_bf16 v[20:23], v[164:167], v[204:207], v[20:23]
	v_mfma_f32_16x16x32_bf16 v[12:15], v[148:151], v[212:215], v[12:15]
	v_mfma_f32_16x16x32_bf16 v[4:7], v[164:167], v[212:215], v[4:7]
	v_mfma_f32_16x16x32_bf16 v[56:59], v[168:171], v[184:187], v[56:59]
	v_mfma_f32_16x16x32_bf16 v[48:51], v[176:179], v[184:187], v[48:51]
	v_mfma_f32_16x16x32_bf16 v[40:43], v[168:171], v[192:195], v[40:43]
	v_mfma_f32_16x16x32_bf16 v[32:35], v[176:179], v[192:195], v[32:35]
	v_mfma_f32_16x16x32_bf16 v[24:27], v[168:171], v[200:203], v[24:27]
	v_mfma_f32_16x16x32_bf16 v[16:19], v[176:179], v[200:203], v[16:19]
	v_mfma_f32_16x16x32_bf16 v[8:11], v[168:171], v[208:211], v[8:11]
	v_mfma_f32_16x16x32_bf16 v[0:3], v[176:179], v[208:211], v[0:3]
	v_mfma_f32_16x16x32_bf16 v[56:59], v[172:175], v[188:191], v[56:59]
	v_mfma_f32_16x16x32_bf16 v[48:51], v[180:183], v[188:191], v[48:51]
	v_mfma_f32_16x16x32_bf16 v[40:43], v[172:175], v[196:199], v[40:43]
	v_mfma_f32_16x16x32_bf16 v[32:35], v[180:183], v[196:199], v[32:35]
	v_mfma_f32_16x16x32_bf16 v[24:27], v[172:175], v[204:207], v[24:27]
	v_mfma_f32_16x16x32_bf16 v[16:19], v[180:183], v[204:207], v[16:19]
	v_mfma_f32_16x16x32_bf16 v[8:11], v[172:175], v[212:215], v[8:11]
	v_mfma_f32_16x16x32_bf16 v[0:3], v[180:183], v[212:215], v[0:3]
	s_barrier
	s_add_i32 s63, s63, 2
	s_add_u32 s61, s61, 0x100
	s_addc_u32 s62, s62, 0
	s_cmp_gt_u32 s63, 61
	s_mov_b64 s[46:47], s[4:5]
	s_cbranch_scc0 .LBB0_1133
	s_and_b64 vcc, exec, s[40:41]
	s_cbranch_vccz .LBB0_1136
	s_barrier

; #define PG8_STAGE(bufoff, gbase, voff) do { _Pragma("unroll") for (int _i = 0; _i < 2; ++_i) \
;         __builtin_amdgcn_global_load_lds((const unsigned*)((const char*)(gbase) + (voff)[_i]), (PG8_LAS unsigned*)(lds + (bufoff) + ldsw + _i * 8192), 16, 0, 0); } while (0)
; #define PG8_STAGE_NT(bufoff, gbase, voff) do { _Pragma("unroll") for (int _i = 0; _i < 2; ++_i) \
;         __builtin_amdgcn_global_load_lds((const unsigned*)((const char*)(gbase) + (voff)[_i]), (PG8_LAS unsigned*)(lds + (bufoff) + ldsw + _i * 8192), 16, 0, PG8_B_AUX); } while (0)
; #define PG8_LDA(dst, b, h) do { _Pragma("unroll") for (int m = 0; m < 4; ++m) _Pragma("unroll") for (int k = 0; k < 2; ++k) dst[m][k] = *(const PG8_LAS bf16x8*)(lds + PG8_SA(b, h) + aoff + m * 2048 + k * 1024); } while (0)
; #define PG8_LDB(dst, b, h) do { _Pragma("unroll") for (int n = 0; n < 2; ++n) _Pragma("unroll") for (int k = 0; k < 2; ++k) dst[n][k] = *(const PG8_LAS bf16x8*)(lds + PG8_SB(b, h) + boff + n * 2048 + k * 1024); } while (0)
; #define PG8_WAIT_V(n) asm volatile("s_waitcnt vmcnt(" #n ")" ::: "memory")
; #define PG8_WAIT_L(n) asm volatile("s_waitcnt lgkmcnt(" #n ")" ::: "memory")
; #define PG8_BAR __builtin_amdgcn_s_barrier()
; #define PG8_SCHED __builtin_amdgcn_sched_barrier(0)
; template <class Epi, class Sched, bool ALIGN_EPI = false, bool SP2 = false>
; __device__ __forceinline__ void gemm_phase(PG8_LAS unsigned char* lds, const Gemm g, const Sched& S, const Epi& E, int wid) {
;     ...
;             const bool last = (t == nt - 2);
;             const char* a1 = cA + (size_t)(t + 1) * kstep;
;             const char* a2 = last ? nA : cA + (size_t)(t + 2) * kstep; const char* b2 = last ? nB : cB + (size_t)(t + 2) * kstep;
;             const char* a3 = a2 + kstep; const char* b3 = b2 + kstep;
;             if (last && has_next) S.a_ready(nxt);
;             if constexpr (SP2) {
;             PG8_LDB(B0, 0, 0); PG8_LDB(B1, 0, 1); PG8_SCHED; PG8_LDA(At, 0, 0); PG8_STAGE(PG8_SA(1, 1), a1 + hstepA, voffA);
;             PG8_WAIT_V(8); PG8_WAIT_L(0); PG8_BAR; PG8_MMA(0, 0, At, B0); PG8_MMA(0, 1, At, B1); PG8_BAR; PG8_SCHED;
;             PG8_LDA(At, 0, 1); PG8_STAGE_NT(PG8_SB(0, 0), b2, voffB); PG8_STAGE_NT(PG8_SB(0, 1), b2 + hstepB, voffB); PG8_STAGE(PG8_SA(0, 0), a2, voffA);
;             PG8_WAIT_V(8); PG8_WAIT_L(0); PG8_BAR; PG8_MMA(1, 0, At, B0); PG8_MMA(1, 1, At, B1); PG8_BAR; PG8_SCHED;
.LBB0_1221:
	ds_read_b128 v[128:131], v205
	ds_read_b128 v[132:135], v205 offset:1024
	ds_read_b128 v[136:139], v205 offset:2048
	ds_read_b128 v[140:143], v205 offset:3072
	ds_read_b128 v[144:147], v206
	ds_read_b128 v[148:151], v206 offset:1024
	ds_read_b128 v[152:155], v206 offset:2048
	ds_read_b128 v[156:159], v206 offset:3072
	s_add_u32 s48, s46, 0x100
	s_addc_u32 s49, s47, 0
	s_cmpk_eq_i32 s63, 0xa8
	s_cselect_b32 s53, s7, s49
	s_cselect_b32 s52, s6, s48
	s_cselect_b32 s51, s45, s62
	s_cselect_b32 s50, s44, s61
	v_lshl_add_u64 v[200:201], s[46:47], 0, v[176:177]
	s_add_i32 m0, s17, 0xc000
	ds_read_b128 v[160:163], v207
	ds_read_b128 v[164:167], v207 offset:1024
	ds_read_b128 v[184:187], v207 offset:2048
	ds_read_b128 v[188:191], v207 offset:3072
	ds_read_b128 v[192:195], v207 offset:4096
	ds_read_b128 v[196:199], v207 offset:5120
	ds_read_b128 v[210:213], v207 offset:6144
	ds_read_b128 v[214:217], v207 offset:7168
	global_load_lds_dwordx4 v[200:201], off
	v_lshl_add_u64 v[200:201], s[46:47], 0, v[178:179]
	s_add_i32 m0, s17, 0xe000
	s_nop 0
	global_load_lds_dwordx4 v[200:201], off
	s_waitcnt vmcnt(8)
	s_waitcnt lgkmcnt(0)
	s_barrier
	s_setprio 1
	s_waitcnt lgkmcnt(0)
	v_mfma_f32_16x16x32_bf16 v[124:127], v[128:131], v[160:163], v[124:127]
	v_mfma_f32_16x16x32_bf16 v[120:123], v[136:139], v[160:163], v[120:123]
	v_mfma_f32_16x16x32_bf16 v[116:119], v[128:131], v[184:187], v[116:119]
	v_mfma_f32_16x16x32_bf16 v[112:115], v[136:139], v[184:187], v[112:115]
	v_mfma_f32_16x16x32_bf16 v[92:95], v[128:131], v[192:195], v[92:95]
	v_mfma_f32_16x16x32_bf16 v[88:91], v[136:139], v[192:195], v[88:91]
	v_mfma_f32_16x16x32_bf16 v[76:79], v[128:131], v[210:213], v[76:79]
	v_mfma_f32_16x16x32_bf16 v[72:75], v[136:139], v[210:213], v[72:75]
	v_mfma_f32_16x16x32_bf16 v[124:127], v[132:135], v[164:167], v[124:127]
	v_mfma_f32_16x16x32_bf16 v[120:123], v[140:143], v[164:167], v[120:123]
	v_mfma_f32_16x16x32_bf16 v[116:119], v[132:135], v[188:191], v[116:119]
	v_mfma_f32_16x16x32_bf16 v[112:115], v[140:143], v[188:191], v[112:115]
	v_mfma_f32_16x16x32_bf16 v[92:95], v[132:135], v[196:199], v[92:95]
	v_mfma_f32_16x16x32_bf16 v[88:91], v[140:143], v[196:199], v[88:91]
	v_mfma_f32_16x16x32_bf16 v[76:79], v[132:135], v[214:217], v[76:79]
	v_mfma_f32_16x16x32_bf16 v[72:75], v[140:143], v[214:217], v[72:75]
	s_setprio 0
	s_setprio 1
	v_mfma_f32_16x16x32_bf16 v[108:111], v[144:147], v[160:163], v[108:111]
	v_mfma_f32_16x16x32_bf16 v[104:107], v[152:155], v[160:163], v[104:107]
	v_mfma_f32_16x16x32_bf16 v[100:103], v[144:147], v[184:187], v[100:103]
	v_mfma_f32_16x16x32_bf16 v[96:99], v[152:155], v[184:187], v[96:99]
	v_mfma_f32_16x16x32_bf16 v[84:87], v[144:147], v[192:195], v[84:87]
	v_mfma_f32_16x16x32_bf16 v[80:83], v[152:155], v[192:195], v[80:83]
	v_mfma_f32_16x16x32_bf16 v[68:71], v[144:147], v[210:213], v[68:71]
	v_mfma_f32_16x16x32_bf16 v[64:67], v[152:155], v[210:213], v[64:67]
	v_mfma_f32_16x16x32_bf16 v[108:111], v[148:151], v[164:167], v[108:111]
	v_mfma_f32_16x16x32_bf16 v[104:107], v[156:159], v[164:167], v[104:107]
	v_mfma_f32_16x16x32_bf16 v[100:103], v[148:151], v[188:191], v[100:103]
	v_mfma_f32_16x16x32_bf16 v[96:99], v[156:159], v[188:191], v[96:99]
	v_mfma_f32_16x16x32_bf16 v[84:87], v[148:151], v[196:199], v[84:87]
	v_mfma_f32_16x16x32_bf16 v[80:83], v[156:159], v[196:199], v[80:83]
	v_mfma_f32_16x16x32_bf16 v[68:71], v[148:151], v[214:217], v[68:71]
	v_mfma_f32_16x16x32_bf16 v[64:67], v[156:159], v[214:217], v[64:67]
	s_setprio 0
	s_barrier
	s_add_i32 s46, s56, s9
	v_lshl_add_u64 v[200:201], s[50:51], 0, v[170:171]
	s_mov_b32 m0, s46
	ds_read_b128 v[160:163], v207 offset:16384
	ds_read_b128 v[164:167], v207 offset:17408
	ds_read_b128 v[184:187], v207 offset:18432
	ds_read_b128 v[188:191], v207 offset:19456
	ds_read_b128 v[192:195], v207 offset:20480
	ds_read_b128 v[196:199], v207 offset:21504
	ds_read_b128 v[210:213], v207 offset:22528
	ds_read_b128 v[214:217], v207 offset:23552
	global_load_lds_dwordx4 v[200:201], off
	s_add_i32 m0, s46, 0x2000
	s_add_u32 s46, s50, 0x2b4000
	v_lshl_add_u64 v[218:219], s[50:51], 0, v[174:175]
	s_addc_u32 s47, s51, 0
	s_add_i32 s64, s57, s9
	global_load_lds_dwordx4 v[218:219], off
	v_lshl_add_u64 v[220:221], s[46:47], 0, v[170:171]
	s_mov_b32 m0, s64
	v_lshl_add_u64 v[222:223], s[52:53], 0, v[172:173]
	global_load_lds_dwordx4 v[220:221], off
	v_lshl_add_u64 v[220:221], s[46:47], 0, v[174:175]
	s_add_i32 m0, s64, 0x2000
	s_nop 0
	global_load_lds_dwordx4 v[220:221], off
	v_lshl_add_u64 v[220:221], s[52:53], 0, v[168:169]
	s_mov_b32 m0, s17
	s_nop 0
	global_load_lds_dwordx4 v[220:221], off
	s_mov_b32 m0, s19
	s_nop 0
	global_load_lds_dwordx4 v[222:223], off
	s_nop 0
	s_waitcnt vmcnt(8)
	s_waitcnt lgkmcnt(0)
	s_barrier
; #define PG8_STAGE(bufoff, gbase, voff) do { _Pragma("unroll") for (int _i = 0; _i < 2; ++_i) \
;         __builtin_amdgcn_global_load_lds((const unsigned*)((const char*)(gbase) + (voff)[_i]), (PG8_LAS unsigned*)(lds + (bufoff) + ldsw + _i * 8192), 16, 0, 0); } while (0)
; #define PG8_STAGE_NT(bufoff, gbase, voff) do { _Pragma("unroll") for (int _i = 0; _i < 2; ++_i) \
;         __builtin_amdgcn_global_load_lds((const unsigned*)((const char*)(gbase) + (voff)[_i]), (PG8_LAS unsigned*)(lds + (bufoff) + ldsw + _i * 8192), 16, 0, PG8_B_AUX); } while (0)
; #define PG8_LDA(dst, b, h) do { _Pragma("unroll") for (int m = 0; m < 4; ++m) _Pragma("unroll") for (int k = 0; k < 2; ++k) dst[m][k] = *(const PG8_LAS bf16x8*)(lds + PG8_SA(b, h) + aoff + m * 2048 + k * 1024); } while (0)
; #define PG8_LDB(dst, b, h) do { _Pragma("unroll") for (int n = 0; n < 2; ++n) _Pragma("unroll") for (int k = 0; k < 2; ++k) dst[n][k] = *(const PG8_LAS bf16x8*)(lds + PG8_SB(b, h) + boff + n * 2048 + k * 1024); } while (0)
; #define PG8_MMA(ai, bj, At, Bt) do { __builtin_amdgcn_s_setprio(1); _Pragma("unroll") for (int m = 0; m < 4; ++m) _Pragma("unroll") for (int n = 0; n < 2; ++n) _Pragma("unroll") for (int k = 0; k < 2; ++k) \
;         acc[ai][bj][m][n] = __builtin_amdgcn_mfma_f32_16x16x32_bf16(Bt[n][k], At[m][k], acc[ai][bj][m][n], 0, 0, 0); __builtin_amdgcn_s_setprio(0); } while (0)
; #define PG8_WAIT_V(n) asm volatile("s_waitcnt vmcnt(" #n ")" ::: "memory")
; #define PG8_WAIT_L(n) asm volatile("s_waitcnt lgkmcnt(" #n ")" ::: "memory")
; #define PG8_BAR __builtin_amdgcn_s_barrier()
; #define PG8_SCHED __builtin_amdgcn_sched_barrier(0)
; template <class Epi, class Sched, bool ALIGN_EPI = false, bool SP2 = false>
; __device__ __forceinline__ void gemm_phase(PG8_LAS unsigned char* lds, const Gemm g, const Sched& S, const Epi& E, int wid) {
;     ...
;             PG8_WAIT_V(8); PG8_WAIT_L(0); PG8_BAR; PG8_MMA(1, 0, At, B0); PG8_MMA(1, 1, At, B1); PG8_BAR; PG8_SCHED;
;             PG8_LDB(B0, 1, 0); PG8_LDB(B1, 1, 1); PG8_SCHED; PG8_LDA(At, 1, 0); PG8_STAGE(PG8_SA(0, 1), a2 + hstepA, voffA);
;             PG8_WAIT_V(8); PG8_WAIT_L(0); PG8_BAR; PG8_MMA(0, 0, At, B0); PG8_MMA(0, 1, At, B1); PG8_BAR; PG8_SCHED;
;             PG8_LDA(At, 1, 1); PG8_STAGE_NT(PG8_SB(1, 0), b3, voffB); PG8_STAGE_NT(PG8_SB(1, 1), b3 + hstepB, voffB); PG8_STAGE(PG8_SA(1, 0), a3, voffA);
	s_setprio 1
	s_waitcnt lgkmcnt(0)
	v_mfma_f32_16x16x32_bf16 v[60:63], v[128:131], v[160:163], v[60:63]
	v_mfma_f32_16x16x32_bf16 v[56:59], v[136:139], v[160:163], v[56:59]
	v_mfma_f32_16x16x32_bf16 v[44:47], v[128:131], v[184:187], v[44:47]
	v_mfma_f32_16x16x32_bf16 v[40:43], v[136:139], v[184:187], v[40:43]
	v_mfma_f32_16x16x32_bf16 v[28:31], v[128:131], v[192:195], v[28:31]
	v_mfma_f32_16x16x32_bf16 v[24:27], v[136:139], v[192:195], v[24:27]
	v_mfma_f32_16x16x32_bf16 v[12:15], v[128:131], v[210:213], v[12:15]
	v_mfma_f32_16x16x32_bf16 v[8:11], v[136:139], v[210:213], v[8:11]
	v_mfma_f32_16x16x32_bf16 v[60:63], v[132:135], v[164:167], v[60:63]
	v_mfma_f32_16x16x32_bf16 v[56:59], v[140:143], v[164:167], v[56:59]
	v_mfma_f32_16x16x32_bf16 v[44:47], v[132:135], v[188:191], v[44:47]
	v_mfma_f32_16x16x32_bf16 v[40:43], v[140:143], v[188:191], v[40:43]
	v_mfma_f32_16x16x32_bf16 v[28:31], v[132:135], v[196:199], v[28:31]
	v_mfma_f32_16x16x32_bf16 v[24:27], v[140:143], v[196:199], v[24:27]
	v_mfma_f32_16x16x32_bf16 v[12:15], v[132:135], v[214:217], v[12:15]
	v_mfma_f32_16x16x32_bf16 v[8:11], v[140:143], v[214:217], v[8:11]
	s_setprio 0
	s_setprio 1
	v_mfma_f32_16x16x32_bf16 v[52:55], v[144:147], v[160:163], v[52:55]
	v_mfma_f32_16x16x32_bf16 v[48:51], v[152:155], v[160:163], v[48:51]
	v_mfma_f32_16x16x32_bf16 v[36:39], v[144:147], v[184:187], v[36:39]
	v_mfma_f32_16x16x32_bf16 v[32:35], v[152:155], v[184:187], v[32:35]
	v_mfma_f32_16x16x32_bf16 v[20:23], v[144:147], v[192:195], v[20:23]
	v_mfma_f32_16x16x32_bf16 v[16:19], v[152:155], v[192:195], v[16:19]
	v_mfma_f32_16x16x32_bf16 v[4:7], v[144:147], v[210:213], v[4:7]
	v_mfma_f32_16x16x32_bf16 v[0:3], v[152:155], v[210:213], v[0:3]
	v_mfma_f32_16x16x32_bf16 v[52:55], v[148:151], v[164:167], v[52:55]
	v_mfma_f32_16x16x32_bf16 v[48:51], v[156:159], v[164:167], v[48:51]
	v_mfma_f32_16x16x32_bf16 v[36:39], v[148:151], v[188:191], v[36:39]
	v_mfma_f32_16x16x32_bf16 v[32:35], v[156:159], v[188:191], v[32:35]
	v_mfma_f32_16x16x32_bf16 v[20:23], v[148:151], v[196:199], v[20:23]
	v_mfma_f32_16x16x32_bf16 v[16:19], v[156:159], v[196:199], v[16:19]
	v_mfma_f32_16x16x32_bf16 v[4:7], v[148:151], v[214:217], v[4:7]
	v_mfma_f32_16x16x32_bf16 v[0:3], v[156:159], v[214:217], v[0:3]
	s_setprio 0
	s_barrier
	s_add_i32 s64, 0, 0x18000
	s_add_i32 s65, 0, 0x1c000
	v_add_u32_e32 v140, s64, v203
	v_add_u32_e32 v156, s65, v203
	ds_read_b128 v[128:131], v140
	ds_read_b128 v[132:135], v140 offset:1024
	ds_read_b128 v[136:139], v140 offset:2048
	ds_read_b128 v[140:143], v140 offset:3072
	ds_read_b128 v[144:147], v156
	ds_read_b128 v[148:151], v156 offset:1024
	ds_read_b128 v[152:155], v156 offset:2048
	ds_read_b128 v[156:159], v156 offset:3072
	s_add_u32 s46, s52, 0x2b4000
	s_addc_u32 s47, s53, 0
	s_mov_b32 m0, s22
	v_lshl_add_u64 v[224:225], s[46:47], 0, v[168:169]
	ds_read_b128 v[160:163], v207 offset:32768
	ds_read_b128 v[164:167], v207 offset:33792
	ds_read_b128 v[184:187], v207 offset:34816
	ds_read_b128 v[188:191], v207 offset:35840
	ds_read_b128 v[192:195], v207 offset:36864
	ds_read_b128 v[196:199], v207 offset:37888
	ds_read_b128 v[210:213], v207 offset:38912
	ds_read_b128 v[214:217], v207 offset:39936
	global_load_lds_dwordx4 v[224:225], off
	v_lshl_add_u64 v[224:225], s[46:47], 0, v[172:173]
	s_mov_b32 m0, s23
	s_nop 0
	global_load_lds_dwordx4 v[224:225], off
	s_nop 0
	s_waitcnt vmcnt(8)
	s_waitcnt lgkmcnt(0)
	s_barrier
	s_setprio 1
	s_waitcnt lgkmcnt(0)
	v_mfma_f32_16x16x32_bf16 v[124:127], v[128:131], v[160:163], v[124:127]
	v_mfma_f32_16x16x32_bf16 v[120:123], v[136:139], v[160:163], v[120:123]
	v_mfma_f32_16x16x32_bf16 v[116:119], v[128:131], v[184:187], v[116:119]
	v_mfma_f32_16x16x32_bf16 v[112:115], v[136:139], v[184:187], v[112:115]
	v_mfma_f32_16x16x32_bf16 v[92:95], v[128:131], v[192:195], v[92:95]
	v_mfma_f32_16x16x32_bf16 v[88:91], v[136:139], v[192:195], v[88:91]
	v_mfma_f32_16x16x32_bf16 v[76:79], v[128:131], v[210:213], v[76:79]
	v_mfma_f32_16x16x32_bf16 v[72:75], v[136:139], v[210:213], v[72:75]
	v_mfma_f32_16x16x32_bf16 v[124:127], v[132:135], v[164:167], v[124:127]
	v_mfma_f32_16x16x32_bf16 v[120:123], v[140:143], v[164:167], v[120:123]
	v_mfma_f32_16x16x32_bf16 v[116:119], v[132:135], v[188:191], v[116:119]
	v_mfma_f32_16x16x32_bf16 v[112:115], v[140:143], v[188:191], v[112:115]
	v_mfma_f32_16x16x32_bf16 v[92:95], v[132:135], v[196:199], v[92:95]
	v_mfma_f32_16x16x32_bf16 v[88:91], v[140:143], v[196:199], v[88:91]
	v_mfma_f32_16x16x32_bf16 v[76:79], v[132:135], v[214:217], v[76:79]
	v_mfma_f32_16x16x32_bf16 v[72:75], v[140:143], v[214:217], v[72:75]
	s_setprio 0
	s_setprio 1
	v_mfma_f32_16x16x32_bf16 v[108:111], v[144:147], v[160:163], v[108:111]
	v_mfma_f32_16x16x32_bf16 v[104:107], v[152:155], v[160:163], v[104:107]
	v_mfma_f32_16x16x32_bf16 v[100:103], v[144:147], v[184:187], v[100:103]
	v_mfma_f32_16x16x32_bf16 v[96:99], v[152:155], v[184:187], v[96:99]
	v_mfma_f32_16x16x32_bf16 v[84:87], v[144:147], v[192:195], v[84:87]
	v_mfma_f32_16x16x32_bf16 v[80:83], v[152:155], v[192:195], v[80:83]
	v_mfma_f32_16x16x32_bf16 v[68:71], v[144:147], v[210:213], v[68:71]
	v_mfma_f32_16x16x32_bf16 v[64:67], v[152:155], v[210:213], v[64:67]
	v_mfma_f32_16x16x32_bf16 v[108:111], v[148:151], v[164:167], v[108:111]
	v_mfma_f32_16x16x32_bf16 v[104:107], v[156:159], v[164:167], v[104:107]
	v_mfma_f32_16x16x32_bf16 v[100:103], v[148:151], v[188:191], v[100:103]
	v_mfma_f32_16x16x32_bf16 v[96:99], v[156:159], v[188:191], v[96:99]
	v_mfma_f32_16x16x32_bf16 v[84:87], v[148:151], v[196:199], v[84:87]
	v_mfma_f32_16x16x32_bf16 v[80:83], v[156:159], v[196:199], v[80:83]
	v_mfma_f32_16x16x32_bf16 v[68:71], v[148:151], v[214:217], v[68:71]
	v_mfma_f32_16x16x32_bf16 v[64:67], v[156:159], v[214:217], v[64:67]
	s_setprio 0
	s_barrier
; #define PG8_STAGE(bufoff, gbase, voff) do { _Pragma("unroll") for (int _i = 0; _i < 2; ++_i) \
;         __builtin_amdgcn_global_load_lds((const unsigned*)((const char*)(gbase) + (voff)[_i]), (PG8_LAS unsigned*)(lds + (bufoff) + ldsw + _i * 8192), 16, 0, 0); } while (0)
; #define PG8_STAGE_NT(bufoff, gbase, voff) do { _Pragma("unroll") for (int _i = 0; _i < 2; ++_i) \
;         __builtin_amdgcn_global_load_lds((const unsigned*)((const char*)(gbase) + (voff)[_i]), (PG8_LAS unsigned*)(lds + (bufoff) + ldsw + _i * 8192), 16, 0, PG8_B_AUX); } while (0)
; #define PG8_LDA(dst, b, h) do { _Pragma("unroll") for (int m = 0; m < 4; ++m) _Pragma("unroll") for (int k = 0; k < 2; ++k) dst[m][k] = *(const PG8_LAS bf16x8*)(lds + PG8_SA(b, h) + aoff + m * 2048 + k * 1024); } while (0)
; #define PG8_MMA(ai, bj, At, Bt) do { __builtin_amdgcn_s_setprio(1); _Pragma("unroll") for (int m = 0; m < 4; ++m) _Pragma("unroll") for (int n = 0; n < 2; ++n) _Pragma("unroll") for (int k = 0; k < 2; ++k) \
;         acc[ai][bj][m][n] = __builtin_amdgcn_mfma_f32_16x16x32_bf16(Bt[n][k], At[m][k], acc[ai][bj][m][n], 0, 0, 0); __builtin_amdgcn_s_setprio(0); } while (0)
; #define PG8_WAIT_V(n) asm volatile("s_waitcnt vmcnt(" #n ")" ::: "memory")
; #define PG8_WAIT_L(n) asm volatile("s_waitcnt lgkmcnt(" #n ")" ::: "memory")
; #define PG8_BAR __builtin_amdgcn_s_barrier()
; #define PG8_SCHED __builtin_amdgcn_sched_barrier(0)
; template <class Epi, class Sched, bool ALIGN_EPI = false, bool SP2 = false>
; __device__ __forceinline__ void gemm_phase(PG8_LAS unsigned char* lds, const Gemm g, const Sched& S, const Epi& E, int wid) {
;     ...
;             PG8_LDA(At, 1, 1); PG8_STAGE_NT(PG8_SB(1, 0), b3, voffB); PG8_STAGE_NT(PG8_SB(1, 1), b3 + hstepB, voffB); PG8_STAGE(PG8_SA(1, 0), a3, voffA);
;             PG8_WAIT_V(8); PG8_WAIT_L(0); PG8_BAR; PG8_MMA(1, 0, At, B0); PG8_MMA(1, 1, At, B1); PG8_BAR; PG8_SCHED;
;     ...
;         if constexpr (ALIGN_EPI) { if (wr == 0) PG8_BAR; }
	s_add_i32 s46, s64, s9
	v_lshl_add_u64 v[200:201], v[200:201], 0, s[40:41]
	s_mov_b32 m0, s46
	ds_read_b128 v[160:163], v207 offset:49152
	ds_read_b128 v[164:167], v207 offset:50176
	ds_read_b128 v[184:187], v207 offset:51200
	ds_read_b128 v[188:191], v207 offset:52224
	ds_read_b128 v[192:195], v207 offset:53248
	ds_read_b128 v[196:199], v207 offset:54272
	ds_read_b128 v[210:213], v207 offset:55296
	ds_read_b128 v[214:217], v207 offset:56320
	global_load_lds_dwordx4 v[200:201], off
	s_add_i32 m0, s46, 0x2000
	s_add_u32 s46, s50, 0x2b4080
	v_lshl_add_u64 v[200:201], v[218:219], 0, s[40:41]
	s_addc_u32 s47, s51, 0
	s_add_i32 s50, s65, s9
	global_load_lds_dwordx4 v[200:201], off
	v_lshl_add_u64 v[200:201], s[46:47], 0, v[170:171]
	s_mov_b32 m0, s50
	s_nop 0
	global_load_lds_dwordx4 v[200:201], off
	v_lshl_add_u64 v[200:201], s[46:47], 0, v[174:175]
	s_add_i32 m0, s50, 0x2000
	s_nop 0
	global_load_lds_dwordx4 v[200:201], off
	v_lshl_add_u64 v[200:201], v[220:221], 0, s[40:41]
	s_mov_b32 m0, s25
	s_nop 0
	global_load_lds_dwordx4 v[200:201], off
	v_lshl_add_u64 v[200:201], v[222:223], 0, s[40:41]
	s_mov_b32 m0, s29
	s_nop 0
	global_load_lds_dwordx4 v[200:201], off
	s_waitcnt vmcnt(8)
	s_waitcnt lgkmcnt(0)
	s_barrier
	s_setprio 1
	s_waitcnt lgkmcnt(0)
	v_mfma_f32_16x16x32_bf16 v[60:63], v[128:131], v[160:163], v[60:63]
	v_mfma_f32_16x16x32_bf16 v[56:59], v[136:139], v[160:163], v[56:59]
	v_mfma_f32_16x16x32_bf16 v[44:47], v[128:131], v[184:187], v[44:47]
	v_mfma_f32_16x16x32_bf16 v[40:43], v[136:139], v[184:187], v[40:43]
	v_mfma_f32_16x16x32_bf16 v[28:31], v[128:131], v[192:195], v[28:31]
	v_mfma_f32_16x16x32_bf16 v[24:27], v[136:139], v[192:195], v[24:27]
	v_mfma_f32_16x16x32_bf16 v[12:15], v[128:131], v[210:213], v[12:15]
	v_mfma_f32_16x16x32_bf16 v[8:11], v[136:139], v[210:213], v[8:11]
	v_mfma_f32_16x16x32_bf16 v[60:63], v[132:135], v[164:167], v[60:63]
	v_mfma_f32_16x16x32_bf16 v[56:59], v[140:143], v[164:167], v[56:59]
	v_mfma_f32_16x16x32_bf16 v[44:47], v[132:135], v[188:191], v[44:47]
	v_mfma_f32_16x16x32_bf16 v[40:43], v[140:143], v[188:191], v[40:43]
	v_mfma_f32_16x16x32_bf16 v[28:31], v[132:135], v[196:199], v[28:31]
	v_mfma_f32_16x16x32_bf16 v[24:27], v[140:143], v[196:199], v[24:27]
	v_mfma_f32_16x16x32_bf16 v[12:15], v[132:135], v[214:217], v[12:15]
	v_mfma_f32_16x16x32_bf16 v[8:11], v[140:143], v[214:217], v[8:11]
	s_setprio 0
	s_setprio 1
	v_mfma_f32_16x16x32_bf16 v[52:55], v[144:147], v[160:163], v[52:55]
	v_mfma_f32_16x16x32_bf16 v[48:51], v[152:155], v[160:163], v[48:51]
	v_mfma_f32_16x16x32_bf16 v[36:39], v[144:147], v[184:187], v[36:39]
	v_mfma_f32_16x16x32_bf16 v[32:35], v[152:155], v[184:187], v[32:35]
	v_mfma_f32_16x16x32_bf16 v[20:23], v[144:147], v[192:195], v[20:23]
	v_mfma_f32_16x16x32_bf16 v[16:19], v[152:155], v[192:195], v[16:19]
	v_mfma_f32_16x16x32_bf16 v[4:7], v[144:147], v[210:213], v[4:7]
	v_mfma_f32_16x16x32_bf16 v[0:3], v[152:155], v[210:213], v[0:3]
	v_mfma_f32_16x16x32_bf16 v[52:55], v[148:151], v[164:167], v[52:55]
	v_mfma_f32_16x16x32_bf16 v[48:51], v[156:159], v[164:167], v[48:51]
	v_mfma_f32_16x16x32_bf16 v[36:39], v[148:151], v[188:191], v[36:39]
	v_mfma_f32_16x16x32_bf16 v[32:35], v[156:159], v[188:191], v[32:35]
	v_mfma_f32_16x16x32_bf16 v[20:23], v[148:151], v[196:199], v[20:23]
	v_mfma_f32_16x16x32_bf16 v[16:19], v[156:159], v[196:199], v[16:19]
	v_mfma_f32_16x16x32_bf16 v[4:7], v[148:151], v[214:217], v[4:7]
	v_mfma_f32_16x16x32_bf16 v[0:3], v[156:159], v[214:217], v[0:3]
	s_setprio 0
	s_barrier
	s_add_i32 s63, s63, 2
	s_add_u32 s61, s61, 0x100
	s_addc_u32 s62, s62, 0
	s_cmpk_gt_u32 s63, 0xa9
	s_mov_b64 s[46:47], s[48:49]
	s_cbranch_scc0 .LBB0_1221
	s_and_b64 vcc, exec, s[42:43]
	s_cbranch_vccz .LBB0_1224
	s_barrier

; #define PG8_STAGE(bufoff, gbase, voff) do { _Pragma("unroll") for (int _i = 0; _i < 2; ++_i) \
;         __builtin_amdgcn_global_load_lds((const unsigned*)((const char*)(gbase) + (voff)[_i]), (PG8_LAS unsigned*)(lds + (bufoff) + ldsw + _i * 8192), 16, 0, 0); } while (0)
; #define PG8_STAGE_NT(bufoff, gbase, voff) do { _Pragma("unroll") for (int _i = 0; _i < 2; ++_i) \
;         __builtin_amdgcn_global_load_lds((const unsigned*)((const char*)(gbase) + (voff)[_i]), (PG8_LAS unsigned*)(lds + (bufoff) + ldsw + _i * 8192), 16, 0, PG8_B_AUX); } while (0)
; #define PG8_LDA(dst, b, h) do { _Pragma("unroll") for (int m = 0; m < 4; ++m) _Pragma("unroll") for (int k = 0; k < 2; ++k) dst[m][k] = *(const PG8_LAS bf16x8*)(lds + PG8_SA(b, h) + aoff + m * 2048 + k * 1024); } while (0)
; #define PG8_LDB(dst, b, h) do { _Pragma("unroll") for (int n = 0; n < 2; ++n) _Pragma("unroll") for (int k = 0; k < 2; ++k) dst[n][k] = *(const PG8_LAS bf16x8*)(lds + PG8_SB(b, h) + boff + n * 2048 + k * 1024); } while (0)
; #define PG8_WAIT_V(n) asm volatile("s_waitcnt vmcnt(" #n ")" ::: "memory")
; #define PG8_WAIT_L(n) asm volatile("s_waitcnt lgkmcnt(" #n ")" ::: "memory")
; #define PG8_BAR __builtin_amdgcn_s_barrier()
; #define PG8_SCHED __builtin_amdgcn_sched_barrier(0)
; template <class Epi, class Sched, bool ALIGN_EPI = false, bool SP2 = false>
; __device__ __forceinline__ void gemm_phase(PG8_LAS unsigned char* lds, const Gemm g, const Sched& S, const Epi& E, int wid) {
;     ...
;             const bool last = (t == nt - 2);
;             const char* a1 = cA + (size_t)(t + 1) * kstep;
;             const char* a2 = last ? nA : cA + (size_t)(t + 2) * kstep; const char* b2 = last ? nB : cB + (size_t)(t + 2) * kstep;
;             const char* a3 = a2 + kstep; const char* b3 = b2 + kstep;
;             if (last && has_next) S.a_ready(nxt);
;             if constexpr (SP2) {
;             PG8_LDB(B0, 0, 0); PG8_LDB(B1, 0, 1); PG8_SCHED; PG8_LDA(At, 0, 0); PG8_STAGE(PG8_SA(1, 1), a1 + hstepA, voffA);
;             PG8_WAIT_V(8); PG8_WAIT_L(0); PG8_BAR; PG8_MMA(0, 0, At, B0); PG8_MMA(0, 1, At, B1); PG8_BAR; PG8_SCHED;
;             PG8_LDA(At, 0, 1); PG8_STAGE_NT(PG8_SB(0, 0), b2, voffB); PG8_STAGE_NT(PG8_SB(0, 1), b2 + hstepB, voffB); PG8_STAGE(PG8_SA(0, 0), a2, voffA);
;             PG8_WAIT_V(8); PG8_WAIT_L(0); PG8_BAR; PG8_MMA(1, 0, At, B0); PG8_MMA(1, 1, At, B1); PG8_BAR; PG8_SCHED;
.LBB0_1249:
	ds_read_b128 v[146:149], v141
	ds_read_b128 v[150:153], v141 offset:1024
	ds_read_b128 v[154:157], v141 offset:2048
	ds_read_b128 v[158:161], v141 offset:3072
	ds_read_b128 v[162:165], v142
	ds_read_b128 v[166:169], v142 offset:1024
	ds_read_b128 v[170:173], v142 offset:2048
	ds_read_b128 v[174:177], v142 offset:3072
	s_add_u32 s46, s14, s50
	s_addc_u32 s47, s15, s51
	s_add_u32 s53, s14, s44
	s_addc_u32 s54, s15, s45
	s_cmpk_eq_i32 s52, 0xa8
	s_cselect_b32 s49, s3, s47
	s_cselect_b32 s48, s2, s46
	s_cselect_b32 s47, s11, s54
	s_cselect_b32 s46, s10, s53
	s_mov_b32 m0, s57
	v_lshl_add_u64 v[212:213], s[14:15], 0, v[136:137]
	ds_read_b128 v[178:181], v143
	ds_read_b128 v[182:185], v143 offset:1024
	ds_read_b128 v[186:189], v143 offset:2048
	ds_read_b128 v[190:193], v143 offset:3072
	ds_read_b128 v[194:197], v143 offset:4096
	ds_read_b128 v[198:201], v143 offset:5120
	ds_read_b128 v[202:205], v143 offset:6144
	ds_read_b128 v[208:211], v143 offset:7168
	global_load_lds_dwordx4 v[212:213], off
	v_lshl_add_u64 v[212:213], s[14:15], 0, v[138:139]
	s_mov_b32 m0, s58
	s_nop 0
	global_load_lds_dwordx4 v[212:213], off
	s_waitcnt vmcnt(8)
	s_waitcnt lgkmcnt(0)
	s_barrier
	s_setprio 1
	s_waitcnt lgkmcnt(0)
	v_mfma_f32_16x16x32_bf16 v[124:127], v[146:149], v[178:181], v[124:127]
	v_mfma_f32_16x16x32_bf16 v[120:123], v[154:157], v[178:181], v[120:123]
	v_mfma_f32_16x16x32_bf16 v[108:111], v[146:149], v[186:189], v[108:111]
	v_mfma_f32_16x16x32_bf16 v[104:107], v[154:157], v[186:189], v[104:107]
	v_mfma_f32_16x16x32_bf16 v[92:95], v[146:149], v[194:197], v[92:95]
	v_mfma_f32_16x16x32_bf16 v[88:91], v[154:157], v[194:197], v[88:91]
	v_mfma_f32_16x16x32_bf16 v[76:79], v[146:149], v[202:205], v[76:79]
	v_mfma_f32_16x16x32_bf16 v[72:75], v[154:157], v[202:205], v[72:75]
	v_mfma_f32_16x16x32_bf16 v[124:127], v[150:153], v[182:185], v[124:127]
	v_mfma_f32_16x16x32_bf16 v[120:123], v[158:161], v[182:185], v[120:123]
	v_mfma_f32_16x16x32_bf16 v[108:111], v[150:153], v[190:193], v[108:111]
	v_mfma_f32_16x16x32_bf16 v[104:107], v[158:161], v[190:193], v[104:107]
	v_mfma_f32_16x16x32_bf16 v[92:95], v[150:153], v[198:201], v[92:95]
	v_mfma_f32_16x16x32_bf16 v[88:91], v[158:161], v[198:201], v[88:91]
	v_mfma_f32_16x16x32_bf16 v[76:79], v[150:153], v[208:211], v[76:79]
	v_mfma_f32_16x16x32_bf16 v[72:75], v[158:161], v[208:211], v[72:75]
	s_setprio 0
	s_setprio 1
	v_mfma_f32_16x16x32_bf16 v[116:119], v[162:165], v[178:181], v[116:119]
	v_mfma_f32_16x16x32_bf16 v[112:115], v[170:173], v[178:181], v[112:115]
	v_mfma_f32_16x16x32_bf16 v[100:103], v[162:165], v[186:189], v[100:103]
	v_mfma_f32_16x16x32_bf16 v[96:99], v[170:173], v[186:189], v[96:99]
	v_mfma_f32_16x16x32_bf16 v[84:87], v[162:165], v[194:197], v[84:87]
	v_mfma_f32_16x16x32_bf16 v[80:83], v[170:173], v[194:197], v[80:83]
	v_mfma_f32_16x16x32_bf16 v[68:71], v[162:165], v[202:205], v[68:71]
	v_mfma_f32_16x16x32_bf16 v[64:67], v[170:173], v[202:205], v[64:67]
	v_mfma_f32_16x16x32_bf16 v[116:119], v[166:169], v[182:185], v[116:119]
	v_mfma_f32_16x16x32_bf16 v[112:115], v[174:177], v[182:185], v[112:115]
	v_mfma_f32_16x16x32_bf16 v[100:103], v[166:169], v[190:193], v[100:103]
	v_mfma_f32_16x16x32_bf16 v[96:99], v[174:177], v[190:193], v[96:99]
	v_mfma_f32_16x16x32_bf16 v[84:87], v[166:169], v[198:201], v[84:87]
	v_mfma_f32_16x16x32_bf16 v[80:83], v[174:177], v[198:201], v[80:83]
	v_mfma_f32_16x16x32_bf16 v[68:71], v[166:169], v[208:211], v[68:71]
	v_mfma_f32_16x16x32_bf16 v[64:67], v[174:177], v[208:211], v[64:67]
	s_setprio 0
	s_barrier
	s_mov_b32 m0, s59
	v_lshl_add_u64 v[212:213], s[46:47], 0, v[130:131]
	s_add_u32 s54, s46, 0x2b4000
	ds_read_b128 v[178:181], v143 offset:16384
	ds_read_b128 v[182:185], v143 offset:17408
	ds_read_b128 v[186:189], v143 offset:18432
	ds_read_b128 v[190:193], v143 offset:19456
	ds_read_b128 v[194:197], v143 offset:20480
	ds_read_b128 v[198:201], v143 offset:21504
	ds_read_b128 v[202:205], v143 offset:22528
	ds_read_b128 v[208:211], v143 offset:23552
	global_load_lds_dwordx4 v[212:213], off
	v_lshl_add_u64 v[214:215], s[46:47], 0, v[134:135]
	s_mov_b32 m0, s60
	s_addc_u32 s55, s47, 0
	global_load_lds_dwordx4 v[214:215], off
	v_lshl_add_u64 v[216:217], s[54:55], 0, v[130:131]
	s_mov_b32 m0, s61
	v_lshl_add_u64 v[218:219], s[48:49], 0, v[132:133]
	global_load_lds_dwordx4 v[216:217], off
	v_lshl_add_u64 v[216:217], s[54:55], 0, v[134:135]
	s_mov_b32 m0, s62
	s_nop 0
	global_load_lds_dwordx4 v[216:217], off
	v_lshl_add_u64 v[216:217], s[48:49], 0, v[128:129]
	s_mov_b32 m0, s17
	s_nop 0
	global_load_lds_dwordx4 v[216:217], off
	s_mov_b32 m0, s19
	s_nop 0
	global_load_lds_dwordx4 v[218:219], off
	s_nop 0
	s_waitcnt vmcnt(8)
	s_waitcnt lgkmcnt(0)
	s_barrier
; #define PG8_STAGE(bufoff, gbase, voff) do { _Pragma("unroll") for (int _i = 0; _i < 2; ++_i) \
;         __builtin_amdgcn_global_load_lds((const unsigned*)((const char*)(gbase) + (voff)[_i]), (PG8_LAS unsigned*)(lds + (bufoff) + ldsw + _i * 8192), 16, 0, 0); } while (0)
; #define PG8_STAGE_NT(bufoff, gbase, voff) do { _Pragma("unroll") for (int _i = 0; _i < 2; ++_i) \
;         __builtin_amdgcn_global_load_lds((const unsigned*)((const char*)(gbase) + (voff)[_i]), (PG8_LAS unsigned*)(lds + (bufoff) + ldsw + _i * 8192), 16, 0, PG8_B_AUX); } while (0)
; #define PG8_LDA(dst, b, h) do { _Pragma("unroll") for (int m = 0; m < 4; ++m) _Pragma("unroll") for (int k = 0; k < 2; ++k) dst[m][k] = *(const PG8_LAS bf16x8*)(lds + PG8_SA(b, h) + aoff + m * 2048 + k * 1024); } while (0)
; #define PG8_LDB(dst, b, h) do { _Pragma("unroll") for (int n = 0; n < 2; ++n) _Pragma("unroll") for (int k = 0; k < 2; ++k) dst[n][k] = *(const PG8_LAS bf16x8*)(lds + PG8_SB(b, h) + boff + n * 2048 + k * 1024); } while (0)
; #define PG8_MMA(ai, bj, At, Bt) do { __builtin_amdgcn_s_setprio(1); _Pragma("unroll") for (int m = 0; m < 4; ++m) _Pragma("unroll") for (int n = 0; n < 2; ++n) _Pragma("unroll") for (int k = 0; k < 2; ++k) \
;         acc[ai][bj][m][n] = __builtin_amdgcn_mfma_f32_16x16x32_bf16(Bt[n][k], At[m][k], acc[ai][bj][m][n], 0, 0, 0); __builtin_amdgcn_s_setprio(0); } while (0)
; #define PG8_WAIT_V(n) asm volatile("s_waitcnt vmcnt(" #n ")" ::: "memory")
; #define PG8_WAIT_L(n) asm volatile("s_waitcnt lgkmcnt(" #n ")" ::: "memory")
; #define PG8_BAR __builtin_amdgcn_s_barrier()
; #define PG8_SCHED __builtin_amdgcn_sched_barrier(0)
; template <class Epi, class Sched, bool ALIGN_EPI = false, bool SP2 = false>
; __device__ __forceinline__ void gemm_phase(PG8_LAS unsigned char* lds, const Gemm g, const Sched& S, const Epi& E, int wid) {
;     ...
;             PG8_WAIT_V(8); PG8_WAIT_L(0); PG8_BAR; PG8_MMA(1, 0, At, B0); PG8_MMA(1, 1, At, B1); PG8_BAR; PG8_SCHED;
;             PG8_LDB(B0, 1, 0); PG8_LDB(B1, 1, 1); PG8_SCHED; PG8_LDA(At, 1, 0); PG8_STAGE(PG8_SA(0, 1), a2 + hstepA, voffA);
;             PG8_WAIT_V(8); PG8_WAIT_L(0); PG8_BAR; PG8_MMA(0, 0, At, B0); PG8_MMA(0, 1, At, B1); PG8_BAR; PG8_SCHED;
;             PG8_LDA(At, 1, 1); PG8_STAGE_NT(PG8_SB(1, 0), b3, voffB); PG8_STAGE_NT(PG8_SB(1, 1), b3 + hstepB, voffB); PG8_STAGE(PG8_SA(1, 0), a3, voffA);
	s_setprio 1
	s_waitcnt lgkmcnt(0)
	v_mfma_f32_16x16x32_bf16 v[60:63], v[146:149], v[178:181], v[60:63]
	v_mfma_f32_16x16x32_bf16 v[56:59], v[154:157], v[178:181], v[56:59]
	v_mfma_f32_16x16x32_bf16 v[44:47], v[146:149], v[186:189], v[44:47]
	v_mfma_f32_16x16x32_bf16 v[40:43], v[154:157], v[186:189], v[40:43]
	v_mfma_f32_16x16x32_bf16 v[28:31], v[146:149], v[194:197], v[28:31]
	v_mfma_f32_16x16x32_bf16 v[24:27], v[154:157], v[194:197], v[24:27]
	v_mfma_f32_16x16x32_bf16 v[12:15], v[146:149], v[202:205], v[12:15]
	v_mfma_f32_16x16x32_bf16 v[8:11], v[154:157], v[202:205], v[8:11]
	v_mfma_f32_16x16x32_bf16 v[60:63], v[150:153], v[182:185], v[60:63]
	v_mfma_f32_16x16x32_bf16 v[56:59], v[158:161], v[182:185], v[56:59]
	v_mfma_f32_16x16x32_bf16 v[44:47], v[150:153], v[190:193], v[44:47]
	v_mfma_f32_16x16x32_bf16 v[40:43], v[158:161], v[190:193], v[40:43]
	v_mfma_f32_16x16x32_bf16 v[28:31], v[150:153], v[198:201], v[28:31]
	v_mfma_f32_16x16x32_bf16 v[24:27], v[158:161], v[198:201], v[24:27]
	v_mfma_f32_16x16x32_bf16 v[12:15], v[150:153], v[208:211], v[12:15]
	v_mfma_f32_16x16x32_bf16 v[8:11], v[158:161], v[208:211], v[8:11]
	s_setprio 0
	s_setprio 1
	v_mfma_f32_16x16x32_bf16 v[52:55], v[162:165], v[178:181], v[52:55]
	v_mfma_f32_16x16x32_bf16 v[48:51], v[170:173], v[178:181], v[48:51]
	v_mfma_f32_16x16x32_bf16 v[36:39], v[162:165], v[186:189], v[36:39]
	v_mfma_f32_16x16x32_bf16 v[32:35], v[170:173], v[186:189], v[32:35]
	v_mfma_f32_16x16x32_bf16 v[20:23], v[162:165], v[194:197], v[20:23]
	v_mfma_f32_16x16x32_bf16 v[16:19], v[170:173], v[194:197], v[16:19]
	v_mfma_f32_16x16x32_bf16 v[4:7], v[162:165], v[202:205], v[4:7]
	v_mfma_f32_16x16x32_bf16 v[0:3], v[170:173], v[202:205], v[0:3]
	v_mfma_f32_16x16x32_bf16 v[52:55], v[166:169], v[182:185], v[52:55]
	v_mfma_f32_16x16x32_bf16 v[48:51], v[174:177], v[182:185], v[48:51]
	v_mfma_f32_16x16x32_bf16 v[36:39], v[166:169], v[190:193], v[36:39]
	v_mfma_f32_16x16x32_bf16 v[32:35], v[174:177], v[190:193], v[32:35]
	v_mfma_f32_16x16x32_bf16 v[20:23], v[166:169], v[198:201], v[20:23]
	v_mfma_f32_16x16x32_bf16 v[16:19], v[174:177], v[198:201], v[16:19]
	v_mfma_f32_16x16x32_bf16 v[4:7], v[166:169], v[208:211], v[4:7]
	v_mfma_f32_16x16x32_bf16 v[0:3], v[174:177], v[208:211], v[0:3]
	s_setprio 0
	s_barrier
	ds_read_b128 v[146:149], v144
	ds_read_b128 v[150:153], v144 offset:1024
	ds_read_b128 v[154:157], v144 offset:2048
	ds_read_b128 v[158:161], v144 offset:3072
	ds_read_b128 v[162:165], v145
	ds_read_b128 v[166:169], v145 offset:1024
	ds_read_b128 v[170:173], v145 offset:2048
	ds_read_b128 v[174:177], v145 offset:3072
	s_add_u32 s48, s48, 0x2b4000
	s_addc_u32 s49, s49, 0
	s_mov_b32 m0, s22
	v_lshl_add_u64 v[220:221], s[48:49], 0, v[128:129]
	ds_read_b128 v[178:181], v143 offset:32768
	ds_read_b128 v[182:185], v143 offset:33792
	ds_read_b128 v[186:189], v143 offset:34816
	ds_read_b128 v[190:193], v143 offset:35840
	ds_read_b128 v[194:197], v143 offset:36864
	ds_read_b128 v[198:201], v143 offset:37888
	ds_read_b128 v[202:205], v143 offset:38912
	ds_read_b128 v[208:211], v143 offset:39936
	global_load_lds_dwordx4 v[220:221], off
	v_lshl_add_u64 v[220:221], s[48:49], 0, v[132:133]
	s_mov_b32 m0, s23
	s_nop 0
	global_load_lds_dwordx4 v[220:221], off
	s_nop 0
	s_waitcnt vmcnt(8)
	s_waitcnt lgkmcnt(0)
	s_barrier
	s_setprio 1
	s_waitcnt lgkmcnt(0)
	v_mfma_f32_16x16x32_bf16 v[124:127], v[146:149], v[178:181], v[124:127]
	v_mfma_f32_16x16x32_bf16 v[120:123], v[154:157], v[178:181], v[120:123]
	v_mfma_f32_16x16x32_bf16 v[108:111], v[146:149], v[186:189], v[108:111]
	v_mfma_f32_16x16x32_bf16 v[104:107], v[154:157], v[186:189], v[104:107]
	v_mfma_f32_16x16x32_bf16 v[92:95], v[146:149], v[194:197], v[92:95]
	v_mfma_f32_16x16x32_bf16 v[88:91], v[154:157], v[194:197], v[88:91]
	v_mfma_f32_16x16x32_bf16 v[76:79], v[146:149], v[202:205], v[76:79]
	v_mfma_f32_16x16x32_bf16 v[72:75], v[154:157], v[202:205], v[72:75]
	v_mfma_f32_16x16x32_bf16 v[124:127], v[150:153], v[182:185], v[124:127]
	v_mfma_f32_16x16x32_bf16 v[120:123], v[158:161], v[182:185], v[120:123]
	v_mfma_f32_16x16x32_bf16 v[108:111], v[150:153], v[190:193], v[108:111]
	v_mfma_f32_16x16x32_bf16 v[104:107], v[158:161], v[190:193], v[104:107]
	v_mfma_f32_16x16x32_bf16 v[92:95], v[150:153], v[198:201], v[92:95]
	v_mfma_f32_16x16x32_bf16 v[88:91], v[158:161], v[198:201], v[88:91]
	v_mfma_f32_16x16x32_bf16 v[76:79], v[150:153], v[208:211], v[76:79]
	v_mfma_f32_16x16x32_bf16 v[72:75], v[158:161], v[208:211], v[72:75]
	s_setprio 0
	s_setprio 1
	v_mfma_f32_16x16x32_bf16 v[116:119], v[162:165], v[178:181], v[116:119]
	v_mfma_f32_16x16x32_bf16 v[112:115], v[170:173], v[178:181], v[112:115]
	v_mfma_f32_16x16x32_bf16 v[100:103], v[162:165], v[186:189], v[100:103]
	v_mfma_f32_16x16x32_bf16 v[96:99], v[170:173], v[186:189], v[96:99]
	v_mfma_f32_16x16x32_bf16 v[84:87], v[162:165], v[194:197], v[84:87]
	v_mfma_f32_16x16x32_bf16 v[80:83], v[170:173], v[194:197], v[80:83]
	v_mfma_f32_16x16x32_bf16 v[68:71], v[162:165], v[202:205], v[68:71]
	v_mfma_f32_16x16x32_bf16 v[64:67], v[170:173], v[202:205], v[64:67]
	v_mfma_f32_16x16x32_bf16 v[116:119], v[166:169], v[182:185], v[116:119]
	v_mfma_f32_16x16x32_bf16 v[112:115], v[174:177], v[182:185], v[112:115]
	v_mfma_f32_16x16x32_bf16 v[100:103], v[166:169], v[190:193], v[100:103]
	v_mfma_f32_16x16x32_bf16 v[96:99], v[174:177], v[190:193], v[96:99]
	v_mfma_f32_16x16x32_bf16 v[84:87], v[166:169], v[198:201], v[84:87]
	v_mfma_f32_16x16x32_bf16 v[80:83], v[174:177], v[198:201], v[80:83]
	v_mfma_f32_16x16x32_bf16 v[68:71], v[166:169], v[208:211], v[68:71]
	v_mfma_f32_16x16x32_bf16 v[64:67], v[174:177], v[208:211], v[64:67]
	s_setprio 0
	s_barrier
; #define PG8_STAGE(bufoff, gbase, voff) do { _Pragma("unroll") for (int _i = 0; _i < 2; ++_i) \
;         __builtin_amdgcn_global_load_lds((const unsigned*)((const char*)(gbase) + (voff)[_i]), (PG8_LAS unsigned*)(lds + (bufoff) + ldsw + _i * 8192), 16, 0, 0); } while (0)
; #define PG8_STAGE_NT(bufoff, gbase, voff) do { _Pragma("unroll") for (int _i = 0; _i < 2; ++_i) \
;         __builtin_amdgcn_global_load_lds((const unsigned*)((const char*)(gbase) + (voff)[_i]), (PG8_LAS unsigned*)(lds + (bufoff) + ldsw + _i * 8192), 16, 0, PG8_B_AUX); } while (0)
; #define PG8_LDA(dst, b, h) do { _Pragma("unroll") for (int m = 0; m < 4; ++m) _Pragma("unroll") for (int k = 0; k < 2; ++k) dst[m][k] = *(const PG8_LAS bf16x8*)(lds + PG8_SA(b, h) + aoff + m * 2048 + k * 1024); } while (0)
; #define PG8_MMA(ai, bj, At, Bt) do { __builtin_amdgcn_s_setprio(1); _Pragma("unroll") for (int m = 0; m < 4; ++m) _Pragma("unroll") for (int n = 0; n < 2; ++n) _Pragma("unroll") for (int k = 0; k < 2; ++k) \
;         acc[ai][bj][m][n] = __builtin_amdgcn_mfma_f32_16x16x32_bf16(Bt[n][k], At[m][k], acc[ai][bj][m][n], 0, 0, 0); __builtin_amdgcn_s_setprio(0); } while (0)
; #define PG8_WAIT_V(n) asm volatile("s_waitcnt vmcnt(" #n ")" ::: "memory")
; #define PG8_WAIT_L(n) asm volatile("s_waitcnt lgkmcnt(" #n ")" ::: "memory")
; #define PG8_BAR __builtin_amdgcn_s_barrier()
; #define PG8_SCHED __builtin_amdgcn_sched_barrier(0)
; template <class Epi, class Sched, bool ALIGN_EPI = false, bool SP2 = false>
; __device__ __forceinline__ void gemm_phase(PG8_LAS unsigned char* lds, const Gemm g, const Sched& S, const Epi& E, int wid) {
;     ...
;             PG8_LDA(At, 1, 1); PG8_STAGE_NT(PG8_SB(1, 0), b3, voffB); PG8_STAGE_NT(PG8_SB(1, 1), b3 + hstepB, voffB); PG8_STAGE(PG8_SA(1, 0), a3, voffA);
;             PG8_WAIT_V(8); PG8_WAIT_L(0); PG8_BAR; PG8_MMA(1, 0, At, B0); PG8_MMA(1, 1, At, B1); PG8_BAR; PG8_SCHED;
;     ...
;     PG8_WAIT_V(0);
;     if constexpr (!ALIGN_EPI) { if (wr == 0) PG8_BAR; }
;     PG8_BAR;
	s_mov_b32 m0, s63
	v_lshl_add_u64 v[212:213], v[212:213], 0, s[4:5]
	s_add_u32 s46, s46, 0x2b4080
	ds_read_b128 v[178:181], v143 offset:49152
	ds_read_b128 v[182:185], v143 offset:50176
	ds_read_b128 v[186:189], v143 offset:51200
	ds_read_b128 v[190:193], v143 offset:52224
	ds_read_b128 v[194:197], v143 offset:53248
	ds_read_b128 v[198:201], v143 offset:54272
	ds_read_b128 v[202:205], v143 offset:55296
	ds_read_b128 v[208:211], v143 offset:56320
	global_load_lds_dwordx4 v[212:213], off
	v_lshl_add_u64 v[212:213], v[214:215], 0, s[4:5]
	s_mov_b32 m0, s64
	s_addc_u32 s47, s47, 0
	global_load_lds_dwordx4 v[212:213], off
	v_lshl_add_u64 v[212:213], s[46:47], 0, v[130:131]
	s_mov_b32 m0, s65
	s_nop 0
	global_load_lds_dwordx4 v[212:213], off
	v_lshl_add_u64 v[212:213], s[46:47], 0, v[134:135]
	s_mov_b32 m0, s66
	s_nop 0
	global_load_lds_dwordx4 v[212:213], off
	v_lshl_add_u64 v[212:213], v[216:217], 0, s[4:5]
	s_mov_b32 m0, s25
	s_nop 0
	global_load_lds_dwordx4 v[212:213], off
	v_lshl_add_u64 v[212:213], v[218:219], 0, s[4:5]
	s_mov_b32 m0, s56
	s_nop 0
	global_load_lds_dwordx4 v[212:213], off
	s_waitcnt vmcnt(8)
	s_waitcnt lgkmcnt(0)
	s_barrier
	s_setprio 1
	s_waitcnt lgkmcnt(0)
	v_mfma_f32_16x16x32_bf16 v[60:63], v[146:149], v[178:181], v[60:63]
	v_mfma_f32_16x16x32_bf16 v[56:59], v[154:157], v[178:181], v[56:59]
	v_mfma_f32_16x16x32_bf16 v[44:47], v[146:149], v[186:189], v[44:47]
	v_mfma_f32_16x16x32_bf16 v[40:43], v[154:157], v[186:189], v[40:43]
	v_mfma_f32_16x16x32_bf16 v[28:31], v[146:149], v[194:197], v[28:31]
	v_mfma_f32_16x16x32_bf16 v[24:27], v[154:157], v[194:197], v[24:27]
	v_mfma_f32_16x16x32_bf16 v[12:15], v[146:149], v[202:205], v[12:15]
	v_mfma_f32_16x16x32_bf16 v[8:11], v[154:157], v[202:205], v[8:11]
	v_mfma_f32_16x16x32_bf16 v[60:63], v[150:153], v[182:185], v[60:63]
	v_mfma_f32_16x16x32_bf16 v[56:59], v[158:161], v[182:185], v[56:59]
	v_mfma_f32_16x16x32_bf16 v[44:47], v[150:153], v[190:193], v[44:47]
	v_mfma_f32_16x16x32_bf16 v[40:43], v[158:161], v[190:193], v[40:43]
	v_mfma_f32_16x16x32_bf16 v[28:31], v[150:153], v[198:201], v[28:31]
	v_mfma_f32_16x16x32_bf16 v[24:27], v[158:161], v[198:201], v[24:27]
	v_mfma_f32_16x16x32_bf16 v[12:15], v[150:153], v[208:211], v[12:15]
	v_mfma_f32_16x16x32_bf16 v[8:11], v[158:161], v[208:211], v[8:11]
	s_setprio 0
	s_setprio 1
	v_mfma_f32_16x16x32_bf16 v[52:55], v[162:165], v[178:181], v[52:55]
	v_mfma_f32_16x16x32_bf16 v[48:51], v[170:173], v[178:181], v[48:51]
	v_mfma_f32_16x16x32_bf16 v[36:39], v[162:165], v[186:189], v[36:39]
	v_mfma_f32_16x16x32_bf16 v[32:35], v[170:173], v[186:189], v[32:35]
	v_mfma_f32_16x16x32_bf16 v[20:23], v[162:165], v[194:197], v[20:23]
	v_mfma_f32_16x16x32_bf16 v[16:19], v[170:173], v[194:197], v[16:19]
	v_mfma_f32_16x16x32_bf16 v[4:7], v[162:165], v[202:205], v[4:7]
	v_mfma_f32_16x16x32_bf16 v[0:3], v[170:173], v[202:205], v[0:3]
	v_mfma_f32_16x16x32_bf16 v[52:55], v[166:169], v[182:185], v[52:55]
	v_mfma_f32_16x16x32_bf16 v[48:51], v[174:177], v[182:185], v[48:51]
	v_mfma_f32_16x16x32_bf16 v[36:39], v[166:169], v[190:193], v[36:39]
	v_mfma_f32_16x16x32_bf16 v[32:35], v[174:177], v[190:193], v[32:35]
	v_mfma_f32_16x16x32_bf16 v[20:23], v[166:169], v[198:201], v[20:23]
	v_mfma_f32_16x16x32_bf16 v[16:19], v[174:177], v[198:201], v[16:19]
	v_mfma_f32_16x16x32_bf16 v[4:7], v[166:169], v[208:211], v[4:7]
	v_mfma_f32_16x16x32_bf16 v[0:3], v[174:177], v[208:211], v[0:3]
	s_setprio 0
	s_barrier
	s_add_i32 s52, s52, 2
	s_add_u32 s50, s50, 0x100
	s_addc_u32 s51, s51, 0
	s_add_u32 s44, s44, 0x100
	s_addc_u32 s45, s45, 0
	v_lshl_add_u64 v[136:137], v[136:137], 0, s[42:43]
	s_cmpk_lt_u32 s52, 0xaa
	v_lshl_add_u64 v[138:139], v[138:139], 0, s[42:43]
	s_cbranch_scc1 .LBB0_1249
	s_waitcnt vmcnt(0)
	s_cmpk_lt_u32 s95, 0x100
	s_cselect_b64 s[44:45], -1, 0
	s_cmpk_gt_u32 s95, 0xff
	s_cbranch_scc1 .LBB0_1252
	s_barrier

; #define PG8_STAGE(bufoff, gbase, voff) do { _Pragma("unroll") for (int _i = 0; _i < 2; ++_i) \
;         __builtin_amdgcn_global_load_lds((const unsigned*)((const char*)(gbase) + (voff)[_i]), (PG8_LAS unsigned*)(lds + (bufoff) + ldsw + _i * 8192), 16, 0, 0); } while (0)
; #define PG8_STAGE_NT(bufoff, gbase, voff) do { _Pragma("unroll") for (int _i = 0; _i < 2; ++_i) \
;         __builtin_amdgcn_global_load_lds((const unsigned*)((const char*)(gbase) + (voff)[_i]), (PG8_LAS unsigned*)(lds + (bufoff) + ldsw + _i * 8192), 16, 0, PG8_B_AUX); } while (0)
; #define PG8_LDA(dst, b, h) do { _Pragma("unroll") for (int m = 0; m < 4; ++m) _Pragma("unroll") for (int k = 0; k < 2; ++k) dst[m][k] = *(const PG8_LAS bf16x8*)(lds + PG8_SA(b, h) + aoff + m * 2048 + k * 1024); } while (0)
; #define PG8_LDB(dst, b, h) do { _Pragma("unroll") for (int n = 0; n < 2; ++n) _Pragma("unroll") for (int k = 0; k < 2; ++k) dst[n][k] = *(const PG8_LAS bf16x8*)(lds + PG8_SB(b, h) + boff + n * 2048 + k * 1024); } while (0)
; #define PG8_WAIT_V(n) asm volatile("s_waitcnt vmcnt(" #n ")" ::: "memory")
; #define PG8_WAIT_L(n) asm volatile("s_waitcnt lgkmcnt(" #n ")" ::: "memory")
; #define PG8_BAR __builtin_amdgcn_s_barrier()
; #define PG8_SCHED __builtin_amdgcn_sched_barrier(0)
; template <class Epi, class Sched, bool ALIGN_EPI = false, bool SP2 = false>
; __device__ __forceinline__ void gemm_phase(PG8_LAS unsigned char* lds, const Gemm g, const Sched& S, const Epi& E, int wid) {
;     ...
;             const bool last = (t == nt - 2);
;             const char* a1 = cA + (size_t)(t + 1) * kstep;
;             const char* a2 = last ? nA : cA + (size_t)(t + 2) * kstep; const char* b2 = last ? nB : cB + (size_t)(t + 2) * kstep;
;             const char* a3 = a2 + kstep; const char* b3 = b2 + kstep;
;             if (last && has_next) S.a_ready(nxt);
;             if constexpr (SP2) {
;             PG8_LDB(B0, 0, 0); PG8_LDB(B1, 0, 1); PG8_SCHED; PG8_LDA(At, 0, 0); PG8_STAGE(PG8_SA(1, 1), a1 + hstepA, voffA);
;             PG8_WAIT_V(8); PG8_WAIT_L(0); PG8_BAR; PG8_MMA(0, 0, At, B0); PG8_MMA(0, 1, At, B1); PG8_BAR; PG8_SCHED;
;             PG8_LDA(At, 0, 1); PG8_STAGE_NT(PG8_SB(0, 0), b2, voffB); PG8_STAGE_NT(PG8_SB(0, 1), b2 + hstepB, voffB); PG8_STAGE(PG8_SA(0, 0), a2, voffA);
;             PG8_WAIT_V(8); PG8_WAIT_L(0); PG8_BAR; PG8_MMA(1, 0, At, B0); PG8_MMA(1, 1, At, B1); PG8_BAR; PG8_SCHED;
.LBB0_1307:
	ds_read_b128 v[146:149], v141
	ds_read_b128 v[150:153], v141 offset:1024
	ds_read_b128 v[154:157], v141 offset:2048
	ds_read_b128 v[158:161], v141 offset:3072
	ds_read_b128 v[162:165], v142
	ds_read_b128 v[166:169], v142 offset:1024
	ds_read_b128 v[170:173], v142 offset:2048
	ds_read_b128 v[174:177], v142 offset:3072
	s_add_u32 s30, s14, s21
	s_addc_u32 s31, s15, s40
	s_add_u32 s48, s14, s8
	s_addc_u32 s49, s15, s9
	s_cmpk_eq_i32 s41, 0xa8
	s_cselect_b32 s39, s3, s31
	s_cselect_b32 s38, s2, s30
	s_cselect_b32 s31, s11, s49
	s_cselect_b32 s30, s10, s48
	s_mov_b32 m0, s57
	v_lshl_add_u64 v[202:203], s[14:15], 0, v[136:137]
	ds_read_b128 v[178:181], v143
	ds_read_b128 v[182:185], v143 offset:1024
	ds_read_b128 v[186:189], v143 offset:2048
	ds_read_b128 v[190:193], v143 offset:3072
	ds_read_b128 v[194:197], v143 offset:4096
	ds_read_b128 v[198:201], v143 offset:5120
	ds_read_b128 v[208:211], v143 offset:6144
	ds_read_b128 v[212:215], v143 offset:7168
	global_load_lds_dwordx4 v[202:203], off
	v_lshl_add_u64 v[202:203], s[14:15], 0, v[138:139]
	s_mov_b32 m0, s58
	s_nop 0
	global_load_lds_dwordx4 v[202:203], off
	s_waitcnt vmcnt(8)
	s_waitcnt lgkmcnt(0)
	s_barrier
	s_setprio 1
	s_waitcnt lgkmcnt(0)
	v_mfma_f32_16x16x32_bf16 v[124:127], v[146:149], v[178:181], v[124:127]
	v_mfma_f32_16x16x32_bf16 v[120:123], v[154:157], v[178:181], v[120:123]
	v_mfma_f32_16x16x32_bf16 v[108:111], v[146:149], v[186:189], v[108:111]
	v_mfma_f32_16x16x32_bf16 v[104:107], v[154:157], v[186:189], v[104:107]
	v_mfma_f32_16x16x32_bf16 v[92:95], v[146:149], v[194:197], v[92:95]
	v_mfma_f32_16x16x32_bf16 v[88:91], v[154:157], v[194:197], v[88:91]
	v_mfma_f32_16x16x32_bf16 v[76:79], v[146:149], v[208:211], v[76:79]
	v_mfma_f32_16x16x32_bf16 v[72:75], v[154:157], v[208:211], v[72:75]
	v_mfma_f32_16x16x32_bf16 v[124:127], v[150:153], v[182:185], v[124:127]
	v_mfma_f32_16x16x32_bf16 v[120:123], v[158:161], v[182:185], v[120:123]
	v_mfma_f32_16x16x32_bf16 v[108:111], v[150:153], v[190:193], v[108:111]
	v_mfma_f32_16x16x32_bf16 v[104:107], v[158:161], v[190:193], v[104:107]
	v_mfma_f32_16x16x32_bf16 v[92:95], v[150:153], v[198:201], v[92:95]
	v_mfma_f32_16x16x32_bf16 v[88:91], v[158:161], v[198:201], v[88:91]
	v_mfma_f32_16x16x32_bf16 v[76:79], v[150:153], v[212:215], v[76:79]
	v_mfma_f32_16x16x32_bf16 v[72:75], v[158:161], v[212:215], v[72:75]
	s_setprio 0
	s_setprio 1
	v_mfma_f32_16x16x32_bf16 v[116:119], v[162:165], v[178:181], v[116:119]
	v_mfma_f32_16x16x32_bf16 v[112:115], v[170:173], v[178:181], v[112:115]
	v_mfma_f32_16x16x32_bf16 v[100:103], v[162:165], v[186:189], v[100:103]
	v_mfma_f32_16x16x32_bf16 v[96:99], v[170:173], v[186:189], v[96:99]
	v_mfma_f32_16x16x32_bf16 v[84:87], v[162:165], v[194:197], v[84:87]
	v_mfma_f32_16x16x32_bf16 v[80:83], v[170:173], v[194:197], v[80:83]
	v_mfma_f32_16x16x32_bf16 v[68:71], v[162:165], v[208:211], v[68:71]
	v_mfma_f32_16x16x32_bf16 v[64:67], v[170:173], v[208:211], v[64:67]
	v_mfma_f32_16x16x32_bf16 v[116:119], v[166:169], v[182:185], v[116:119]
	v_mfma_f32_16x16x32_bf16 v[112:115], v[174:177], v[182:185], v[112:115]
	v_mfma_f32_16x16x32_bf16 v[100:103], v[166:169], v[190:193], v[100:103]
	v_mfma_f32_16x16x32_bf16 v[96:99], v[174:177], v[190:193], v[96:99]
	v_mfma_f32_16x16x32_bf16 v[84:87], v[166:169], v[198:201], v[84:87]
	v_mfma_f32_16x16x32_bf16 v[80:83], v[174:177], v[198:201], v[80:83]
	v_mfma_f32_16x16x32_bf16 v[68:71], v[166:169], v[212:215], v[68:71]
	v_mfma_f32_16x16x32_bf16 v[64:67], v[174:177], v[212:215], v[64:67]
	s_setprio 0
	s_barrier
	s_mov_b32 m0, s59
	v_lshl_add_u64 v[202:203], s[30:31], 0, v[130:131]
	s_add_u32 s48, s30, 0x2b4000
	ds_read_b128 v[178:181], v143 offset:16384
	ds_read_b128 v[182:185], v143 offset:17408
	ds_read_b128 v[186:189], v143 offset:18432
	ds_read_b128 v[190:193], v143 offset:19456
	ds_read_b128 v[194:197], v143 offset:20480
	ds_read_b128 v[198:201], v143 offset:21504
	ds_read_b128 v[208:211], v143 offset:22528
	ds_read_b128 v[212:215], v143 offset:23552
	global_load_lds_dwordx4 v[202:203], off
	v_lshl_add_u64 v[216:217], s[30:31], 0, v[134:135]
	s_mov_b32 m0, s60
	s_addc_u32 s49, s31, 0
	global_load_lds_dwordx4 v[216:217], off
	v_lshl_add_u64 v[218:219], s[48:49], 0, v[130:131]
	s_mov_b32 m0, s61
	v_lshl_add_u64 v[220:221], s[38:39], 0, v[132:133]
	global_load_lds_dwordx4 v[218:219], off
	v_lshl_add_u64 v[218:219], s[48:49], 0, v[134:135]
	s_mov_b32 m0, s62
	s_nop 0
	global_load_lds_dwordx4 v[218:219], off
	v_lshl_add_u64 v[218:219], s[38:39], 0, v[128:129]
	s_mov_b32 m0, s17
	s_nop 0
	global_load_lds_dwordx4 v[218:219], off
	s_mov_b32 m0, s19
	s_nop 0
	global_load_lds_dwordx4 v[220:221], off
	s_nop 0
	s_waitcnt vmcnt(8)
	s_waitcnt lgkmcnt(0)
	s_barrier
; #define PG8_STAGE(bufoff, gbase, voff) do { _Pragma("unroll") for (int _i = 0; _i < 2; ++_i) \
;         __builtin_amdgcn_global_load_lds((const unsigned*)((const char*)(gbase) + (voff)[_i]), (PG8_LAS unsigned*)(lds + (bufoff) + ldsw + _i * 8192), 16, 0, 0); } while (0)
; #define PG8_STAGE_NT(bufoff, gbase, voff) do { _Pragma("unroll") for (int _i = 0; _i < 2; ++_i) \
;         __builtin_amdgcn_global_load_lds((const unsigned*)((const char*)(gbase) + (voff)[_i]), (PG8_LAS unsigned*)(lds + (bufoff) + ldsw + _i * 8192), 16, 0, PG8_B_AUX); } while (0)
; #define PG8_LDA(dst, b, h) do { _Pragma("unroll") for (int m = 0; m < 4; ++m) _Pragma("unroll") for (int k = 0; k < 2; ++k) dst[m][k] = *(const PG8_LAS bf16x8*)(lds + PG8_SA(b, h) + aoff + m * 2048 + k * 1024); } while (0)
; #define PG8_LDB(dst, b, h) do { _Pragma("unroll") for (int n = 0; n < 2; ++n) _Pragma("unroll") for (int k = 0; k < 2; ++k) dst[n][k] = *(const PG8_LAS bf16x8*)(lds + PG8_SB(b, h) + boff + n * 2048 + k * 1024); } while (0)
; #define PG8_MMA(ai, bj, At, Bt) do { __builtin_amdgcn_s_setprio(1); _Pragma("unroll") for (int m = 0; m < 4; ++m) _Pragma("unroll") for (int n = 0; n < 2; ++n) _Pragma("unroll") for (int k = 0; k < 2; ++k) \
;         acc[ai][bj][m][n] = __builtin_amdgcn_mfma_f32_16x16x32_bf16(Bt[n][k], At[m][k], acc[ai][bj][m][n], 0, 0, 0); __builtin_amdgcn_s_setprio(0); } while (0)
; #define PG8_WAIT_V(n) asm volatile("s_waitcnt vmcnt(" #n ")" ::: "memory")
; #define PG8_WAIT_L(n) asm volatile("s_waitcnt lgkmcnt(" #n ")" ::: "memory")
; #define PG8_BAR __builtin_amdgcn_s_barrier()
; #define PG8_SCHED __builtin_amdgcn_sched_barrier(0)
; template <class Epi, class Sched, bool ALIGN_EPI = false, bool SP2 = false>
; __device__ __forceinline__ void gemm_phase(PG8_LAS unsigned char* lds, const Gemm g, const Sched& S, const Epi& E, int wid) {
;     ...
;             PG8_WAIT_V(8); PG8_WAIT_L(0); PG8_BAR; PG8_MMA(1, 0, At, B0); PG8_MMA(1, 1, At, B1); PG8_BAR; PG8_SCHED;
;             PG8_LDB(B0, 1, 0); PG8_LDB(B1, 1, 1); PG8_SCHED; PG8_LDA(At, 1, 0); PG8_STAGE(PG8_SA(0, 1), a2 + hstepA, voffA);
;             PG8_WAIT_V(8); PG8_WAIT_L(0); PG8_BAR; PG8_MMA(0, 0, At, B0); PG8_MMA(0, 1, At, B1); PG8_BAR; PG8_SCHED;
;             PG8_LDA(At, 1, 1); PG8_STAGE_NT(PG8_SB(1, 0), b3, voffB); PG8_STAGE_NT(PG8_SB(1, 1), b3 + hstepB, voffB); PG8_STAGE(PG8_SA(1, 0), a3, voffA);
	s_setprio 1
	s_waitcnt lgkmcnt(0)
	v_mfma_f32_16x16x32_bf16 v[60:63], v[146:149], v[178:181], v[60:63]
	v_mfma_f32_16x16x32_bf16 v[56:59], v[154:157], v[178:181], v[56:59]
	v_mfma_f32_16x16x32_bf16 v[44:47], v[146:149], v[186:189], v[44:47]
	v_mfma_f32_16x16x32_bf16 v[40:43], v[154:157], v[186:189], v[40:43]
	v_mfma_f32_16x16x32_bf16 v[28:31], v[146:149], v[194:197], v[28:31]
	v_mfma_f32_16x16x32_bf16 v[24:27], v[154:157], v[194:197], v[24:27]
	v_mfma_f32_16x16x32_bf16 v[12:15], v[146:149], v[208:211], v[12:15]
	v_mfma_f32_16x16x32_bf16 v[8:11], v[154:157], v[208:211], v[8:11]
	v_mfma_f32_16x16x32_bf16 v[60:63], v[150:153], v[182:185], v[60:63]
	v_mfma_f32_16x16x32_bf16 v[56:59], v[158:161], v[182:185], v[56:59]
	v_mfma_f32_16x16x32_bf16 v[44:47], v[150:153], v[190:193], v[44:47]
	v_mfma_f32_16x16x32_bf16 v[40:43], v[158:161], v[190:193], v[40:43]
	v_mfma_f32_16x16x32_bf16 v[28:31], v[150:153], v[198:201], v[28:31]
	v_mfma_f32_16x16x32_bf16 v[24:27], v[158:161], v[198:201], v[24:27]
	v_mfma_f32_16x16x32_bf16 v[12:15], v[150:153], v[212:215], v[12:15]
	v_mfma_f32_16x16x32_bf16 v[8:11], v[158:161], v[212:215], v[8:11]
	s_setprio 0
	s_setprio 1
	v_mfma_f32_16x16x32_bf16 v[52:55], v[162:165], v[178:181], v[52:55]
	v_mfma_f32_16x16x32_bf16 v[48:51], v[170:173], v[178:181], v[48:51]
	v_mfma_f32_16x16x32_bf16 v[36:39], v[162:165], v[186:189], v[36:39]
	v_mfma_f32_16x16x32_bf16 v[32:35], v[170:173], v[186:189], v[32:35]
	v_mfma_f32_16x16x32_bf16 v[20:23], v[162:165], v[194:197], v[20:23]
	v_mfma_f32_16x16x32_bf16 v[16:19], v[170:173], v[194:197], v[16:19]
	v_mfma_f32_16x16x32_bf16 v[4:7], v[162:165], v[208:211], v[4:7]
	v_mfma_f32_16x16x32_bf16 v[0:3], v[170:173], v[208:211], v[0:3]
	v_mfma_f32_16x16x32_bf16 v[52:55], v[166:169], v[182:185], v[52:55]
	v_mfma_f32_16x16x32_bf16 v[48:51], v[174:177], v[182:185], v[48:51]
	v_mfma_f32_16x16x32_bf16 v[36:39], v[166:169], v[190:193], v[36:39]
	v_mfma_f32_16x16x32_bf16 v[32:35], v[174:177], v[190:193], v[32:35]
	v_mfma_f32_16x16x32_bf16 v[20:23], v[166:169], v[198:201], v[20:23]
	v_mfma_f32_16x16x32_bf16 v[16:19], v[174:177], v[198:201], v[16:19]
	v_mfma_f32_16x16x32_bf16 v[4:7], v[166:169], v[212:215], v[4:7]
	v_mfma_f32_16x16x32_bf16 v[0:3], v[174:177], v[212:215], v[0:3]
	s_setprio 0
	s_barrier
	ds_read_b128 v[146:149], v144
	ds_read_b128 v[150:153], v144 offset:1024
	ds_read_b128 v[154:157], v144 offset:2048
	ds_read_b128 v[158:161], v144 offset:3072
	ds_read_b128 v[162:165], v145
	ds_read_b128 v[166:169], v145 offset:1024
	ds_read_b128 v[170:173], v145 offset:2048
	ds_read_b128 v[174:177], v145 offset:3072
	s_add_u32 s38, s38, 0x2b4000
	s_addc_u32 s39, s39, 0
	s_mov_b32 m0, s22
	v_lshl_add_u64 v[222:223], s[38:39], 0, v[128:129]
	ds_read_b128 v[178:181], v143 offset:32768
	ds_read_b128 v[182:185], v143 offset:33792
	ds_read_b128 v[186:189], v143 offset:34816
	ds_read_b128 v[190:193], v143 offset:35840
	ds_read_b128 v[194:197], v143 offset:36864
	ds_read_b128 v[198:201], v143 offset:37888
	ds_read_b128 v[208:211], v143 offset:38912
	ds_read_b128 v[212:215], v143 offset:39936
	global_load_lds_dwordx4 v[222:223], off
	v_lshl_add_u64 v[222:223], s[38:39], 0, v[132:133]
	s_mov_b32 m0, s23
	s_nop 0
	global_load_lds_dwordx4 v[222:223], off
	s_nop 0
	s_waitcnt vmcnt(8)
	s_waitcnt lgkmcnt(0)
	s_barrier
	s_setprio 1
	s_waitcnt lgkmcnt(0)
	v_mfma_f32_16x16x32_bf16 v[124:127], v[146:149], v[178:181], v[124:127]
	v_mfma_f32_16x16x32_bf16 v[120:123], v[154:157], v[178:181], v[120:123]
	v_mfma_f32_16x16x32_bf16 v[108:111], v[146:149], v[186:189], v[108:111]
	v_mfma_f32_16x16x32_bf16 v[104:107], v[154:157], v[186:189], v[104:107]
	v_mfma_f32_16x16x32_bf16 v[92:95], v[146:149], v[194:197], v[92:95]
	v_mfma_f32_16x16x32_bf16 v[88:91], v[154:157], v[194:197], v[88:91]
	v_mfma_f32_16x16x32_bf16 v[76:79], v[146:149], v[208:211], v[76:79]
	v_mfma_f32_16x16x32_bf16 v[72:75], v[154:157], v[208:211], v[72:75]
	v_mfma_f32_16x16x32_bf16 v[124:127], v[150:153], v[182:185], v[124:127]
	v_mfma_f32_16x16x32_bf16 v[120:123], v[158:161], v[182:185], v[120:123]
	v_mfma_f32_16x16x32_bf16 v[108:111], v[150:153], v[190:193], v[108:111]
	v_mfma_f32_16x16x32_bf16 v[104:107], v[158:161], v[190:193], v[104:107]
	v_mfma_f32_16x16x32_bf16 v[92:95], v[150:153], v[198:201], v[92:95]
	v_mfma_f32_16x16x32_bf16 v[88:91], v[158:161], v[198:201], v[88:91]
	v_mfma_f32_16x16x32_bf16 v[76:79], v[150:153], v[212:215], v[76:79]
	v_mfma_f32_16x16x32_bf16 v[72:75], v[158:161], v[212:215], v[72:75]
	s_setprio 0
	s_setprio 1
	v_mfma_f32_16x16x32_bf16 v[116:119], v[162:165], v[178:181], v[116:119]
	v_mfma_f32_16x16x32_bf16 v[112:115], v[170:173], v[178:181], v[112:115]
	v_mfma_f32_16x16x32_bf16 v[100:103], v[162:165], v[186:189], v[100:103]
	v_mfma_f32_16x16x32_bf16 v[96:99], v[170:173], v[186:189], v[96:99]
	v_mfma_f32_16x16x32_bf16 v[84:87], v[162:165], v[194:197], v[84:87]
	v_mfma_f32_16x16x32_bf16 v[80:83], v[170:173], v[194:197], v[80:83]
	v_mfma_f32_16x16x32_bf16 v[68:71], v[162:165], v[208:211], v[68:71]
	v_mfma_f32_16x16x32_bf16 v[64:67], v[170:173], v[208:211], v[64:67]
	v_mfma_f32_16x16x32_bf16 v[116:119], v[166:169], v[182:185], v[116:119]
	v_mfma_f32_16x16x32_bf16 v[112:115], v[174:177], v[182:185], v[112:115]
	v_mfma_f32_16x16x32_bf16 v[100:103], v[166:169], v[190:193], v[100:103]
	v_mfma_f32_16x16x32_bf16 v[96:99], v[174:177], v[190:193], v[96:99]
	v_mfma_f32_16x16x32_bf16 v[84:87], v[166:169], v[198:201], v[84:87]
	v_mfma_f32_16x16x32_bf16 v[80:83], v[174:177], v[198:201], v[80:83]
	v_mfma_f32_16x16x32_bf16 v[68:71], v[166:169], v[212:215], v[68:71]
	v_mfma_f32_16x16x32_bf16 v[64:67], v[174:177], v[212:215], v[64:67]
	s_setprio 0
	s_barrier
; #define PG8_STAGE(bufoff, gbase, voff) do { _Pragma("unroll") for (int _i = 0; _i < 2; ++_i) \
;         __builtin_amdgcn_global_load_lds((const unsigned*)((const char*)(gbase) + (voff)[_i]), (PG8_LAS unsigned*)(lds + (bufoff) + ldsw + _i * 8192), 16, 0, 0); } while (0)
; #define PG8_STAGE_NT(bufoff, gbase, voff) do { _Pragma("unroll") for (int _i = 0; _i < 2; ++_i) \
;         __builtin_amdgcn_global_load_lds((const unsigned*)((const char*)(gbase) + (voff)[_i]), (PG8_LAS unsigned*)(lds + (bufoff) + ldsw + _i * 8192), 16, 0, PG8_B_AUX); } while (0)
; #define PG8_LDA(dst, b, h) do { _Pragma("unroll") for (int m = 0; m < 4; ++m) _Pragma("unroll") for (int k = 0; k < 2; ++k) dst[m][k] = *(const PG8_LAS bf16x8*)(lds + PG8_SA(b, h) + aoff + m * 2048 + k * 1024); } while (0)
; #define PG8_MMA(ai, bj, At, Bt) do { __builtin_amdgcn_s_setprio(1); _Pragma("unroll") for (int m = 0; m < 4; ++m) _Pragma("unroll") for (int n = 0; n < 2; ++n) _Pragma("unroll") for (int k = 0; k < 2; ++k) \
;         acc[ai][bj][m][n] = __builtin_amdgcn_mfma_f32_16x16x32_bf16(Bt[n][k], At[m][k], acc[ai][bj][m][n], 0, 0, 0); __builtin_amdgcn_s_setprio(0); } while (0)
; #define PG8_WAIT_V(n) asm volatile("s_waitcnt vmcnt(" #n ")" ::: "memory")
; #define PG8_WAIT_L(n) asm volatile("s_waitcnt lgkmcnt(" #n ")" ::: "memory")
; #define PG8_BAR __builtin_amdgcn_s_barrier()
; #define PG8_SCHED __builtin_amdgcn_sched_barrier(0)
; template <class Epi, class Sched, bool ALIGN_EPI = false, bool SP2 = false>
; __device__ __forceinline__ void gemm_phase(PG8_LAS unsigned char* lds, const Gemm g, const Sched& S, const Epi& E, int wid) {
;     ...
;             PG8_LDA(At, 1, 1); PG8_STAGE_NT(PG8_SB(1, 0), b3, voffB); PG8_STAGE_NT(PG8_SB(1, 1), b3 + hstepB, voffB); PG8_STAGE(PG8_SA(1, 0), a3, voffA);
;             PG8_WAIT_V(8); PG8_WAIT_L(0); PG8_BAR; PG8_MMA(1, 0, At, B0); PG8_MMA(1, 1, At, B1); PG8_BAR; PG8_SCHED;
;     ...
;     PG8_WAIT_V(0);
;     if constexpr (!ALIGN_EPI) { if (wr == 0) PG8_BAR; }
;     PG8_BAR;
	s_mov_b32 m0, s63
	v_lshl_add_u64 v[202:203], v[202:203], 0, s[4:5]
	s_add_u32 s30, s30, 0x2b4080
	ds_read_b128 v[178:181], v143 offset:49152
	ds_read_b128 v[182:185], v143 offset:50176
	ds_read_b128 v[186:189], v143 offset:51200
	ds_read_b128 v[190:193], v143 offset:52224
	ds_read_b128 v[194:197], v143 offset:53248
	ds_read_b128 v[198:201], v143 offset:54272
	ds_read_b128 v[208:211], v143 offset:55296
	ds_read_b128 v[212:215], v143 offset:56320
	global_load_lds_dwordx4 v[202:203], off
	v_lshl_add_u64 v[202:203], v[216:217], 0, s[4:5]
	s_mov_b32 m0, s64
	s_addc_u32 s31, s31, 0
	global_load_lds_dwordx4 v[202:203], off
	v_lshl_add_u64 v[202:203], s[30:31], 0, v[130:131]
	s_mov_b32 m0, s65
	s_nop 0
	global_load_lds_dwordx4 v[202:203], off
	v_lshl_add_u64 v[202:203], s[30:31], 0, v[134:135]
	s_mov_b32 m0, s66
	s_nop 0
	global_load_lds_dwordx4 v[202:203], off
	v_lshl_add_u64 v[202:203], v[218:219], 0, s[4:5]
	s_mov_b32 m0, s25
	s_nop 0
	global_load_lds_dwordx4 v[202:203], off
	v_lshl_add_u64 v[202:203], v[220:221], 0, s[4:5]
	s_mov_b32 m0, s56
	s_nop 0
	global_load_lds_dwordx4 v[202:203], off
	s_waitcnt vmcnt(8)
	s_waitcnt lgkmcnt(0)
	s_barrier
	s_setprio 1
	s_waitcnt lgkmcnt(0)
	v_mfma_f32_16x16x32_bf16 v[60:63], v[146:149], v[178:181], v[60:63]
	v_mfma_f32_16x16x32_bf16 v[56:59], v[154:157], v[178:181], v[56:59]
	v_mfma_f32_16x16x32_bf16 v[44:47], v[146:149], v[186:189], v[44:47]
	v_mfma_f32_16x16x32_bf16 v[40:43], v[154:157], v[186:189], v[40:43]
	v_mfma_f32_16x16x32_bf16 v[28:31], v[146:149], v[194:197], v[28:31]
	v_mfma_f32_16x16x32_bf16 v[24:27], v[154:157], v[194:197], v[24:27]
	v_mfma_f32_16x16x32_bf16 v[12:15], v[146:149], v[208:211], v[12:15]
	v_mfma_f32_16x16x32_bf16 v[8:11], v[154:157], v[208:211], v[8:11]
	v_mfma_f32_16x16x32_bf16 v[60:63], v[150:153], v[182:185], v[60:63]
	v_mfma_f32_16x16x32_bf16 v[56:59], v[158:161], v[182:185], v[56:59]
	v_mfma_f32_16x16x32_bf16 v[44:47], v[150:153], v[190:193], v[44:47]
	v_mfma_f32_16x16x32_bf16 v[40:43], v[158:161], v[190:193], v[40:43]
	v_mfma_f32_16x16x32_bf16 v[28:31], v[150:153], v[198:201], v[28:31]
	v_mfma_f32_16x16x32_bf16 v[24:27], v[158:161], v[198:201], v[24:27]
	v_mfma_f32_16x16x32_bf16 v[12:15], v[150:153], v[212:215], v[12:15]
	v_mfma_f32_16x16x32_bf16 v[8:11], v[158:161], v[212:215], v[8:11]
	s_setprio 0
	s_setprio 1
	v_mfma_f32_16x16x32_bf16 v[52:55], v[162:165], v[178:181], v[52:55]
	v_mfma_f32_16x16x32_bf16 v[48:51], v[170:173], v[178:181], v[48:51]
	v_mfma_f32_16x16x32_bf16 v[36:39], v[162:165], v[186:189], v[36:39]
	v_mfma_f32_16x16x32_bf16 v[32:35], v[170:173], v[186:189], v[32:35]
	v_mfma_f32_16x16x32_bf16 v[20:23], v[162:165], v[194:197], v[20:23]
	v_mfma_f32_16x16x32_bf16 v[16:19], v[170:173], v[194:197], v[16:19]
	v_mfma_f32_16x16x32_bf16 v[4:7], v[162:165], v[208:211], v[4:7]
	v_mfma_f32_16x16x32_bf16 v[0:3], v[170:173], v[208:211], v[0:3]
	v_mfma_f32_16x16x32_bf16 v[52:55], v[166:169], v[182:185], v[52:55]
	v_mfma_f32_16x16x32_bf16 v[48:51], v[174:177], v[182:185], v[48:51]
	v_mfma_f32_16x16x32_bf16 v[36:39], v[166:169], v[190:193], v[36:39]
	v_mfma_f32_16x16x32_bf16 v[32:35], v[174:177], v[190:193], v[32:35]
	v_mfma_f32_16x16x32_bf16 v[20:23], v[166:169], v[198:201], v[20:23]
	v_mfma_f32_16x16x32_bf16 v[16:19], v[174:177], v[198:201], v[16:19]
	v_mfma_f32_16x16x32_bf16 v[4:7], v[166:169], v[212:215], v[4:7]
	v_mfma_f32_16x16x32_bf16 v[0:3], v[174:177], v[212:215], v[0:3]
	s_setprio 0
	s_barrier
	s_add_i32 s41, s41, 2
	s_add_u32 s21, s21, 0x100
	s_addc_u32 s40, s40, 0
	s_add_u32 s8, s8, 0x100
	s_addc_u32 s9, s9, 0
	v_lshl_add_u64 v[136:137], v[136:137], 0, s[28:29]
	s_cmpk_lt_u32 s41, 0xaa
	v_lshl_add_u64 v[138:139], v[138:139], 0, s[28:29]
	s_cbranch_scc1 .LBB0_1307
	s_waitcnt vmcnt(0)
	s_andn2_b64 vcc, exec, s[44:45]
	s_cbranch_vccnz .LBB0_1310
	s_barrier
